# v8 + M0 wait-state slot filled by the scalar base add instead of s_nop 0 (one per K-loop iteration)
# baseline (speedup 1.0000x reference)
; #define PG8_STAGE(bufoff, gbase, voff) do { _Pragma("unroll") for (int _i = 0; _i < 2; ++_i) \
;         __builtin_amdgcn_global_load_lds((const unsigned*)((const char*)(gbase) + (voff)[_i]), (PG8_LAS unsigned*)(lds + (bufoff) + ldsw + _i * 8192), 16, 0, 0); } while (0)
; #define PG8_LDA(dst, b, h) do { _Pragma("unroll") for (int m = 0; m < 4; ++m) _Pragma("unroll") for (int k = 0; k < 2; ++k) dst[m][k] = *(const PG8_LAS bf16x8*)(lds + PG8_SA(b, h) + aoff + m * 2048 + k * 1024); } while (0)
; #define PG8_LDB(dst, b, h) do { _Pragma("unroll") for (int n = 0; n < 2; ++n) _Pragma("unroll") for (int k = 0; k < 2; ++k) dst[n][k] = *(const PG8_LAS bf16x8*)(lds + PG8_SB(b, h) + boff + n * 2048 + k * 1024); } while (0)
; #define PG8_MMA(ai, bj, At, Bt) do { __builtin_amdgcn_s_setprio(1); _Pragma("unroll") for (int m = 0; m < 4; ++m) _Pragma("unroll") for (int n = 0; n < 2; ++n) _Pragma("unroll") for (int k = 0; k < 2; ++k) \
;         acc[ai][bj][m][n] = __builtin_amdgcn_mfma_f32_16x16x32_f16(Bt[n][k], At[m][k], acc[ai][bj][m][n], 0, 0, 0); __builtin_amdgcn_s_setprio(0); } while (0)
; #define PG8_WAIT_V(n) asm volatile("s_waitcnt vmcnt(" #n ")" ::: "memory")
; #define PG8_BAR __builtin_amdgcn_s_barrier()
; template <class Epi, class Sched, bool ALIGN_EPI = false, bool SP2 = false>
; __device__ __forceinline__ void gemm_phase(PG8_LAS unsigned char* lds, const Gemm g, const Sched& S, const Epi& E) {
;     ...
;         const char* nA = has_next ? (const char*)g.A + (size_t)nxt.pm * tstep : cA; const char* nB = has_next ? (const char*)g.Bt + (size_t)nxt.pn * tstep : cB;
;         for (int t = 0; t < nt; t += 2) {
;             const bool last = (t == nt - 2);
;             const char* a1 = cA + (size_t)(t + 1) * kstep;
;             const char* a2 = last ? nA : cA + (size_t)(t + 2) * kstep; const char* b2 = last ? nB : cB + (size_t)(t + 2) * kstep;
;     ...
;             PG8_LDB(B0, 0, 0); PG8_LDB(B1, 0, 1); PG8_SCHED; PG8_LDA(At, 0, 0); PG8_STAGE(PG8_SA(1, 1), a1 + hstep, voffA);
;             PG8_WAIT_V(8); PG8_WAIT_L(0); PG8_BAR; PG8_MMA(0, 0, At, B0); PG8_MMA(0, 1, At, B1); PG8_BAR; PG8_SCHED;
;             PG8_LDA(At, 0, 1); PG8_STAGE(PG8_SB(0, 0), b2, voffB); PG8_STAGE(PG8_SB(0, 1), b2 + hstep, voffB); PG8_STAGE(PG8_SA(0, 0), a2, voffA);
;             PG8_WAIT_V(8); PG8_WAIT_L(0); PG8_BAR; PG8_MMA(1, 0, At, B0); PG8_MMA(1, 1, At, B1); PG8_BAR; PG8_SCHED;
.LBB0_146:
	ds_read_b128 v[150:153], v147
	ds_read_b128 v[154:157], v147 offset:1024
	ds_read_b128 v[158:161], v147 offset:2048
	ds_read_b128 v[162:165], v147 offset:3072
	ds_read_b128 v[166:169], v148
	ds_read_b128 v[170:173], v148 offset:1024
	ds_read_b128 v[174:177], v148 offset:2048
	ds_read_b128 v[178:181], v148 offset:3072
	s_add_u32 s24, s22, 0xfff80080
	s_addc_u32 s25, s23, -1
	s_cmp_eq_u32 s62, 28
	s_cselect_b32 s27, s17, s25
	s_cselect_b32 s26, s54, s24
	s_cselect_b32 s25, s15, s61
	s_cselect_b32 s24, s55, s60
	s_add_i32 m0, s13, 0xc000
	ds_read_b128 v[182:185], v149
	ds_read_b128 v[186:189], v149 offset:1024
	ds_read_b128 v[190:193], v149 offset:2048
	ds_read_b128 v[194:197], v149 offset:3072
	ds_read_b128 v[198:201], v149 offset:4096
	ds_read_b128 v[206:209], v149 offset:5120
	ds_read_b128 v[210:213], v149 offset:6144
	ds_read_b128 v[214:217], v149 offset:7168
	global_load_lds_dwordx4 v138, s[22:23]
	s_add_i32 m0, s13, 0xe000
	s_nop 0
	global_load_lds_dwordx4 v136, s[22:23]
	s_waitcnt vmcnt(8)
	s_waitcnt lgkmcnt(0)
	s_barrier
	v_mfma_f32_16x16x32_f16 v[120:123], v[158:161], v[182:185], v[120:123]
	v_mfma_f32_16x16x32_f16 v[124:127], v[150:153], v[182:185], v[124:127]
	v_mfma_f32_16x16x32_f16 v[112:115], v[158:161], v[190:193], v[112:115]
	v_mfma_f32_16x16x32_f16 v[116:119], v[150:153], v[190:193], v[116:119]
	v_mfma_f32_16x16x32_f16 v[96:99], v[158:161], v[198:201], v[96:99]
	v_mfma_f32_16x16x32_f16 v[100:103], v[150:153], v[198:201], v[100:103]
	v_mfma_f32_16x16x32_f16 v[80:83], v[158:161], v[210:213], v[80:83]
	v_mfma_f32_16x16x32_f16 v[84:87], v[150:153], v[210:213], v[84:87]
	v_mfma_f32_16x16x32_f16 v[120:123], v[162:165], v[186:189], v[120:123]
	v_mfma_f32_16x16x32_f16 v[124:127], v[154:157], v[186:189], v[124:127]
	v_mfma_f32_16x16x32_f16 v[112:115], v[162:165], v[194:197], v[112:115]
	v_mfma_f32_16x16x32_f16 v[116:119], v[154:157], v[194:197], v[116:119]
	v_mfma_f32_16x16x32_f16 v[96:99], v[162:165], v[206:209], v[96:99]
	v_mfma_f32_16x16x32_f16 v[100:103], v[154:157], v[206:209], v[100:103]
	v_mfma_f32_16x16x32_f16 v[80:83], v[162:165], v[214:217], v[80:83]
	v_mfma_f32_16x16x32_f16 v[84:87], v[154:157], v[214:217], v[84:87]
	v_mfma_f32_16x16x32_f16 v[104:107], v[174:177], v[182:185], v[104:107]
	v_mfma_f32_16x16x32_f16 v[108:111], v[166:169], v[182:185], v[108:111]
	v_mfma_f32_16x16x32_f16 v[88:91], v[174:177], v[190:193], v[88:91]
	v_mfma_f32_16x16x32_f16 v[92:95], v[166:169], v[190:193], v[92:95]
	v_mfma_f32_16x16x32_f16 v[72:75], v[174:177], v[198:201], v[72:75]
	v_mfma_f32_16x16x32_f16 v[76:79], v[166:169], v[198:201], v[76:79]
	v_mfma_f32_16x16x32_f16 v[64:67], v[174:177], v[210:213], v[64:67]
	v_mfma_f32_16x16x32_f16 v[68:71], v[166:169], v[210:213], v[68:71]
	v_mfma_f32_16x16x32_f16 v[104:107], v[178:181], v[186:189], v[104:107]
	v_mfma_f32_16x16x32_f16 v[108:111], v[170:173], v[186:189], v[108:111]
	v_mfma_f32_16x16x32_f16 v[88:91], v[178:181], v[194:197], v[88:91]
	v_mfma_f32_16x16x32_f16 v[92:95], v[170:173], v[194:197], v[92:95]
	v_mfma_f32_16x16x32_f16 v[72:75], v[178:181], v[206:209], v[72:75]
	v_mfma_f32_16x16x32_f16 v[76:79], v[170:173], v[206:209], v[76:79]
	v_mfma_f32_16x16x32_f16 v[64:67], v[178:181], v[214:217], v[64:67]
	v_mfma_f32_16x16x32_f16 v[68:71], v[170:173], v[214:217], v[68:71]
	s_barrier
	s_add_i32 s63, s44, s34
	s_add_u32 s98, s24, s8
	s_addc_u32 s99, s25, s9
	s_mov_b32 m0, s63
	ds_read_b128 v[182:185], v149 offset:16384
	ds_read_b128 v[186:189], v149 offset:17408
	ds_read_b128 v[190:193], v149 offset:18432
	ds_read_b128 v[194:197], v149 offset:19456
	ds_read_b128 v[198:201], v149 offset:20480
	ds_read_b128 v[206:209], v149 offset:21504
	ds_read_b128 v[210:213], v149 offset:22528
	ds_read_b128 v[214:217], v149 offset:23552
	global_load_lds_dwordx4 v132, s[24:25]
	s_add_i32 m0, s63, 0x2000
	s_add_u32 s66, s24, 0x80000
	s_addc_u32 s67, s25, 0
	s_add_i32 s63, s45, s34
	global_load_lds_dwordx4 v128, s[24:25]
	s_mov_b32 m0, s63
	s_nop 0
	global_load_lds_dwordx4 v132, s[66:67]
	s_add_i32 m0, s63, 0x2000
	s_nop 0
	global_load_lds_dwordx4 v128, s[66:67]
	s_mov_b32 m0, s13
	s_add_u32 s100, s26, s8
	s_addc_u32 s101, s27, s9
	global_load_lds_dwordx4 v134, s[26:27]
	s_mov_b32 m0, s37
	s_nop 0
	global_load_lds_dwordx4 v130, s[26:27]
	s_waitcnt vmcnt(8)
	s_waitcnt lgkmcnt(0)
	s_barrier
	v_mfma_f32_16x16x32_f16 v[56:59], v[158:161], v[182:185], v[56:59]
	v_mfma_f32_16x16x32_f16 v[60:63], v[150:153], v[182:185], v[60:63]
	v_mfma_f32_16x16x32_f16 v[48:51], v[158:161], v[190:193], v[48:51]
	v_mfma_f32_16x16x32_f16 v[52:55], v[150:153], v[190:193], v[52:55]
	v_mfma_f32_16x16x32_f16 v[32:35], v[158:161], v[198:201], v[32:35]
	v_mfma_f32_16x16x32_f16 v[36:39], v[150:153], v[198:201], v[36:39]
	v_mfma_f32_16x16x32_f16 v[16:19], v[158:161], v[210:213], v[16:19]
	v_mfma_f32_16x16x32_f16 v[20:23], v[150:153], v[210:213], v[20:23]
	v_mfma_f32_16x16x32_f16 v[56:59], v[162:165], v[186:189], v[56:59]
	v_mfma_f32_16x16x32_f16 v[60:63], v[154:157], v[186:189], v[60:63]
	v_mfma_f32_16x16x32_f16 v[48:51], v[162:165], v[194:197], v[48:51]
	v_mfma_f32_16x16x32_f16 v[52:55], v[154:157], v[194:197], v[52:55]
	v_mfma_f32_16x16x32_f16 v[32:35], v[162:165], v[206:209], v[32:35]
	v_mfma_f32_16x16x32_f16 v[36:39], v[154:157], v[206:209], v[36:39]
	v_mfma_f32_16x16x32_f16 v[16:19], v[162:165], v[214:217], v[16:19]
	v_mfma_f32_16x16x32_f16 v[20:23], v[154:157], v[214:217], v[20:23]
	v_mfma_f32_16x16x32_f16 v[40:43], v[174:177], v[182:185], v[40:43]
	v_mfma_f32_16x16x32_f16 v[44:47], v[166:169], v[182:185], v[44:47]
	v_mfma_f32_16x16x32_f16 v[24:27], v[174:177], v[190:193], v[24:27]
	v_mfma_f32_16x16x32_f16 v[28:31], v[166:169], v[190:193], v[28:31]
	v_mfma_f32_16x16x32_f16 v[8:11], v[174:177], v[198:201], v[8:11]
	v_mfma_f32_16x16x32_f16 v[12:15], v[166:169], v[198:201], v[12:15]
	v_mfma_f32_16x16x32_f16 v[0:3], v[174:177], v[210:213], v[0:3]
	v_mfma_f32_16x16x32_f16 v[4:7], v[166:169], v[210:213], v[4:7]
	v_mfma_f32_16x16x32_f16 v[40:43], v[178:181], v[186:189], v[40:43]
	v_mfma_f32_16x16x32_f16 v[44:47], v[170:173], v[186:189], v[44:47]
	v_mfma_f32_16x16x32_f16 v[24:27], v[178:181], v[194:197], v[24:27]
	v_mfma_f32_16x16x32_f16 v[28:31], v[170:173], v[194:197], v[28:31]
	v_mfma_f32_16x16x32_f16 v[8:11], v[178:181], v[206:209], v[8:11]
	v_mfma_f32_16x16x32_f16 v[12:15], v[170:173], v[206:209], v[12:15]
	v_mfma_f32_16x16x32_f16 v[0:3], v[178:181], v[214:217], v[0:3]
	v_mfma_f32_16x16x32_f16 v[4:7], v[170:173], v[214:217], v[4:7]
	s_barrier
; #define PG8_STAGE(bufoff, gbase, voff) do { _Pragma("unroll") for (int _i = 0; _i < 2; ++_i) \
;         __builtin_amdgcn_global_load_lds((const unsigned*)((const char*)(gbase) + (voff)[_i]), (PG8_LAS unsigned*)(lds + (bufoff) + ldsw + _i * 8192), 16, 0, 0); } while (0)
; #define PG8_LDA(dst, b, h) do { _Pragma("unroll") for (int m = 0; m < 4; ++m) _Pragma("unroll") for (int k = 0; k < 2; ++k) dst[m][k] = *(const PG8_LAS bf16x8*)(lds + PG8_SA(b, h) + aoff + m * 2048 + k * 1024); } while (0)
; #define PG8_LDB(dst, b, h) do { _Pragma("unroll") for (int n = 0; n < 2; ++n) _Pragma("unroll") for (int k = 0; k < 2; ++k) dst[n][k] = *(const PG8_LAS bf16x8*)(lds + PG8_SB(b, h) + boff + n * 2048 + k * 1024); } while (0)
; #define PG8_MMA(ai, bj, At, Bt) do { __builtin_amdgcn_s_setprio(1); _Pragma("unroll") for (int m = 0; m < 4; ++m) _Pragma("unroll") for (int n = 0; n < 2; ++n) _Pragma("unroll") for (int k = 0; k < 2; ++k) \
;         acc[ai][bj][m][n] = __builtin_amdgcn_mfma_f32_16x16x32_f16(Bt[n][k], At[m][k], acc[ai][bj][m][n], 0, 0, 0); __builtin_amdgcn_s_setprio(0); } while (0)
; #define PG8_WAIT_V(n) asm volatile("s_waitcnt vmcnt(" #n ")" ::: "memory")
; #define PG8_WAIT_L(n) asm volatile("s_waitcnt lgkmcnt(" #n ")" ::: "memory")
; #define PG8_BAR __builtin_amdgcn_s_barrier()
; #define PG8_SCHED __builtin_amdgcn_sched_barrier(0)
; template <class Epi, class Sched, bool ALIGN_EPI = false, bool SP2 = false>
; __device__ __forceinline__ void gemm_phase(PG8_LAS unsigned char* lds, const Gemm g, const Sched& S, const Epi& E) {
;     ...
;         for (int t = 0; t < nt; t += 2) {
;     ...
;             PG8_LDB(B0, 1, 0); PG8_LDB(B1, 1, 1); PG8_SCHED; PG8_LDA(At, 1, 0); PG8_STAGE(PG8_SA(0, 1), a2 + hstep, voffA);
;             PG8_WAIT_V(8); PG8_WAIT_L(0); PG8_BAR; PG8_MMA(0, 0, At, B0); PG8_MMA(0, 1, At, B1); PG8_BAR; PG8_SCHED;
;             PG8_LDA(At, 1, 1); PG8_STAGE(PG8_SB(1, 0), b3, voffB); PG8_STAGE(PG8_SB(1, 1), b3 + hstep, voffB); PG8_STAGE(PG8_SA(1, 0), a3, voffA);
;             PG8_WAIT_V(8); PG8_WAIT_L(0); PG8_BAR; PG8_MMA(1, 0, At, B0); PG8_MMA(1, 1, At, B1); PG8_BAR; PG8_SCHED;
	s_add_i32 s63, 0, 0x18000
	s_add_i32 s66, 0, 0x1c000
	v_add_u32_e32 v162, s63, v145
	v_add_u32_e32 v178, s66, v145
	ds_read_b128 v[150:153], v162
	ds_read_b128 v[154:157], v162 offset:1024
	ds_read_b128 v[158:161], v162 offset:2048
	ds_read_b128 v[162:165], v162 offset:3072
	ds_read_b128 v[166:169], v178
	ds_read_b128 v[170:173], v178 offset:1024
	ds_read_b128 v[174:177], v178 offset:2048
	ds_read_b128 v[178:181], v178 offset:3072
	s_add_u32 s26, s26, 0x80000
	s_addc_u32 s27, s27, 0
	s_mov_b32 m0, s38
	ds_read_b128 v[182:185], v149 offset:32768
	ds_read_b128 v[186:189], v149 offset:33792
	ds_read_b128 v[190:193], v149 offset:34816
	ds_read_b128 v[194:197], v149 offset:35840
	ds_read_b128 v[198:201], v149 offset:36864
	ds_read_b128 v[206:209], v149 offset:37888
	ds_read_b128 v[210:213], v149 offset:38912
	ds_read_b128 v[214:217], v149 offset:39936
	global_load_lds_dwordx4 v134, s[26:27]
	s_mov_b32 m0, s39
	s_nop 0
	global_load_lds_dwordx4 v130, s[26:27]
	s_waitcnt vmcnt(8)
	s_waitcnt lgkmcnt(0)
	s_barrier
	v_mfma_f32_16x16x32_f16 v[120:123], v[158:161], v[182:185], v[120:123]
	v_mfma_f32_16x16x32_f16 v[124:127], v[150:153], v[182:185], v[124:127]
	v_mfma_f32_16x16x32_f16 v[112:115], v[158:161], v[190:193], v[112:115]
	v_mfma_f32_16x16x32_f16 v[116:119], v[150:153], v[190:193], v[116:119]
	v_mfma_f32_16x16x32_f16 v[96:99], v[158:161], v[198:201], v[96:99]
	v_mfma_f32_16x16x32_f16 v[100:103], v[150:153], v[198:201], v[100:103]
	v_mfma_f32_16x16x32_f16 v[80:83], v[158:161], v[210:213], v[80:83]
	v_mfma_f32_16x16x32_f16 v[84:87], v[150:153], v[210:213], v[84:87]
	v_mfma_f32_16x16x32_f16 v[120:123], v[162:165], v[186:189], v[120:123]
	v_mfma_f32_16x16x32_f16 v[124:127], v[154:157], v[186:189], v[124:127]
	v_mfma_f32_16x16x32_f16 v[112:115], v[162:165], v[194:197], v[112:115]
	v_mfma_f32_16x16x32_f16 v[116:119], v[154:157], v[194:197], v[116:119]
	v_mfma_f32_16x16x32_f16 v[96:99], v[162:165], v[206:209], v[96:99]
	v_mfma_f32_16x16x32_f16 v[100:103], v[154:157], v[206:209], v[100:103]
	v_mfma_f32_16x16x32_f16 v[80:83], v[162:165], v[214:217], v[80:83]
	v_mfma_f32_16x16x32_f16 v[84:87], v[154:157], v[214:217], v[84:87]
	v_mfma_f32_16x16x32_f16 v[104:107], v[174:177], v[182:185], v[104:107]
	v_mfma_f32_16x16x32_f16 v[108:111], v[166:169], v[182:185], v[108:111]
	v_mfma_f32_16x16x32_f16 v[88:91], v[174:177], v[190:193], v[88:91]
	v_mfma_f32_16x16x32_f16 v[92:95], v[166:169], v[190:193], v[92:95]
	v_mfma_f32_16x16x32_f16 v[72:75], v[174:177], v[198:201], v[72:75]
	v_mfma_f32_16x16x32_f16 v[76:79], v[166:169], v[198:201], v[76:79]
	v_mfma_f32_16x16x32_f16 v[64:67], v[174:177], v[210:213], v[64:67]
	v_mfma_f32_16x16x32_f16 v[68:71], v[166:169], v[210:213], v[68:71]
	v_mfma_f32_16x16x32_f16 v[104:107], v[178:181], v[186:189], v[104:107]
	v_mfma_f32_16x16x32_f16 v[108:111], v[170:173], v[186:189], v[108:111]
	v_mfma_f32_16x16x32_f16 v[88:91], v[178:181], v[194:197], v[88:91]
	v_mfma_f32_16x16x32_f16 v[92:95], v[170:173], v[194:197], v[92:95]
	v_mfma_f32_16x16x32_f16 v[72:75], v[178:181], v[206:209], v[72:75]
	v_mfma_f32_16x16x32_f16 v[76:79], v[170:173], v[206:209], v[76:79]
	v_mfma_f32_16x16x32_f16 v[64:67], v[178:181], v[214:217], v[64:67]
	v_mfma_f32_16x16x32_f16 v[68:71], v[170:173], v[214:217], v[68:71]
	s_barrier
	s_add_i32 s26, s63, s34
	s_mov_b32 m0, s26
	ds_read_b128 v[182:185], v149 offset:49152
	ds_read_b128 v[186:189], v149 offset:50176
	ds_read_b128 v[190:193], v149 offset:51200
	ds_read_b128 v[194:197], v149 offset:52224
	ds_read_b128 v[198:201], v149 offset:53248
	ds_read_b128 v[206:209], v149 offset:54272
	ds_read_b128 v[210:213], v149 offset:55296
	ds_read_b128 v[214:217], v149 offset:56320
	global_load_lds_dwordx4 v132, s[98:99]
	s_add_i32 m0, s26, 0x2000
	s_add_u32 s24, s24, 0x80080
	s_addc_u32 s25, s25, 0
	s_add_i32 s26, s66, s34
	global_load_lds_dwordx4 v128, s[98:99]
	s_mov_b32 m0, s26
	s_nop 0
	global_load_lds_dwordx4 v132, s[24:25]
	s_add_i32 m0, s26, 0x2000
	s_nop 0
	global_load_lds_dwordx4 v128, s[24:25]
	s_mov_b32 m0, s41
	s_nop 0
	global_load_lds_dwordx4 v134, s[100:101]
	s_mov_b32 m0, s42
	s_nop 0
	global_load_lds_dwordx4 v130, s[100:101]
	s_waitcnt vmcnt(8)
	s_waitcnt lgkmcnt(0)
	s_barrier
	v_mfma_f32_16x16x32_f16 v[56:59], v[158:161], v[182:185], v[56:59]
	v_mfma_f32_16x16x32_f16 v[60:63], v[150:153], v[182:185], v[60:63]
	v_mfma_f32_16x16x32_f16 v[48:51], v[158:161], v[190:193], v[48:51]
	v_mfma_f32_16x16x32_f16 v[52:55], v[150:153], v[190:193], v[52:55]
	v_mfma_f32_16x16x32_f16 v[32:35], v[158:161], v[198:201], v[32:35]
	v_mfma_f32_16x16x32_f16 v[36:39], v[150:153], v[198:201], v[36:39]
	v_mfma_f32_16x16x32_f16 v[16:19], v[158:161], v[210:213], v[16:19]
	v_mfma_f32_16x16x32_f16 v[20:23], v[150:153], v[210:213], v[20:23]
	v_mfma_f32_16x16x32_f16 v[56:59], v[162:165], v[186:189], v[56:59]
	v_mfma_f32_16x16x32_f16 v[60:63], v[154:157], v[186:189], v[60:63]
	v_mfma_f32_16x16x32_f16 v[48:51], v[162:165], v[194:197], v[48:51]
	v_mfma_f32_16x16x32_f16 v[52:55], v[154:157], v[194:197], v[52:55]
	v_mfma_f32_16x16x32_f16 v[32:35], v[162:165], v[206:209], v[32:35]
	v_mfma_f32_16x16x32_f16 v[36:39], v[154:157], v[206:209], v[36:39]
	v_mfma_f32_16x16x32_f16 v[16:19], v[162:165], v[214:217], v[16:19]
	v_mfma_f32_16x16x32_f16 v[20:23], v[154:157], v[214:217], v[20:23]
	v_mfma_f32_16x16x32_f16 v[40:43], v[174:177], v[182:185], v[40:43]
	v_mfma_f32_16x16x32_f16 v[44:47], v[166:169], v[182:185], v[44:47]
	v_mfma_f32_16x16x32_f16 v[24:27], v[174:177], v[190:193], v[24:27]
	v_mfma_f32_16x16x32_f16 v[28:31], v[166:169], v[190:193], v[28:31]
	v_mfma_f32_16x16x32_f16 v[8:11], v[174:177], v[198:201], v[8:11]
	v_mfma_f32_16x16x32_f16 v[12:15], v[166:169], v[198:201], v[12:15]
	v_mfma_f32_16x16x32_f16 v[0:3], v[174:177], v[210:213], v[0:3]
	v_mfma_f32_16x16x32_f16 v[4:7], v[166:169], v[210:213], v[4:7]
	v_mfma_f32_16x16x32_f16 v[40:43], v[178:181], v[186:189], v[40:43]
	v_mfma_f32_16x16x32_f16 v[44:47], v[170:173], v[186:189], v[44:47]
	v_mfma_f32_16x16x32_f16 v[24:27], v[178:181], v[194:197], v[24:27]
	v_mfma_f32_16x16x32_f16 v[28:31], v[170:173], v[194:197], v[28:31]
	v_mfma_f32_16x16x32_f16 v[8:11], v[178:181], v[206:209], v[8:11]
	v_mfma_f32_16x16x32_f16 v[12:15], v[170:173], v[206:209], v[12:15]
	v_mfma_f32_16x16x32_f16 v[0:3], v[178:181], v[214:217], v[0:3]
	v_mfma_f32_16x16x32_f16 v[4:7], v[170:173], v[214:217], v[4:7]
	s_barrier
	s_add_i32 s62, s62, 2
	s_add_u32 s60, s60, 0x100
	s_addc_u32 s61, s61, 0
	s_add_u32 s22, s22, 0x100
	s_addc_u32 s23, s23, 0
	s_cmp_gt_u32 s62, 29
	s_cbranch_scc0 .LBB0_146
	s_and_b64 vcc, exec, s[10:11]
	s_cbranch_vccz .LBB0_149
	s_barrier

; #define PG8_STAGE(bufoff, gbase, voff) do { _Pragma("unroll") for (int _i = 0; _i < 2; ++_i) \
;         __builtin_amdgcn_global_load_lds((const unsigned*)((const char*)(gbase) + (voff)[_i]), (PG8_LAS unsigned*)(lds + (bufoff) + ldsw + _i * 8192), 16, 0, 0); } while (0)
; #define PG8_LDA(dst, b, h) do { _Pragma("unroll") for (int m = 0; m < 4; ++m) _Pragma("unroll") for (int k = 0; k < 2; ++k) dst[m][k] = *(const PG8_LAS bf16x8*)(lds + PG8_SA(b, h) + aoff + m * 2048 + k * 1024); } while (0)
; #define PG8_LDB(dst, b, h) do { _Pragma("unroll") for (int n = 0; n < 2; ++n) _Pragma("unroll") for (int k = 0; k < 2; ++k) dst[n][k] = *(const PG8_LAS bf16x8*)(lds + PG8_SB(b, h) + boff + n * 2048 + k * 1024); } while (0)
; #define PG8_MMA(ai, bj, At, Bt) do { __builtin_amdgcn_s_setprio(1); _Pragma("unroll") for (int m = 0; m < 4; ++m) _Pragma("unroll") for (int n = 0; n < 2; ++n) _Pragma("unroll") for (int k = 0; k < 2; ++k) \
;         acc[ai][bj][m][n] = __builtin_amdgcn_mfma_f32_16x16x32_f16(Bt[n][k], At[m][k], acc[ai][bj][m][n], 0, 0, 0); __builtin_amdgcn_s_setprio(0); } while (0)
; #define PG8_WAIT_V(n) asm volatile("s_waitcnt vmcnt(" #n ")" ::: "memory")
; #define PG8_BAR __builtin_amdgcn_s_barrier()
; template <class Epi, class Sched, bool ALIGN_EPI = false, bool SP2 = false>
; __device__ __forceinline__ void gemm_phase(PG8_LAS unsigned char* lds, const Gemm g, const Sched& S, const Epi& E) {
;     ...
;         const char* nA = has_next ? (const char*)g.A + (size_t)nxt.pm * tstep : cA; const char* nB = has_next ? (const char*)g.Bt + (size_t)nxt.pn * tstep : cB;
;         for (int t = 0; t < nt; t += 2) {
;             const bool last = (t == nt - 2);
;             const char* a1 = cA + (size_t)(t + 1) * kstep;
;             const char* a2 = last ? nA : cA + (size_t)(t + 2) * kstep; const char* b2 = last ? nB : cB + (size_t)(t + 2) * kstep;
;     ...
;             PG8_LDB(B0, 0, 0); PG8_LDB(B1, 0, 1); PG8_SCHED; PG8_LDA(At, 0, 0); PG8_STAGE(PG8_SA(1, 1), a1 + hstep, voffA);
;             PG8_WAIT_V(8); PG8_WAIT_L(0); PG8_BAR; PG8_MMA(0, 0, At, B0); PG8_MMA(0, 1, At, B1); PG8_BAR; PG8_SCHED;
;             PG8_LDA(At, 0, 1); PG8_STAGE(PG8_SB(0, 0), b2, voffB); PG8_STAGE(PG8_SB(0, 1), b2 + hstep, voffB); PG8_STAGE(PG8_SA(0, 0), a2, voffA);
;             PG8_WAIT_V(8); PG8_WAIT_L(0); PG8_BAR; PG8_MMA(1, 0, At, B0); PG8_MMA(1, 1, At, B1); PG8_BAR; PG8_SCHED;
.LBB0_485:
	ds_read_b128 v[128:131], v163
	ds_read_b128 v[132:135], v163 offset:1024
	ds_read_b128 v[152:155], v163 offset:2048
	ds_read_b128 v[156:159], v163 offset:3072
	ds_read_b128 v[166:169], v164
	ds_read_b128 v[170:173], v164 offset:1024
	ds_read_b128 v[174:177], v164 offset:2048
	ds_read_b128 v[178:181], v164 offset:3072
	s_add_u32 s26, s24, 0x100
	s_addc_u32 s27, s25, 0
	s_cmp_eq_u32 s65, 20
	s_cselect_b32 s31, s1, s27
	s_cselect_b32 s30, s0, s26
	s_cselect_b32 s29, s23, s64
	s_cselect_b32 s28, s22, s63
	s_add_i32 m0, s37, 0xc000
	ds_read_b128 v[182:185], v165
	ds_read_b128 v[186:189], v165 offset:1024
	ds_read_b128 v[190:193], v165 offset:2048
	ds_read_b128 v[194:197], v165 offset:3072
	ds_read_b128 v[198:201], v165 offset:4096
	ds_read_b128 v[208:211], v165 offset:5120
	ds_read_b128 v[212:215], v165 offset:6144
	ds_read_b128 v[216:219], v165 offset:7168
	global_load_lds_dwordx4 v146, s[24:25]
	s_add_i32 m0, s37, 0xe000
	s_nop 0
	global_load_lds_dwordx4 v144, s[24:25]
	s_waitcnt vmcnt(8)
	s_waitcnt lgkmcnt(0)
	s_barrier
	v_mfma_f32_16x16x32_f16 v[120:123], v[152:155], v[182:185], v[120:123]
	v_mfma_f32_16x16x32_f16 v[124:127], v[128:131], v[182:185], v[124:127]
	v_mfma_f32_16x16x32_f16 v[104:107], v[152:155], v[190:193], v[104:107]
	v_mfma_f32_16x16x32_f16 v[108:111], v[128:131], v[190:193], v[108:111]
	v_mfma_f32_16x16x32_f16 v[88:91], v[152:155], v[198:201], v[88:91]
	v_mfma_f32_16x16x32_f16 v[92:95], v[128:131], v[198:201], v[92:95]
	v_mfma_f32_16x16x32_f16 v[72:75], v[152:155], v[212:215], v[72:75]
	v_mfma_f32_16x16x32_f16 v[76:79], v[128:131], v[212:215], v[76:79]
	v_mfma_f32_16x16x32_f16 v[120:123], v[156:159], v[186:189], v[120:123]
	v_mfma_f32_16x16x32_f16 v[124:127], v[132:135], v[186:189], v[124:127]
	v_mfma_f32_16x16x32_f16 v[104:107], v[156:159], v[194:197], v[104:107]
	v_mfma_f32_16x16x32_f16 v[108:111], v[132:135], v[194:197], v[108:111]
	v_mfma_f32_16x16x32_f16 v[88:91], v[156:159], v[208:211], v[88:91]
	v_mfma_f32_16x16x32_f16 v[92:95], v[132:135], v[208:211], v[92:95]
	v_mfma_f32_16x16x32_f16 v[72:75], v[156:159], v[216:219], v[72:75]
	v_mfma_f32_16x16x32_f16 v[76:79], v[132:135], v[216:219], v[76:79]
	v_mfma_f32_16x16x32_f16 v[112:115], v[174:177], v[182:185], v[112:115]
	v_mfma_f32_16x16x32_f16 v[116:119], v[166:169], v[182:185], v[116:119]
	v_mfma_f32_16x16x32_f16 v[96:99], v[174:177], v[190:193], v[96:99]
	v_mfma_f32_16x16x32_f16 v[100:103], v[166:169], v[190:193], v[100:103]
	v_mfma_f32_16x16x32_f16 v[80:83], v[174:177], v[198:201], v[80:83]
	v_mfma_f32_16x16x32_f16 v[84:87], v[166:169], v[198:201], v[84:87]
	v_mfma_f32_16x16x32_f16 v[64:67], v[174:177], v[212:215], v[64:67]
	v_mfma_f32_16x16x32_f16 v[68:71], v[166:169], v[212:215], v[68:71]
	v_mfma_f32_16x16x32_f16 v[112:115], v[178:181], v[186:189], v[112:115]
	v_mfma_f32_16x16x32_f16 v[116:119], v[170:173], v[186:189], v[116:119]
	v_mfma_f32_16x16x32_f16 v[96:99], v[178:181], v[194:197], v[96:99]
	v_mfma_f32_16x16x32_f16 v[100:103], v[170:173], v[194:197], v[100:103]
	v_mfma_f32_16x16x32_f16 v[80:83], v[178:181], v[208:211], v[80:83]
	v_mfma_f32_16x16x32_f16 v[84:87], v[170:173], v[208:211], v[84:87]
	v_mfma_f32_16x16x32_f16 v[64:67], v[178:181], v[216:219], v[64:67]
	v_mfma_f32_16x16x32_f16 v[68:71], v[170:173], v[216:219], v[68:71]
	s_barrier
	s_add_i32 s24, s45, s36
	s_add_u32 s98, s28, s16
	s_addc_u32 s99, s29, s17
	s_mov_b32 m0, s24
	ds_read_b128 v[182:185], v165 offset:16384
	ds_read_b128 v[186:189], v165 offset:17408
	ds_read_b128 v[190:193], v165 offset:18432
	ds_read_b128 v[194:197], v165 offset:19456
	ds_read_b128 v[198:201], v165 offset:20480
	ds_read_b128 v[208:211], v165 offset:21504
	ds_read_b128 v[212:215], v165 offset:22528
	ds_read_b128 v[216:219], v165 offset:23552
	global_load_lds_dwordx4 v138, s[28:29]
	s_add_i32 m0, s24, 0x2000
	s_add_u32 s24, s28, 0x60000
	s_addc_u32 s25, s29, 0
	s_add_i32 s66, s52, s36
	global_load_lds_dwordx4 v142, s[28:29]
	s_mov_b32 m0, s66
	s_nop 0
	global_load_lds_dwordx4 v138, s[24:25]
	s_add_i32 m0, s66, 0x2000
	s_nop 0
	global_load_lds_dwordx4 v142, s[24:25]
	s_mov_b32 m0, s37
	s_add_u32 s100, s30, s16
	s_addc_u32 s101, s31, s17
	global_load_lds_dwordx4 v136, s[30:31]
	s_mov_b32 m0, s38
	s_nop 0
	global_load_lds_dwordx4 v140, s[30:31]
	s_waitcnt vmcnt(8)
	s_waitcnt lgkmcnt(0)
	s_barrier
	v_mfma_f32_16x16x32_f16 v[56:59], v[152:155], v[182:185], v[56:59]
	v_mfma_f32_16x16x32_f16 v[60:63], v[128:131], v[182:185], v[60:63]
	v_mfma_f32_16x16x32_f16 v[40:43], v[152:155], v[190:193], v[40:43]
	v_mfma_f32_16x16x32_f16 v[44:47], v[128:131], v[190:193], v[44:47]
	v_mfma_f32_16x16x32_f16 v[24:27], v[152:155], v[198:201], v[24:27]
	v_mfma_f32_16x16x32_f16 v[28:31], v[128:131], v[198:201], v[28:31]
	v_mfma_f32_16x16x32_f16 v[8:11], v[152:155], v[212:215], v[8:11]
	v_mfma_f32_16x16x32_f16 v[12:15], v[128:131], v[212:215], v[12:15]
	v_mfma_f32_16x16x32_f16 v[56:59], v[156:159], v[186:189], v[56:59]
	v_mfma_f32_16x16x32_f16 v[60:63], v[132:135], v[186:189], v[60:63]
	v_mfma_f32_16x16x32_f16 v[40:43], v[156:159], v[194:197], v[40:43]
	v_mfma_f32_16x16x32_f16 v[44:47], v[132:135], v[194:197], v[44:47]
	v_mfma_f32_16x16x32_f16 v[24:27], v[156:159], v[208:211], v[24:27]
	v_mfma_f32_16x16x32_f16 v[28:31], v[132:135], v[208:211], v[28:31]
	v_mfma_f32_16x16x32_f16 v[8:11], v[156:159], v[216:219], v[8:11]
	v_mfma_f32_16x16x32_f16 v[12:15], v[132:135], v[216:219], v[12:15]
	v_mfma_f32_16x16x32_f16 v[48:51], v[174:177], v[182:185], v[48:51]
	v_mfma_f32_16x16x32_f16 v[52:55], v[166:169], v[182:185], v[52:55]
	v_mfma_f32_16x16x32_f16 v[32:35], v[174:177], v[190:193], v[32:35]
	v_mfma_f32_16x16x32_f16 v[36:39], v[166:169], v[190:193], v[36:39]
	v_mfma_f32_16x16x32_f16 v[16:19], v[174:177], v[198:201], v[16:19]
	v_mfma_f32_16x16x32_f16 v[20:23], v[166:169], v[198:201], v[20:23]
	v_mfma_f32_16x16x32_f16 v[0:3], v[174:177], v[212:215], v[0:3]
	v_mfma_f32_16x16x32_f16 v[4:7], v[166:169], v[212:215], v[4:7]
	v_mfma_f32_16x16x32_f16 v[48:51], v[178:181], v[186:189], v[48:51]
	v_mfma_f32_16x16x32_f16 v[52:55], v[170:173], v[186:189], v[52:55]
	v_mfma_f32_16x16x32_f16 v[32:35], v[178:181], v[194:197], v[32:35]
	v_mfma_f32_16x16x32_f16 v[36:39], v[170:173], v[194:197], v[36:39]
	v_mfma_f32_16x16x32_f16 v[16:19], v[178:181], v[208:211], v[16:19]
	v_mfma_f32_16x16x32_f16 v[20:23], v[170:173], v[208:211], v[20:23]
	v_mfma_f32_16x16x32_f16 v[0:3], v[178:181], v[216:219], v[0:3]
	v_mfma_f32_16x16x32_f16 v[4:7], v[170:173], v[216:219], v[4:7]
	s_barrier
; #define PG8_STAGE(bufoff, gbase, voff) do { _Pragma("unroll") for (int _i = 0; _i < 2; ++_i) \
;         __builtin_amdgcn_global_load_lds((const unsigned*)((const char*)(gbase) + (voff)[_i]), (PG8_LAS unsigned*)(lds + (bufoff) + ldsw + _i * 8192), 16, 0, 0); } while (0)
; #define PG8_LDA(dst, b, h) do { _Pragma("unroll") for (int m = 0; m < 4; ++m) _Pragma("unroll") for (int k = 0; k < 2; ++k) dst[m][k] = *(const PG8_LAS bf16x8*)(lds + PG8_SA(b, h) + aoff + m * 2048 + k * 1024); } while (0)
; #define PG8_LDB(dst, b, h) do { _Pragma("unroll") for (int n = 0; n < 2; ++n) _Pragma("unroll") for (int k = 0; k < 2; ++k) dst[n][k] = *(const PG8_LAS bf16x8*)(lds + PG8_SB(b, h) + boff + n * 2048 + k * 1024); } while (0)
; #define PG8_MMA(ai, bj, At, Bt) do { __builtin_amdgcn_s_setprio(1); _Pragma("unroll") for (int m = 0; m < 4; ++m) _Pragma("unroll") for (int n = 0; n < 2; ++n) _Pragma("unroll") for (int k = 0; k < 2; ++k) \
;         acc[ai][bj][m][n] = __builtin_amdgcn_mfma_f32_16x16x32_f16(Bt[n][k], At[m][k], acc[ai][bj][m][n], 0, 0, 0); __builtin_amdgcn_s_setprio(0); } while (0)
; #define PG8_WAIT_V(n) asm volatile("s_waitcnt vmcnt(" #n ")" ::: "memory")
; #define PG8_WAIT_L(n) asm volatile("s_waitcnt lgkmcnt(" #n ")" ::: "memory")
; #define PG8_BAR __builtin_amdgcn_s_barrier()
; #define PG8_SCHED __builtin_amdgcn_sched_barrier(0)
; template <class Epi, class Sched, bool ALIGN_EPI = false, bool SP2 = false>
; __device__ __forceinline__ void gemm_phase(PG8_LAS unsigned char* lds, const Gemm g, const Sched& S, const Epi& E) {
;     ...
;         for (int t = 0; t < nt; t += 2) {
;     ...
;             PG8_LDB(B0, 1, 0); PG8_LDB(B1, 1, 1); PG8_SCHED; PG8_LDA(At, 1, 0); PG8_STAGE(PG8_SA(0, 1), a2 + hstep, voffA);
;             PG8_WAIT_V(8); PG8_WAIT_L(0); PG8_BAR; PG8_MMA(0, 0, At, B0); PG8_MMA(0, 1, At, B1); PG8_BAR; PG8_SCHED;
;             PG8_LDA(At, 1, 1); PG8_STAGE(PG8_SB(1, 0), b3, voffB); PG8_STAGE(PG8_SB(1, 1), b3 + hstep, voffB); PG8_STAGE(PG8_SA(1, 0), a3, voffA);
;             PG8_WAIT_V(8); PG8_WAIT_L(0); PG8_BAR; PG8_MMA(1, 0, At, B0); PG8_MMA(1, 1, At, B1); PG8_BAR; PG8_SCHED;
	s_add_i32 s66, 0, 0x18000
	s_add_i32 s67, 0, 0x1c000
	v_add_u32_e32 v156, s66, v161
	v_add_u32_e32 v178, s67, v161
	ds_read_b128 v[128:131], v156
	ds_read_b128 v[132:135], v156 offset:1024
	ds_read_b128 v[152:155], v156 offset:2048
	ds_read_b128 v[156:159], v156 offset:3072
	ds_read_b128 v[166:169], v178
	ds_read_b128 v[170:173], v178 offset:1024
	ds_read_b128 v[174:177], v178 offset:2048
	ds_read_b128 v[178:181], v178 offset:3072
	s_add_u32 s24, s30, 0x60000
	s_addc_u32 s25, s31, 0
	s_mov_b32 m0, s39
	ds_read_b128 v[182:185], v165 offset:32768
	ds_read_b128 v[186:189], v165 offset:33792
	ds_read_b128 v[190:193], v165 offset:34816
	ds_read_b128 v[194:197], v165 offset:35840
	ds_read_b128 v[198:201], v165 offset:36864
	ds_read_b128 v[208:211], v165 offset:37888
	ds_read_b128 v[212:215], v165 offset:38912
	ds_read_b128 v[216:219], v165 offset:39936
	global_load_lds_dwordx4 v136, s[24:25]
	s_mov_b32 m0, s40
	s_nop 0
	global_load_lds_dwordx4 v140, s[24:25]
	s_waitcnt vmcnt(8)
	s_waitcnt lgkmcnt(0)
	s_barrier
	v_mfma_f32_16x16x32_f16 v[120:123], v[152:155], v[182:185], v[120:123]
	v_mfma_f32_16x16x32_f16 v[124:127], v[128:131], v[182:185], v[124:127]
	v_mfma_f32_16x16x32_f16 v[104:107], v[152:155], v[190:193], v[104:107]
	v_mfma_f32_16x16x32_f16 v[108:111], v[128:131], v[190:193], v[108:111]
	v_mfma_f32_16x16x32_f16 v[88:91], v[152:155], v[198:201], v[88:91]
	v_mfma_f32_16x16x32_f16 v[92:95], v[128:131], v[198:201], v[92:95]
	v_mfma_f32_16x16x32_f16 v[72:75], v[152:155], v[212:215], v[72:75]
	v_mfma_f32_16x16x32_f16 v[76:79], v[128:131], v[212:215], v[76:79]
	v_mfma_f32_16x16x32_f16 v[120:123], v[156:159], v[186:189], v[120:123]
	v_mfma_f32_16x16x32_f16 v[124:127], v[132:135], v[186:189], v[124:127]
	v_mfma_f32_16x16x32_f16 v[104:107], v[156:159], v[194:197], v[104:107]
	v_mfma_f32_16x16x32_f16 v[108:111], v[132:135], v[194:197], v[108:111]
	v_mfma_f32_16x16x32_f16 v[88:91], v[156:159], v[208:211], v[88:91]
	v_mfma_f32_16x16x32_f16 v[92:95], v[132:135], v[208:211], v[92:95]
	v_mfma_f32_16x16x32_f16 v[72:75], v[156:159], v[216:219], v[72:75]
	v_mfma_f32_16x16x32_f16 v[76:79], v[132:135], v[216:219], v[76:79]
	v_mfma_f32_16x16x32_f16 v[112:115], v[174:177], v[182:185], v[112:115]
	v_mfma_f32_16x16x32_f16 v[116:119], v[166:169], v[182:185], v[116:119]
	v_mfma_f32_16x16x32_f16 v[96:99], v[174:177], v[190:193], v[96:99]
	v_mfma_f32_16x16x32_f16 v[100:103], v[166:169], v[190:193], v[100:103]
	v_mfma_f32_16x16x32_f16 v[80:83], v[174:177], v[198:201], v[80:83]
	v_mfma_f32_16x16x32_f16 v[84:87], v[166:169], v[198:201], v[84:87]
	v_mfma_f32_16x16x32_f16 v[64:67], v[174:177], v[212:215], v[64:67]
	v_mfma_f32_16x16x32_f16 v[68:71], v[166:169], v[212:215], v[68:71]
	v_mfma_f32_16x16x32_f16 v[112:115], v[178:181], v[186:189], v[112:115]
	v_mfma_f32_16x16x32_f16 v[116:119], v[170:173], v[186:189], v[116:119]
	v_mfma_f32_16x16x32_f16 v[96:99], v[178:181], v[194:197], v[96:99]
	v_mfma_f32_16x16x32_f16 v[100:103], v[170:173], v[194:197], v[100:103]
	v_mfma_f32_16x16x32_f16 v[80:83], v[178:181], v[208:211], v[80:83]
	v_mfma_f32_16x16x32_f16 v[84:87], v[170:173], v[208:211], v[84:87]
	v_mfma_f32_16x16x32_f16 v[64:67], v[178:181], v[216:219], v[64:67]
	v_mfma_f32_16x16x32_f16 v[68:71], v[170:173], v[216:219], v[68:71]
	s_barrier
	s_add_i32 s24, s66, s36
	s_mov_b32 m0, s24
	ds_read_b128 v[182:185], v165 offset:49152
	ds_read_b128 v[186:189], v165 offset:50176
	ds_read_b128 v[190:193], v165 offset:51200
	ds_read_b128 v[194:197], v165 offset:52224
	ds_read_b128 v[198:201], v165 offset:53248
	ds_read_b128 v[208:211], v165 offset:54272
	ds_read_b128 v[212:215], v165 offset:55296
	ds_read_b128 v[216:219], v165 offset:56320
	global_load_lds_dwordx4 v138, s[98:99]
	s_add_i32 m0, s24, 0x2000
	s_add_u32 s24, s28, 0x60080
	s_addc_u32 s25, s29, 0
	s_add_i32 s28, s67, s36
	global_load_lds_dwordx4 v142, s[98:99]
	s_mov_b32 m0, s28
	s_nop 0
	global_load_lds_dwordx4 v138, s[24:25]
	s_add_i32 m0, s28, 0x2000
	s_nop 0
	global_load_lds_dwordx4 v142, s[24:25]
	s_mov_b32 m0, s42
	s_nop 0
	global_load_lds_dwordx4 v136, s[100:101]
	s_mov_b32 m0, s43
	s_nop 0
	global_load_lds_dwordx4 v140, s[100:101]
	s_waitcnt vmcnt(8)
	s_waitcnt lgkmcnt(0)
	s_barrier
	v_mfma_f32_16x16x32_f16 v[56:59], v[152:155], v[182:185], v[56:59]
	v_mfma_f32_16x16x32_f16 v[60:63], v[128:131], v[182:185], v[60:63]
	v_mfma_f32_16x16x32_f16 v[40:43], v[152:155], v[190:193], v[40:43]
	v_mfma_f32_16x16x32_f16 v[44:47], v[128:131], v[190:193], v[44:47]
	v_mfma_f32_16x16x32_f16 v[24:27], v[152:155], v[198:201], v[24:27]
	v_mfma_f32_16x16x32_f16 v[28:31], v[128:131], v[198:201], v[28:31]
	v_mfma_f32_16x16x32_f16 v[8:11], v[152:155], v[212:215], v[8:11]
	v_mfma_f32_16x16x32_f16 v[12:15], v[128:131], v[212:215], v[12:15]
	v_mfma_f32_16x16x32_f16 v[56:59], v[156:159], v[186:189], v[56:59]
	v_mfma_f32_16x16x32_f16 v[60:63], v[132:135], v[186:189], v[60:63]
	v_mfma_f32_16x16x32_f16 v[40:43], v[156:159], v[194:197], v[40:43]
	v_mfma_f32_16x16x32_f16 v[44:47], v[132:135], v[194:197], v[44:47]
	v_mfma_f32_16x16x32_f16 v[24:27], v[156:159], v[208:211], v[24:27]
	v_mfma_f32_16x16x32_f16 v[28:31], v[132:135], v[208:211], v[28:31]
	v_mfma_f32_16x16x32_f16 v[8:11], v[156:159], v[216:219], v[8:11]
	v_mfma_f32_16x16x32_f16 v[12:15], v[132:135], v[216:219], v[12:15]
	v_mfma_f32_16x16x32_f16 v[48:51], v[174:177], v[182:185], v[48:51]
	v_mfma_f32_16x16x32_f16 v[52:55], v[166:169], v[182:185], v[52:55]
	v_mfma_f32_16x16x32_f16 v[32:35], v[174:177], v[190:193], v[32:35]
	v_mfma_f32_16x16x32_f16 v[36:39], v[166:169], v[190:193], v[36:39]
	v_mfma_f32_16x16x32_f16 v[16:19], v[174:177], v[198:201], v[16:19]
	v_mfma_f32_16x16x32_f16 v[20:23], v[166:169], v[198:201], v[20:23]
	v_mfma_f32_16x16x32_f16 v[0:3], v[174:177], v[212:215], v[0:3]
	v_mfma_f32_16x16x32_f16 v[4:7], v[166:169], v[212:215], v[4:7]
	v_mfma_f32_16x16x32_f16 v[48:51], v[178:181], v[186:189], v[48:51]
	v_mfma_f32_16x16x32_f16 v[52:55], v[170:173], v[186:189], v[52:55]
	v_mfma_f32_16x16x32_f16 v[32:35], v[178:181], v[194:197], v[32:35]
	v_mfma_f32_16x16x32_f16 v[36:39], v[170:173], v[194:197], v[36:39]
	v_mfma_f32_16x16x32_f16 v[16:19], v[178:181], v[208:211], v[16:19]
	v_mfma_f32_16x16x32_f16 v[20:23], v[170:173], v[208:211], v[20:23]
	v_mfma_f32_16x16x32_f16 v[0:3], v[178:181], v[216:219], v[0:3]
	v_mfma_f32_16x16x32_f16 v[4:7], v[170:173], v[216:219], v[4:7]
	s_barrier
	s_add_i32 s65, s65, 2
	s_add_u32 s63, s63, 0x100
	s_addc_u32 s64, s64, 0
	s_cmp_gt_u32 s65, 21
	s_mov_b64 s[24:25], s[26:27]
	s_cbranch_scc0 .LBB0_485
	s_and_b64 vcc, exec, s[18:19]
	s_cbranch_vccz .LBB0_488
	s_barrier

; #define PG8_STAGE(bufoff, gbase, voff) do { _Pragma("unroll") for (int _i = 0; _i < 2; ++_i) \
;         __builtin_amdgcn_global_load_lds((const unsigned*)((const char*)(gbase) + (voff)[_i]), (PG8_LAS unsigned*)(lds + (bufoff) + ldsw + _i * 8192), 16, 0, 0); } while (0)
; #define PG8_LDA(dst, b, h) do { _Pragma("unroll") for (int m = 0; m < 4; ++m) _Pragma("unroll") for (int k = 0; k < 2; ++k) dst[m][k] = *(const PG8_LAS bf16x8*)(lds + PG8_SA(b, h) + aoff + m * 2048 + k * 1024); } while (0)
; #define PG8_LDB(dst, b, h) do { _Pragma("unroll") for (int n = 0; n < 2; ++n) _Pragma("unroll") for (int k = 0; k < 2; ++k) dst[n][k] = *(const PG8_LAS bf16x8*)(lds + PG8_SB(b, h) + boff + n * 2048 + k * 1024); } while (0)
; #define PG8_MMA(ai, bj, At, Bt) do { __builtin_amdgcn_s_setprio(1); _Pragma("unroll") for (int m = 0; m < 4; ++m) _Pragma("unroll") for (int n = 0; n < 2; ++n) _Pragma("unroll") for (int k = 0; k < 2; ++k) \
;         acc[ai][bj][m][n] = __builtin_amdgcn_mfma_f32_16x16x32_f16(Bt[n][k], At[m][k], acc[ai][bj][m][n], 0, 0, 0); __builtin_amdgcn_s_setprio(0); } while (0)
; #define PG8_WAIT_V(n) asm volatile("s_waitcnt vmcnt(" #n ")" ::: "memory")
; #define PG8_BAR __builtin_amdgcn_s_barrier()
; template <class Epi, class Sched, bool ALIGN_EPI = false, bool SP2 = false>
; __device__ __forceinline__ void gemm_phase(PG8_LAS unsigned char* lds, const Gemm g, const Sched& S, const Epi& E) {
;     ...
;         const char* nA = has_next ? (const char*)g.A + (size_t)nxt.pm * tstep : cA; const char* nB = has_next ? (const char*)g.Bt + (size_t)nxt.pn * tstep : cB;
;         for (int t = 0; t < nt; t += 2) {
;             const bool last = (t == nt - 2);
;             const char* a1 = cA + (size_t)(t + 1) * kstep;
;             const char* a2 = last ? nA : cA + (size_t)(t + 2) * kstep; const char* b2 = last ? nB : cB + (size_t)(t + 2) * kstep;
;     ...
;             PG8_LDB(B0, 0, 0); PG8_LDB(B1, 0, 1); PG8_SCHED; PG8_LDA(At, 0, 0); PG8_STAGE(PG8_SA(1, 1), a1 + hstep, voffA);
;             PG8_WAIT_V(8); PG8_WAIT_L(0); PG8_BAR; PG8_MMA(0, 0, At, B0); PG8_MMA(0, 1, At, B1); PG8_BAR; PG8_SCHED;
;             PG8_LDA(At, 0, 1); PG8_STAGE(PG8_SB(0, 0), b2, voffB); PG8_STAGE(PG8_SB(0, 1), b2 + hstep, voffB); PG8_STAGE(PG8_SA(0, 0), a2, voffA);
;             PG8_WAIT_V(8); PG8_WAIT_L(0); PG8_BAR; PG8_MMA(1, 0, At, B0); PG8_MMA(1, 1, At, B1); PG8_BAR; PG8_SCHED;
.LBB0_577:
	ds_read_b128 v[128:131], v198
	ds_read_b128 v[132:135], v198 offset:1024
	ds_read_b128 v[136:139], v198 offset:2048
	ds_read_b128 v[140:143], v198 offset:3072
	ds_read_b128 v[144:147], v199
	ds_read_b128 v[148:151], v199 offset:1024
	ds_read_b128 v[152:155], v199 offset:2048
	ds_read_b128 v[156:159], v199 offset:3072
	s_add_u32 s42, s40, 0xfff80080
	s_addc_u32 s43, s41, -1
	s_cmp_eq_u32 s91, 28
	s_cselect_b32 s45, s31, s43
	s_cselect_b32 s44, s87, s42
	s_cselect_b32 s43, s29, s90
	s_cselect_b32 s42, s88, s89
	s_add_i32 m0, s39, 0xc000
	ds_read_b128 v[176:179], v200
	ds_read_b128 v[180:183], v200 offset:1024
	ds_read_b128 v[184:187], v200 offset:2048
	ds_read_b128 v[188:191], v200 offset:3072
	ds_read_b128 v[208:211], v200 offset:4096
	ds_read_b128 v[212:215], v200 offset:5120
	ds_read_b128 v[216:219], v200 offset:6144
	ds_read_b128 v[220:223], v200 offset:7168
	global_load_lds_dwordx4 v170, s[40:41]
	s_add_i32 m0, s39, 0xe000
	s_nop 0
	global_load_lds_dwordx4 v168, s[40:41]
	s_waitcnt vmcnt(8)
	s_waitcnt lgkmcnt(0)
	s_barrier
	v_mfma_f32_16x16x32_f16 v[120:123], v[136:139], v[176:179], v[120:123]
	v_mfma_f32_16x16x32_f16 v[124:127], v[128:131], v[176:179], v[124:127]
	v_mfma_f32_16x16x32_f16 v[104:107], v[136:139], v[184:187], v[104:107]
	v_mfma_f32_16x16x32_f16 v[108:111], v[128:131], v[184:187], v[108:111]
	v_mfma_f32_16x16x32_f16 v[88:91], v[136:139], v[208:211], v[88:91]
	v_mfma_f32_16x16x32_f16 v[92:95], v[128:131], v[208:211], v[92:95]
	v_mfma_f32_16x16x32_f16 v[72:75], v[136:139], v[216:219], v[72:75]
	v_mfma_f32_16x16x32_f16 v[76:79], v[128:131], v[216:219], v[76:79]
	v_mfma_f32_16x16x32_f16 v[120:123], v[140:143], v[180:183], v[120:123]
	v_mfma_f32_16x16x32_f16 v[124:127], v[132:135], v[180:183], v[124:127]
	v_mfma_f32_16x16x32_f16 v[104:107], v[140:143], v[188:191], v[104:107]
	v_mfma_f32_16x16x32_f16 v[108:111], v[132:135], v[188:191], v[108:111]
	v_mfma_f32_16x16x32_f16 v[88:91], v[140:143], v[212:215], v[88:91]
	v_mfma_f32_16x16x32_f16 v[92:95], v[132:135], v[212:215], v[92:95]
	v_mfma_f32_16x16x32_f16 v[72:75], v[140:143], v[220:223], v[72:75]
	v_mfma_f32_16x16x32_f16 v[76:79], v[132:135], v[220:223], v[76:79]
	v_mfma_f32_16x16x32_f16 v[112:115], v[152:155], v[176:179], v[112:115]
	v_mfma_f32_16x16x32_f16 v[116:119], v[144:147], v[176:179], v[116:119]
	v_mfma_f32_16x16x32_f16 v[96:99], v[152:155], v[184:187], v[96:99]
	v_mfma_f32_16x16x32_f16 v[100:103], v[144:147], v[184:187], v[100:103]
	v_mfma_f32_16x16x32_f16 v[80:83], v[152:155], v[208:211], v[80:83]
	v_mfma_f32_16x16x32_f16 v[84:87], v[144:147], v[208:211], v[84:87]
	v_mfma_f32_16x16x32_f16 v[64:67], v[152:155], v[216:219], v[64:67]
	v_mfma_f32_16x16x32_f16 v[68:71], v[144:147], v[216:219], v[68:71]
	v_mfma_f32_16x16x32_f16 v[112:115], v[156:159], v[180:183], v[112:115]
	v_mfma_f32_16x16x32_f16 v[116:119], v[148:151], v[180:183], v[116:119]
	v_mfma_f32_16x16x32_f16 v[96:99], v[156:159], v[188:191], v[96:99]
	v_mfma_f32_16x16x32_f16 v[100:103], v[148:151], v[188:191], v[100:103]
	v_mfma_f32_16x16x32_f16 v[80:83], v[156:159], v[212:215], v[80:83]
	v_mfma_f32_16x16x32_f16 v[84:87], v[148:151], v[212:215], v[84:87]
	v_mfma_f32_16x16x32_f16 v[64:67], v[156:159], v[220:223], v[64:67]
	v_mfma_f32_16x16x32_f16 v[68:71], v[148:151], v[220:223], v[68:71]
	s_barrier
	s_add_i32 s92, s74, s63
	s_add_u32 s98, s42, s16
	s_addc_u32 s99, s43, s17
	s_mov_b32 m0, s92
	ds_read_b128 v[176:179], v200 offset:16384
	ds_read_b128 v[180:183], v200 offset:17408
	ds_read_b128 v[184:187], v200 offset:18432
	ds_read_b128 v[188:191], v200 offset:19456
	ds_read_b128 v[208:211], v200 offset:20480
	ds_read_b128 v[212:215], v200 offset:21504
	ds_read_b128 v[216:219], v200 offset:22528
	ds_read_b128 v[220:223], v200 offset:23552
	global_load_lds_dwordx4 v162, s[42:43]
	s_add_i32 m0, s92, 0x2000
	s_add_u32 s92, s42, 0x80000
	s_addc_u32 s93, s43, 0
	s_add_i32 s94, s75, s63
	global_load_lds_dwordx4 v166, s[42:43]
	s_mov_b32 m0, s94
	s_nop 0
	global_load_lds_dwordx4 v162, s[92:93]
	s_add_i32 m0, s94, 0x2000
	s_nop 0
	global_load_lds_dwordx4 v166, s[92:93]
	s_mov_b32 m0, s39
	s_add_u32 s100, s44, s16
	s_addc_u32 s101, s45, s17
	global_load_lds_dwordx4 v160, s[44:45]
	s_mov_b32 m0, s64
	s_nop 0
	global_load_lds_dwordx4 v164, s[44:45]
	s_waitcnt vmcnt(8)
	s_waitcnt lgkmcnt(0)
	s_barrier
	v_mfma_f32_16x16x32_f16 v[56:59], v[136:139], v[176:179], v[56:59]
	v_mfma_f32_16x16x32_f16 v[60:63], v[128:131], v[176:179], v[60:63]
	v_mfma_f32_16x16x32_f16 v[40:43], v[136:139], v[184:187], v[40:43]
	v_mfma_f32_16x16x32_f16 v[44:47], v[128:131], v[184:187], v[44:47]
	v_mfma_f32_16x16x32_f16 v[24:27], v[136:139], v[208:211], v[24:27]
	v_mfma_f32_16x16x32_f16 v[28:31], v[128:131], v[208:211], v[28:31]
	v_mfma_f32_16x16x32_f16 v[8:11], v[136:139], v[216:219], v[8:11]
	v_mfma_f32_16x16x32_f16 v[12:15], v[128:131], v[216:219], v[12:15]
	v_mfma_f32_16x16x32_f16 v[56:59], v[140:143], v[180:183], v[56:59]
	v_mfma_f32_16x16x32_f16 v[60:63], v[132:135], v[180:183], v[60:63]
	v_mfma_f32_16x16x32_f16 v[40:43], v[140:143], v[188:191], v[40:43]
	v_mfma_f32_16x16x32_f16 v[44:47], v[132:135], v[188:191], v[44:47]
	v_mfma_f32_16x16x32_f16 v[24:27], v[140:143], v[212:215], v[24:27]
	v_mfma_f32_16x16x32_f16 v[28:31], v[132:135], v[212:215], v[28:31]
	v_mfma_f32_16x16x32_f16 v[8:11], v[140:143], v[220:223], v[8:11]
	v_mfma_f32_16x16x32_f16 v[12:15], v[132:135], v[220:223], v[12:15]
	v_mfma_f32_16x16x32_f16 v[48:51], v[152:155], v[176:179], v[48:51]
	v_mfma_f32_16x16x32_f16 v[52:55], v[144:147], v[176:179], v[52:55]
	v_mfma_f32_16x16x32_f16 v[32:35], v[152:155], v[184:187], v[32:35]
	v_mfma_f32_16x16x32_f16 v[36:39], v[144:147], v[184:187], v[36:39]
	v_mfma_f32_16x16x32_f16 v[16:19], v[152:155], v[208:211], v[16:19]
	v_mfma_f32_16x16x32_f16 v[20:23], v[144:147], v[208:211], v[20:23]
	v_mfma_f32_16x16x32_f16 v[0:3], v[152:155], v[216:219], v[0:3]
	v_mfma_f32_16x16x32_f16 v[4:7], v[144:147], v[216:219], v[4:7]
	v_mfma_f32_16x16x32_f16 v[48:51], v[156:159], v[180:183], v[48:51]
	v_mfma_f32_16x16x32_f16 v[52:55], v[148:151], v[180:183], v[52:55]
	v_mfma_f32_16x16x32_f16 v[32:35], v[156:159], v[188:191], v[32:35]
	v_mfma_f32_16x16x32_f16 v[36:39], v[148:151], v[188:191], v[36:39]
	v_mfma_f32_16x16x32_f16 v[16:19], v[156:159], v[212:215], v[16:19]
	v_mfma_f32_16x16x32_f16 v[20:23], v[148:151], v[212:215], v[20:23]
	v_mfma_f32_16x16x32_f16 v[0:3], v[156:159], v[220:223], v[0:3]
	v_mfma_f32_16x16x32_f16 v[4:7], v[148:151], v[220:223], v[4:7]
	s_barrier
; #define PG8_STAGE(bufoff, gbase, voff) do { _Pragma("unroll") for (int _i = 0; _i < 2; ++_i) \
;         __builtin_amdgcn_global_load_lds((const unsigned*)((const char*)(gbase) + (voff)[_i]), (PG8_LAS unsigned*)(lds + (bufoff) + ldsw + _i * 8192), 16, 0, 0); } while (0)
; #define PG8_LDA(dst, b, h) do { _Pragma("unroll") for (int m = 0; m < 4; ++m) _Pragma("unroll") for (int k = 0; k < 2; ++k) dst[m][k] = *(const PG8_LAS bf16x8*)(lds + PG8_SA(b, h) + aoff + m * 2048 + k * 1024); } while (0)
; #define PG8_LDB(dst, b, h) do { _Pragma("unroll") for (int n = 0; n < 2; ++n) _Pragma("unroll") for (int k = 0; k < 2; ++k) dst[n][k] = *(const PG8_LAS bf16x8*)(lds + PG8_SB(b, h) + boff + n * 2048 + k * 1024); } while (0)
; #define PG8_MMA(ai, bj, At, Bt) do { __builtin_amdgcn_s_setprio(1); _Pragma("unroll") for (int m = 0; m < 4; ++m) _Pragma("unroll") for (int n = 0; n < 2; ++n) _Pragma("unroll") for (int k = 0; k < 2; ++k) \
;         acc[ai][bj][m][n] = __builtin_amdgcn_mfma_f32_16x16x32_f16(Bt[n][k], At[m][k], acc[ai][bj][m][n], 0, 0, 0); __builtin_amdgcn_s_setprio(0); } while (0)
; #define PG8_WAIT_V(n) asm volatile("s_waitcnt vmcnt(" #n ")" ::: "memory")
; #define PG8_WAIT_L(n) asm volatile("s_waitcnt lgkmcnt(" #n ")" ::: "memory")
; #define PG8_BAR __builtin_amdgcn_s_barrier()
; #define PG8_SCHED __builtin_amdgcn_sched_barrier(0)
; template <class Epi, class Sched, bool ALIGN_EPI = false, bool SP2 = false>
; __device__ __forceinline__ void gemm_phase(PG8_LAS unsigned char* lds, const Gemm g, const Sched& S, const Epi& E) {
;     ...
;         for (int t = 0; t < nt; t += 2) {
;     ...
;             PG8_LDB(B0, 1, 0); PG8_LDB(B1, 1, 1); PG8_SCHED; PG8_LDA(At, 1, 0); PG8_STAGE(PG8_SA(0, 1), a2 + hstep, voffA);
;             PG8_WAIT_V(8); PG8_WAIT_L(0); PG8_BAR; PG8_MMA(0, 0, At, B0); PG8_MMA(0, 1, At, B1); PG8_BAR; PG8_SCHED;
;             PG8_LDA(At, 1, 1); PG8_STAGE(PG8_SB(1, 0), b3, voffB); PG8_STAGE(PG8_SB(1, 1), b3 + hstep, voffB); PG8_STAGE(PG8_SA(1, 0), a3, voffA);
;             PG8_WAIT_V(8); PG8_WAIT_L(0); PG8_BAR; PG8_MMA(1, 0, At, B0); PG8_MMA(1, 1, At, B1); PG8_BAR; PG8_SCHED;
	s_add_i32 s92, 0, 0x18000
	s_add_i32 s93, 0, 0x1c000
	v_add_u32_e32 v140, s92, v196
	v_add_u32_e32 v156, s93, v196
	ds_read_b128 v[128:131], v140
	ds_read_b128 v[132:135], v140 offset:1024
	ds_read_b128 v[136:139], v140 offset:2048
	ds_read_b128 v[140:143], v140 offset:3072
	ds_read_b128 v[144:147], v156
	ds_read_b128 v[148:151], v156 offset:1024
	ds_read_b128 v[152:155], v156 offset:2048
	ds_read_b128 v[156:159], v156 offset:3072
	s_add_u32 s44, s44, 0x80000
	s_addc_u32 s45, s45, 0
	s_mov_b32 m0, s65
	ds_read_b128 v[176:179], v200 offset:32768
	ds_read_b128 v[180:183], v200 offset:33792
	ds_read_b128 v[184:187], v200 offset:34816
	ds_read_b128 v[188:191], v200 offset:35840
	ds_read_b128 v[208:211], v200 offset:36864
	ds_read_b128 v[212:215], v200 offset:37888
	ds_read_b128 v[216:219], v200 offset:38912
	ds_read_b128 v[220:223], v200 offset:39936
	global_load_lds_dwordx4 v160, s[44:45]
	s_mov_b32 m0, s66
	s_nop 0
	global_load_lds_dwordx4 v164, s[44:45]
	s_waitcnt vmcnt(8)
	s_waitcnt lgkmcnt(0)
	s_barrier
	v_mfma_f32_16x16x32_f16 v[120:123], v[136:139], v[176:179], v[120:123]
	v_mfma_f32_16x16x32_f16 v[124:127], v[128:131], v[176:179], v[124:127]
	v_mfma_f32_16x16x32_f16 v[104:107], v[136:139], v[184:187], v[104:107]
	v_mfma_f32_16x16x32_f16 v[108:111], v[128:131], v[184:187], v[108:111]
	v_mfma_f32_16x16x32_f16 v[88:91], v[136:139], v[208:211], v[88:91]
	v_mfma_f32_16x16x32_f16 v[92:95], v[128:131], v[208:211], v[92:95]
	v_mfma_f32_16x16x32_f16 v[72:75], v[136:139], v[216:219], v[72:75]
	v_mfma_f32_16x16x32_f16 v[76:79], v[128:131], v[216:219], v[76:79]
	v_mfma_f32_16x16x32_f16 v[120:123], v[140:143], v[180:183], v[120:123]
	v_mfma_f32_16x16x32_f16 v[124:127], v[132:135], v[180:183], v[124:127]
	v_mfma_f32_16x16x32_f16 v[104:107], v[140:143], v[188:191], v[104:107]
	v_mfma_f32_16x16x32_f16 v[108:111], v[132:135], v[188:191], v[108:111]
	v_mfma_f32_16x16x32_f16 v[88:91], v[140:143], v[212:215], v[88:91]
	v_mfma_f32_16x16x32_f16 v[92:95], v[132:135], v[212:215], v[92:95]
	v_mfma_f32_16x16x32_f16 v[72:75], v[140:143], v[220:223], v[72:75]
	v_mfma_f32_16x16x32_f16 v[76:79], v[132:135], v[220:223], v[76:79]
	v_mfma_f32_16x16x32_f16 v[112:115], v[152:155], v[176:179], v[112:115]
	v_mfma_f32_16x16x32_f16 v[116:119], v[144:147], v[176:179], v[116:119]
	v_mfma_f32_16x16x32_f16 v[96:99], v[152:155], v[184:187], v[96:99]
	v_mfma_f32_16x16x32_f16 v[100:103], v[144:147], v[184:187], v[100:103]
	v_mfma_f32_16x16x32_f16 v[80:83], v[152:155], v[208:211], v[80:83]
	v_mfma_f32_16x16x32_f16 v[84:87], v[144:147], v[208:211], v[84:87]
	v_mfma_f32_16x16x32_f16 v[64:67], v[152:155], v[216:219], v[64:67]
	v_mfma_f32_16x16x32_f16 v[68:71], v[144:147], v[216:219], v[68:71]
	v_mfma_f32_16x16x32_f16 v[112:115], v[156:159], v[180:183], v[112:115]
	v_mfma_f32_16x16x32_f16 v[116:119], v[148:151], v[180:183], v[116:119]
	v_mfma_f32_16x16x32_f16 v[96:99], v[156:159], v[188:191], v[96:99]
	v_mfma_f32_16x16x32_f16 v[100:103], v[148:151], v[188:191], v[100:103]
	v_mfma_f32_16x16x32_f16 v[80:83], v[156:159], v[212:215], v[80:83]
	v_mfma_f32_16x16x32_f16 v[84:87], v[148:151], v[212:215], v[84:87]
	v_mfma_f32_16x16x32_f16 v[64:67], v[156:159], v[220:223], v[64:67]
	v_mfma_f32_16x16x32_f16 v[68:71], v[148:151], v[220:223], v[68:71]
	s_barrier
	s_add_i32 s44, s92, s63
	s_mov_b32 m0, s44
	ds_read_b128 v[176:179], v200 offset:49152
	ds_read_b128 v[180:183], v200 offset:50176
	ds_read_b128 v[184:187], v200 offset:51200
	ds_read_b128 v[188:191], v200 offset:52224
	ds_read_b128 v[208:211], v200 offset:53248
	ds_read_b128 v[212:215], v200 offset:54272
	ds_read_b128 v[216:219], v200 offset:55296
	ds_read_b128 v[220:223], v200 offset:56320
	global_load_lds_dwordx4 v162, s[98:99]
	s_add_i32 m0, s44, 0x2000
	s_add_u32 s42, s42, 0x80080
	s_addc_u32 s43, s43, 0
	s_add_i32 s44, s93, s63
	global_load_lds_dwordx4 v166, s[98:99]
	s_mov_b32 m0, s44
	s_nop 0
	global_load_lds_dwordx4 v162, s[42:43]
	s_add_i32 m0, s44, 0x2000
	s_nop 0
	global_load_lds_dwordx4 v166, s[42:43]
	s_mov_b32 m0, s68
	s_nop 0
	global_load_lds_dwordx4 v160, s[100:101]
	s_mov_b32 m0, s69
	s_nop 0
	global_load_lds_dwordx4 v164, s[100:101]
	s_waitcnt vmcnt(8)
	s_waitcnt lgkmcnt(0)
	s_barrier
	v_mfma_f32_16x16x32_f16 v[56:59], v[136:139], v[176:179], v[56:59]
	v_mfma_f32_16x16x32_f16 v[60:63], v[128:131], v[176:179], v[60:63]
	v_mfma_f32_16x16x32_f16 v[40:43], v[136:139], v[184:187], v[40:43]
	v_mfma_f32_16x16x32_f16 v[44:47], v[128:131], v[184:187], v[44:47]
	v_mfma_f32_16x16x32_f16 v[24:27], v[136:139], v[208:211], v[24:27]
	v_mfma_f32_16x16x32_f16 v[28:31], v[128:131], v[208:211], v[28:31]
	v_mfma_f32_16x16x32_f16 v[8:11], v[136:139], v[216:219], v[8:11]
	v_mfma_f32_16x16x32_f16 v[12:15], v[128:131], v[216:219], v[12:15]
	v_mfma_f32_16x16x32_f16 v[56:59], v[140:143], v[180:183], v[56:59]
	v_mfma_f32_16x16x32_f16 v[60:63], v[132:135], v[180:183], v[60:63]
	v_mfma_f32_16x16x32_f16 v[40:43], v[140:143], v[188:191], v[40:43]
	v_mfma_f32_16x16x32_f16 v[44:47], v[132:135], v[188:191], v[44:47]
	v_mfma_f32_16x16x32_f16 v[24:27], v[140:143], v[212:215], v[24:27]
	v_mfma_f32_16x16x32_f16 v[28:31], v[132:135], v[212:215], v[28:31]
	v_mfma_f32_16x16x32_f16 v[8:11], v[140:143], v[220:223], v[8:11]
	v_mfma_f32_16x16x32_f16 v[12:15], v[132:135], v[220:223], v[12:15]
	v_mfma_f32_16x16x32_f16 v[48:51], v[152:155], v[176:179], v[48:51]
	v_mfma_f32_16x16x32_f16 v[52:55], v[144:147], v[176:179], v[52:55]
	v_mfma_f32_16x16x32_f16 v[32:35], v[152:155], v[184:187], v[32:35]
	v_mfma_f32_16x16x32_f16 v[36:39], v[144:147], v[184:187], v[36:39]
	v_mfma_f32_16x16x32_f16 v[16:19], v[152:155], v[208:211], v[16:19]
	v_mfma_f32_16x16x32_f16 v[20:23], v[144:147], v[208:211], v[20:23]
	v_mfma_f32_16x16x32_f16 v[0:3], v[152:155], v[216:219], v[0:3]
	v_mfma_f32_16x16x32_f16 v[4:7], v[144:147], v[216:219], v[4:7]
	v_mfma_f32_16x16x32_f16 v[48:51], v[156:159], v[180:183], v[48:51]
	v_mfma_f32_16x16x32_f16 v[52:55], v[148:151], v[180:183], v[52:55]
	v_mfma_f32_16x16x32_f16 v[32:35], v[156:159], v[188:191], v[32:35]
	v_mfma_f32_16x16x32_f16 v[36:39], v[148:151], v[188:191], v[36:39]
	v_mfma_f32_16x16x32_f16 v[16:19], v[156:159], v[212:215], v[16:19]
	v_mfma_f32_16x16x32_f16 v[20:23], v[148:151], v[212:215], v[20:23]
	v_mfma_f32_16x16x32_f16 v[0:3], v[156:159], v[220:223], v[0:3]
	v_mfma_f32_16x16x32_f16 v[4:7], v[148:151], v[220:223], v[4:7]
	s_barrier
	s_add_i32 s91, s91, 2
	s_add_u32 s89, s89, 0x100
	s_addc_u32 s90, s90, 0
	s_add_u32 s40, s40, 0x100
	s_addc_u32 s41, s41, 0
	s_cmp_gt_u32 s91, 29
	s_cbranch_scc0 .LBB0_577
	s_and_b64 vcc, exec, s[18:19]
	s_cbranch_vccz .LBB0_580
	s_barrier

; #define PG8_STAGE(bufoff, gbase, voff) do { _Pragma("unroll") for (int _i = 0; _i < 2; ++_i) \
;         __builtin_amdgcn_global_load_lds((const unsigned*)((const char*)(gbase) + (voff)[_i]), (PG8_LAS unsigned*)(lds + (bufoff) + ldsw + _i * 8192), 16, 0, 0); } while (0)
; #define PG8_LDA(dst, b, h) do { _Pragma("unroll") for (int m = 0; m < 4; ++m) _Pragma("unroll") for (int k = 0; k < 2; ++k) dst[m][k] = *(const PG8_LAS bf16x8*)(lds + PG8_SA(b, h) + aoff + m * 2048 + k * 1024); } while (0)
; #define PG8_LDB(dst, b, h) do { _Pragma("unroll") for (int n = 0; n < 2; ++n) _Pragma("unroll") for (int k = 0; k < 2; ++k) dst[n][k] = *(const PG8_LAS bf16x8*)(lds + PG8_SB(b, h) + boff + n * 2048 + k * 1024); } while (0)
; #define PG8_MMA(ai, bj, At, Bt) do { __builtin_amdgcn_s_setprio(1); _Pragma("unroll") for (int m = 0; m < 4; ++m) _Pragma("unroll") for (int n = 0; n < 2; ++n) _Pragma("unroll") for (int k = 0; k < 2; ++k) \
;         acc[ai][bj][m][n] = __builtin_amdgcn_mfma_f32_16x16x32_f16(Bt[n][k], At[m][k], acc[ai][bj][m][n], 0, 0, 0); __builtin_amdgcn_s_setprio(0); } while (0)
; #define PG8_WAIT_V(n) asm volatile("s_waitcnt vmcnt(" #n ")" ::: "memory")
; #define PG8_BAR __builtin_amdgcn_s_barrier()
; template <class Epi, class Sched, bool ALIGN_EPI = false, bool SP2 = false>
; __device__ __forceinline__ void gemm_phase(PG8_LAS unsigned char* lds, const Gemm g, const Sched& S, const Epi& E) {
;     ...
;         const char* nA = has_next ? (const char*)g.A + (size_t)nxt.pm * tstep : cA; const char* nB = has_next ? (const char*)g.Bt + (size_t)nxt.pn * tstep : cB;
;         for (int t = 0; t < nt; t += 2) {
;             const bool last = (t == nt - 2);
;             const char* a1 = cA + (size_t)(t + 1) * kstep;
;             const char* a2 = last ? nA : cA + (size_t)(t + 2) * kstep; const char* b2 = last ? nB : cB + (size_t)(t + 2) * kstep;
;     ...
;             PG8_LDB(B0, 0, 0); PG8_LDB(B1, 0, 1); PG8_SCHED; PG8_LDA(At, 0, 0); PG8_STAGE(PG8_SA(1, 1), a1 + hstep, voffA);
;             PG8_WAIT_V(8); PG8_WAIT_L(0); PG8_BAR; PG8_MMA(0, 0, At, B0); PG8_MMA(0, 1, At, B1); PG8_BAR; PG8_SCHED;
;             PG8_LDA(At, 0, 1); PG8_STAGE(PG8_SB(0, 0), b2, voffB); PG8_STAGE(PG8_SB(0, 1), b2 + hstep, voffB); PG8_STAGE(PG8_SA(0, 0), a2, voffA);
;             PG8_WAIT_V(8); PG8_WAIT_L(0); PG8_BAR; PG8_MMA(1, 0, At, B0); PG8_MMA(1, 1, At, B1); PG8_BAR; PG8_SCHED;
.LBB0_655:
	ds_read_b128 v[128:131], v211
	ds_read_b128 v[132:135], v211 offset:1024
	ds_read_b128 v[136:139], v211 offset:2048
	ds_read_b128 v[140:143], v211 offset:3072
	ds_read_b128 v[144:147], v212
	ds_read_b128 v[148:151], v212 offset:1024
	ds_read_b128 v[152:155], v212 offset:2048
	ds_read_b128 v[156:159], v212 offset:3072
	s_add_u32 s42, s40, 0xffe00080
	s_addc_u32 s43, s41, -1
	s_cmpk_eq_i32 s86, 0x7c
	s_cselect_b32 s45, s29, s43
	s_cselect_b32 s44, s37, s42
	s_cselect_b32 s43, s27, s83
	s_cselect_b32 s42, s81, s82
	s_add_i32 m0, s39, 0xc000
	ds_read_b128 v[160:163], v213
	ds_read_b128 v[164:167], v213 offset:1024
	ds_read_b128 v[184:187], v213 offset:2048
	ds_read_b128 v[188:191], v213 offset:3072
	ds_read_b128 v[192:195], v213 offset:4096
	ds_read_b128 v[196:199], v213 offset:5120
	ds_read_b128 v[200:203], v213 offset:6144
	ds_read_b128 v[214:217], v213 offset:7168
	global_load_lds_dwordx4 v178, s[40:41]
	s_add_i32 m0, s39, 0xe000
	s_nop 0
	global_load_lds_dwordx4 v176, s[40:41]
	s_waitcnt vmcnt(8)
	s_waitcnt lgkmcnt(0)
	s_barrier
	v_mfma_f32_16x16x32_f16 v[120:123], v[136:139], v[160:163], v[120:123]
	v_mfma_f32_16x16x32_f16 v[124:127], v[128:131], v[160:163], v[124:127]
	v_mfma_f32_16x16x32_f16 v[104:107], v[136:139], v[184:187], v[104:107]
	v_mfma_f32_16x16x32_f16 v[108:111], v[128:131], v[184:187], v[108:111]
	v_mfma_f32_16x16x32_f16 v[88:91], v[136:139], v[192:195], v[88:91]
	v_mfma_f32_16x16x32_f16 v[92:95], v[128:131], v[192:195], v[92:95]
	v_mfma_f32_16x16x32_f16 v[72:75], v[136:139], v[200:203], v[72:75]
	v_mfma_f32_16x16x32_f16 v[76:79], v[128:131], v[200:203], v[76:79]
	v_mfma_f32_16x16x32_f16 v[120:123], v[140:143], v[164:167], v[120:123]
	v_mfma_f32_16x16x32_f16 v[124:127], v[132:135], v[164:167], v[124:127]
	v_mfma_f32_16x16x32_f16 v[104:107], v[140:143], v[188:191], v[104:107]
	v_mfma_f32_16x16x32_f16 v[108:111], v[132:135], v[188:191], v[108:111]
	v_mfma_f32_16x16x32_f16 v[88:91], v[140:143], v[196:199], v[88:91]
	v_mfma_f32_16x16x32_f16 v[92:95], v[132:135], v[196:199], v[92:95]
	v_mfma_f32_16x16x32_f16 v[72:75], v[140:143], v[214:217], v[72:75]
	v_mfma_f32_16x16x32_f16 v[76:79], v[132:135], v[214:217], v[76:79]
	v_mfma_f32_16x16x32_f16 v[112:115], v[152:155], v[160:163], v[112:115]
	v_mfma_f32_16x16x32_f16 v[116:119], v[144:147], v[160:163], v[116:119]
	v_mfma_f32_16x16x32_f16 v[96:99], v[152:155], v[184:187], v[96:99]
	v_mfma_f32_16x16x32_f16 v[100:103], v[144:147], v[184:187], v[100:103]
	v_mfma_f32_16x16x32_f16 v[80:83], v[152:155], v[192:195], v[80:83]
	v_mfma_f32_16x16x32_f16 v[84:87], v[144:147], v[192:195], v[84:87]
	v_mfma_f32_16x16x32_f16 v[64:67], v[152:155], v[200:203], v[64:67]
	v_mfma_f32_16x16x32_f16 v[68:71], v[144:147], v[200:203], v[68:71]
	v_mfma_f32_16x16x32_f16 v[112:115], v[156:159], v[164:167], v[112:115]
	v_mfma_f32_16x16x32_f16 v[116:119], v[148:151], v[164:167], v[116:119]
	v_mfma_f32_16x16x32_f16 v[96:99], v[156:159], v[188:191], v[96:99]
	v_mfma_f32_16x16x32_f16 v[100:103], v[148:151], v[188:191], v[100:103]
	v_mfma_f32_16x16x32_f16 v[80:83], v[156:159], v[196:199], v[80:83]
	v_mfma_f32_16x16x32_f16 v[84:87], v[148:151], v[196:199], v[84:87]
	v_mfma_f32_16x16x32_f16 v[64:67], v[156:159], v[214:217], v[64:67]
	v_mfma_f32_16x16x32_f16 v[68:71], v[148:151], v[214:217], v[68:71]
	s_barrier
	s_add_i32 s87, s69, s61
	s_add_u32 s98, s42, s18
	s_addc_u32 s99, s43, s19
	s_mov_b32 m0, s87
	ds_read_b128 v[160:163], v213 offset:16384
	ds_read_b128 v[164:167], v213 offset:17408
	ds_read_b128 v[184:187], v213 offset:18432
	ds_read_b128 v[188:191], v213 offset:19456
	ds_read_b128 v[192:195], v213 offset:20480
	ds_read_b128 v[196:199], v213 offset:21504
	ds_read_b128 v[200:203], v213 offset:22528
	ds_read_b128 v[214:217], v213 offset:23552
	global_load_lds_dwordx4 v170, s[42:43]
	s_add_i32 m0, s87, 0x2000
	s_add_u32 s88, s42, 0x200000
	s_addc_u32 s89, s43, 0
	s_add_i32 s87, s74, s61
	global_load_lds_dwordx4 v174, s[42:43]
	s_mov_b32 m0, s87
	s_nop 0
	global_load_lds_dwordx4 v170, s[88:89]
	s_add_i32 m0, s87, 0x2000
	s_nop 0
	global_load_lds_dwordx4 v174, s[88:89]
	s_mov_b32 m0, s39
	s_add_u32 s100, s44, s18
	s_addc_u32 s101, s45, s19
	global_load_lds_dwordx4 v168, s[44:45]
	s_mov_b32 m0, s62
	s_nop 0
	global_load_lds_dwordx4 v172, s[44:45]
	s_waitcnt vmcnt(8)
	s_waitcnt lgkmcnt(0)
	s_barrier
	v_mfma_f32_16x16x32_f16 v[56:59], v[136:139], v[160:163], v[56:59]
	v_mfma_f32_16x16x32_f16 v[60:63], v[128:131], v[160:163], v[60:63]
	v_mfma_f32_16x16x32_f16 v[40:43], v[136:139], v[184:187], v[40:43]
	v_mfma_f32_16x16x32_f16 v[44:47], v[128:131], v[184:187], v[44:47]
	v_mfma_f32_16x16x32_f16 v[24:27], v[136:139], v[192:195], v[24:27]
	v_mfma_f32_16x16x32_f16 v[28:31], v[128:131], v[192:195], v[28:31]
	v_mfma_f32_16x16x32_f16 v[8:11], v[136:139], v[200:203], v[8:11]
	v_mfma_f32_16x16x32_f16 v[12:15], v[128:131], v[200:203], v[12:15]
	v_mfma_f32_16x16x32_f16 v[56:59], v[140:143], v[164:167], v[56:59]
	v_mfma_f32_16x16x32_f16 v[60:63], v[132:135], v[164:167], v[60:63]
	v_mfma_f32_16x16x32_f16 v[40:43], v[140:143], v[188:191], v[40:43]
	v_mfma_f32_16x16x32_f16 v[44:47], v[132:135], v[188:191], v[44:47]
	v_mfma_f32_16x16x32_f16 v[24:27], v[140:143], v[196:199], v[24:27]
	v_mfma_f32_16x16x32_f16 v[28:31], v[132:135], v[196:199], v[28:31]
	v_mfma_f32_16x16x32_f16 v[8:11], v[140:143], v[214:217], v[8:11]
	v_mfma_f32_16x16x32_f16 v[12:15], v[132:135], v[214:217], v[12:15]
	v_mfma_f32_16x16x32_f16 v[48:51], v[152:155], v[160:163], v[48:51]
	v_mfma_f32_16x16x32_f16 v[52:55], v[144:147], v[160:163], v[52:55]
	v_mfma_f32_16x16x32_f16 v[32:35], v[152:155], v[184:187], v[32:35]
	v_mfma_f32_16x16x32_f16 v[36:39], v[144:147], v[184:187], v[36:39]
	v_mfma_f32_16x16x32_f16 v[16:19], v[152:155], v[192:195], v[16:19]
	v_mfma_f32_16x16x32_f16 v[20:23], v[144:147], v[192:195], v[20:23]
	v_mfma_f32_16x16x32_f16 v[0:3], v[152:155], v[200:203], v[0:3]
	v_mfma_f32_16x16x32_f16 v[4:7], v[144:147], v[200:203], v[4:7]
	v_mfma_f32_16x16x32_f16 v[48:51], v[156:159], v[164:167], v[48:51]
	v_mfma_f32_16x16x32_f16 v[52:55], v[148:151], v[164:167], v[52:55]
	v_mfma_f32_16x16x32_f16 v[32:35], v[156:159], v[188:191], v[32:35]
	v_mfma_f32_16x16x32_f16 v[36:39], v[148:151], v[188:191], v[36:39]
	v_mfma_f32_16x16x32_f16 v[16:19], v[156:159], v[196:199], v[16:19]
	v_mfma_f32_16x16x32_f16 v[20:23], v[148:151], v[196:199], v[20:23]
	v_mfma_f32_16x16x32_f16 v[0:3], v[156:159], v[214:217], v[0:3]
	v_mfma_f32_16x16x32_f16 v[4:7], v[148:151], v[214:217], v[4:7]
	s_barrier
; #define PG8_STAGE(bufoff, gbase, voff) do { _Pragma("unroll") for (int _i = 0; _i < 2; ++_i) \
;         __builtin_amdgcn_global_load_lds((const unsigned*)((const char*)(gbase) + (voff)[_i]), (PG8_LAS unsigned*)(lds + (bufoff) + ldsw + _i * 8192), 16, 0, 0); } while (0)
; #define PG8_LDA(dst, b, h) do { _Pragma("unroll") for (int m = 0; m < 4; ++m) _Pragma("unroll") for (int k = 0; k < 2; ++k) dst[m][k] = *(const PG8_LAS bf16x8*)(lds + PG8_SA(b, h) + aoff + m * 2048 + k * 1024); } while (0)
; #define PG8_LDB(dst, b, h) do { _Pragma("unroll") for (int n = 0; n < 2; ++n) _Pragma("unroll") for (int k = 0; k < 2; ++k) dst[n][k] = *(const PG8_LAS bf16x8*)(lds + PG8_SB(b, h) + boff + n * 2048 + k * 1024); } while (0)
; #define PG8_MMA(ai, bj, At, Bt) do { __builtin_amdgcn_s_setprio(1); _Pragma("unroll") for (int m = 0; m < 4; ++m) _Pragma("unroll") for (int n = 0; n < 2; ++n) _Pragma("unroll") for (int k = 0; k < 2; ++k) \
;         acc[ai][bj][m][n] = __builtin_amdgcn_mfma_f32_16x16x32_f16(Bt[n][k], At[m][k], acc[ai][bj][m][n], 0, 0, 0); __builtin_amdgcn_s_setprio(0); } while (0)
; #define PG8_WAIT_V(n) asm volatile("s_waitcnt vmcnt(" #n ")" ::: "memory")
; #define PG8_WAIT_L(n) asm volatile("s_waitcnt lgkmcnt(" #n ")" ::: "memory")
; #define PG8_BAR __builtin_amdgcn_s_barrier()
; #define PG8_SCHED __builtin_amdgcn_sched_barrier(0)
; template <class Epi, class Sched, bool ALIGN_EPI = false, bool SP2 = false>
; __device__ __forceinline__ void gemm_phase(PG8_LAS unsigned char* lds, const Gemm g, const Sched& S, const Epi& E) {
;     ...
;         for (int t = 0; t < nt; t += 2) {
;     ...
;             PG8_LDB(B0, 1, 0); PG8_LDB(B1, 1, 1); PG8_SCHED; PG8_LDA(At, 1, 0); PG8_STAGE(PG8_SA(0, 1), a2 + hstep, voffA);
;             PG8_WAIT_V(8); PG8_WAIT_L(0); PG8_BAR; PG8_MMA(0, 0, At, B0); PG8_MMA(0, 1, At, B1); PG8_BAR; PG8_SCHED;
;             PG8_LDA(At, 1, 1); PG8_STAGE(PG8_SB(1, 0), b3, voffB); PG8_STAGE(PG8_SB(1, 1), b3 + hstep, voffB); PG8_STAGE(PG8_SA(1, 0), a3, voffA);
;             PG8_WAIT_V(8); PG8_WAIT_L(0); PG8_BAR; PG8_MMA(1, 0, At, B0); PG8_MMA(1, 1, At, B1); PG8_BAR; PG8_SCHED;
	s_add_i32 s87, 0, 0x18000
	s_add_i32 s88, 0, 0x1c000
	v_add_u32_e32 v140, s87, v209
	v_add_u32_e32 v156, s88, v209
	ds_read_b128 v[128:131], v140
	ds_read_b128 v[132:135], v140 offset:1024
	ds_read_b128 v[136:139], v140 offset:2048
	ds_read_b128 v[140:143], v140 offset:3072
	ds_read_b128 v[144:147], v156
	ds_read_b128 v[148:151], v156 offset:1024
	ds_read_b128 v[152:155], v156 offset:2048
	ds_read_b128 v[156:159], v156 offset:3072
	s_add_u32 s44, s44, 0x200000
	s_addc_u32 s45, s45, 0
	s_mov_b32 m0, s63
	ds_read_b128 v[160:163], v213 offset:32768
	ds_read_b128 v[164:167], v213 offset:33792
	ds_read_b128 v[184:187], v213 offset:34816
	ds_read_b128 v[188:191], v213 offset:35840
	ds_read_b128 v[192:195], v213 offset:36864
	ds_read_b128 v[196:199], v213 offset:37888
	ds_read_b128 v[200:203], v213 offset:38912
	ds_read_b128 v[214:217], v213 offset:39936
	global_load_lds_dwordx4 v168, s[44:45]
	s_mov_b32 m0, s64
	s_nop 0
	global_load_lds_dwordx4 v172, s[44:45]
	s_waitcnt vmcnt(8)
	s_waitcnt lgkmcnt(0)
	s_barrier
	v_mfma_f32_16x16x32_f16 v[120:123], v[136:139], v[160:163], v[120:123]
	v_mfma_f32_16x16x32_f16 v[124:127], v[128:131], v[160:163], v[124:127]
	v_mfma_f32_16x16x32_f16 v[104:107], v[136:139], v[184:187], v[104:107]
	v_mfma_f32_16x16x32_f16 v[108:111], v[128:131], v[184:187], v[108:111]
	v_mfma_f32_16x16x32_f16 v[88:91], v[136:139], v[192:195], v[88:91]
	v_mfma_f32_16x16x32_f16 v[92:95], v[128:131], v[192:195], v[92:95]
	v_mfma_f32_16x16x32_f16 v[72:75], v[136:139], v[200:203], v[72:75]
	v_mfma_f32_16x16x32_f16 v[76:79], v[128:131], v[200:203], v[76:79]
	v_mfma_f32_16x16x32_f16 v[120:123], v[140:143], v[164:167], v[120:123]
	v_mfma_f32_16x16x32_f16 v[124:127], v[132:135], v[164:167], v[124:127]
	v_mfma_f32_16x16x32_f16 v[104:107], v[140:143], v[188:191], v[104:107]
	v_mfma_f32_16x16x32_f16 v[108:111], v[132:135], v[188:191], v[108:111]
	v_mfma_f32_16x16x32_f16 v[88:91], v[140:143], v[196:199], v[88:91]
	v_mfma_f32_16x16x32_f16 v[92:95], v[132:135], v[196:199], v[92:95]
	v_mfma_f32_16x16x32_f16 v[72:75], v[140:143], v[214:217], v[72:75]
	v_mfma_f32_16x16x32_f16 v[76:79], v[132:135], v[214:217], v[76:79]
	v_mfma_f32_16x16x32_f16 v[112:115], v[152:155], v[160:163], v[112:115]
	v_mfma_f32_16x16x32_f16 v[116:119], v[144:147], v[160:163], v[116:119]
	v_mfma_f32_16x16x32_f16 v[96:99], v[152:155], v[184:187], v[96:99]
	v_mfma_f32_16x16x32_f16 v[100:103], v[144:147], v[184:187], v[100:103]
	v_mfma_f32_16x16x32_f16 v[80:83], v[152:155], v[192:195], v[80:83]
	v_mfma_f32_16x16x32_f16 v[84:87], v[144:147], v[192:195], v[84:87]
	v_mfma_f32_16x16x32_f16 v[64:67], v[152:155], v[200:203], v[64:67]
	v_mfma_f32_16x16x32_f16 v[68:71], v[144:147], v[200:203], v[68:71]
	v_mfma_f32_16x16x32_f16 v[112:115], v[156:159], v[164:167], v[112:115]
	v_mfma_f32_16x16x32_f16 v[116:119], v[148:151], v[164:167], v[116:119]
	v_mfma_f32_16x16x32_f16 v[96:99], v[156:159], v[188:191], v[96:99]
	v_mfma_f32_16x16x32_f16 v[100:103], v[148:151], v[188:191], v[100:103]
	v_mfma_f32_16x16x32_f16 v[80:83], v[156:159], v[196:199], v[80:83]
	v_mfma_f32_16x16x32_f16 v[84:87], v[148:151], v[196:199], v[84:87]
	v_mfma_f32_16x16x32_f16 v[64:67], v[156:159], v[214:217], v[64:67]
	v_mfma_f32_16x16x32_f16 v[68:71], v[148:151], v[214:217], v[68:71]
	s_barrier
	s_add_i32 s44, s87, s61
	s_mov_b32 m0, s44
	ds_read_b128 v[160:163], v213 offset:49152
	ds_read_b128 v[164:167], v213 offset:50176
	ds_read_b128 v[184:187], v213 offset:51200
	ds_read_b128 v[188:191], v213 offset:52224
	ds_read_b128 v[192:195], v213 offset:53248
	ds_read_b128 v[196:199], v213 offset:54272
	ds_read_b128 v[200:203], v213 offset:55296
	ds_read_b128 v[214:217], v213 offset:56320
	global_load_lds_dwordx4 v170, s[98:99]
	s_add_i32 m0, s44, 0x2000
	s_add_u32 s42, s42, 0x200080
	s_addc_u32 s43, s43, 0
	s_add_i32 s44, s88, s61
	global_load_lds_dwordx4 v174, s[98:99]
	s_mov_b32 m0, s44
	s_nop 0
	global_load_lds_dwordx4 v170, s[42:43]
	s_add_i32 m0, s44, 0x2000
	s_nop 0
	global_load_lds_dwordx4 v174, s[42:43]
	s_mov_b32 m0, s66
	s_nop 0
	global_load_lds_dwordx4 v168, s[100:101]
	s_mov_b32 m0, s67
	s_nop 0
	global_load_lds_dwordx4 v172, s[100:101]
	s_waitcnt vmcnt(8)
	s_waitcnt lgkmcnt(0)
	s_barrier
	v_mfma_f32_16x16x32_f16 v[56:59], v[136:139], v[160:163], v[56:59]
	v_mfma_f32_16x16x32_f16 v[60:63], v[128:131], v[160:163], v[60:63]
	v_mfma_f32_16x16x32_f16 v[40:43], v[136:139], v[184:187], v[40:43]
	v_mfma_f32_16x16x32_f16 v[44:47], v[128:131], v[184:187], v[44:47]
	v_mfma_f32_16x16x32_f16 v[24:27], v[136:139], v[192:195], v[24:27]
	v_mfma_f32_16x16x32_f16 v[28:31], v[128:131], v[192:195], v[28:31]
	v_mfma_f32_16x16x32_f16 v[8:11], v[136:139], v[200:203], v[8:11]
	v_mfma_f32_16x16x32_f16 v[12:15], v[128:131], v[200:203], v[12:15]
	v_mfma_f32_16x16x32_f16 v[56:59], v[140:143], v[164:167], v[56:59]
	v_mfma_f32_16x16x32_f16 v[60:63], v[132:135], v[164:167], v[60:63]
	v_mfma_f32_16x16x32_f16 v[40:43], v[140:143], v[188:191], v[40:43]
	v_mfma_f32_16x16x32_f16 v[44:47], v[132:135], v[188:191], v[44:47]
	v_mfma_f32_16x16x32_f16 v[24:27], v[140:143], v[196:199], v[24:27]
	v_mfma_f32_16x16x32_f16 v[28:31], v[132:135], v[196:199], v[28:31]
	v_mfma_f32_16x16x32_f16 v[8:11], v[140:143], v[214:217], v[8:11]
	v_mfma_f32_16x16x32_f16 v[12:15], v[132:135], v[214:217], v[12:15]
	v_mfma_f32_16x16x32_f16 v[48:51], v[152:155], v[160:163], v[48:51]
	v_mfma_f32_16x16x32_f16 v[52:55], v[144:147], v[160:163], v[52:55]
	v_mfma_f32_16x16x32_f16 v[32:35], v[152:155], v[184:187], v[32:35]
	v_mfma_f32_16x16x32_f16 v[36:39], v[144:147], v[184:187], v[36:39]
	v_mfma_f32_16x16x32_f16 v[16:19], v[152:155], v[192:195], v[16:19]
	v_mfma_f32_16x16x32_f16 v[20:23], v[144:147], v[192:195], v[20:23]
	v_mfma_f32_16x16x32_f16 v[0:3], v[152:155], v[200:203], v[0:3]
	v_mfma_f32_16x16x32_f16 v[4:7], v[144:147], v[200:203], v[4:7]
	v_mfma_f32_16x16x32_f16 v[48:51], v[156:159], v[164:167], v[48:51]
	v_mfma_f32_16x16x32_f16 v[52:55], v[148:151], v[164:167], v[52:55]
	v_mfma_f32_16x16x32_f16 v[32:35], v[156:159], v[188:191], v[32:35]
	v_mfma_f32_16x16x32_f16 v[36:39], v[148:151], v[188:191], v[36:39]
	v_mfma_f32_16x16x32_f16 v[16:19], v[156:159], v[196:199], v[16:19]
	v_mfma_f32_16x16x32_f16 v[20:23], v[148:151], v[196:199], v[20:23]
	v_mfma_f32_16x16x32_f16 v[0:3], v[156:159], v[214:217], v[0:3]
	v_mfma_f32_16x16x32_f16 v[4:7], v[148:151], v[214:217], v[4:7]
	s_barrier
	s_add_i32 s86, s86, 2
	s_add_u32 s82, s82, 0x100
	s_addc_u32 s83, s83, 0
	s_add_u32 s40, s40, 0x100
	s_addc_u32 s41, s41, 0
	s_cmpk_gt_u32 s86, 0x7d
	s_cbranch_scc0 .LBB0_655
	s_and_b64 vcc, exec, s[20:21]
	s_cbranch_vccz .LBB0_658
	s_barrier

; #define PG8_STAGE(bufoff, gbase, voff) do { _Pragma("unroll") for (int _i = 0; _i < 2; ++_i) \
;         __builtin_amdgcn_global_load_lds((const unsigned*)((const char*)(gbase) + (voff)[_i]), (PG8_LAS unsigned*)(lds + (bufoff) + ldsw + _i * 8192), 16, 0, 0); } while (0)
; #define PG8_LDA(dst, b, h) do { _Pragma("unroll") for (int m = 0; m < 4; ++m) _Pragma("unroll") for (int k = 0; k < 2; ++k) dst[m][k] = *(const PG8_LAS bf16x8*)(lds + PG8_SA(b, h) + aoff + m * 2048 + k * 1024); } while (0)
; #define PG8_LDB(dst, b, h) do { _Pragma("unroll") for (int n = 0; n < 2; ++n) _Pragma("unroll") for (int k = 0; k < 2; ++k) dst[n][k] = *(const PG8_LAS bf16x8*)(lds + PG8_SB(b, h) + boff + n * 2048 + k * 1024); } while (0)
; #define PG8_MMA(ai, bj, At, Bt) do { __builtin_amdgcn_s_setprio(1); _Pragma("unroll") for (int m = 0; m < 4; ++m) _Pragma("unroll") for (int n = 0; n < 2; ++n) _Pragma("unroll") for (int k = 0; k < 2; ++k) \
;         acc[ai][bj][m][n] = __builtin_amdgcn_mfma_f32_16x16x32_f16(Bt[n][k], At[m][k], acc[ai][bj][m][n], 0, 0, 0); __builtin_amdgcn_s_setprio(0); } while (0)
; #define PG8_WAIT_V(n) asm volatile("s_waitcnt vmcnt(" #n ")" ::: "memory")
; #define PG8_BAR __builtin_amdgcn_s_barrier()
; template <class Epi, class Sched, bool ALIGN_EPI = false, bool SP2 = false>
; __device__ __forceinline__ void gemm_phase(PG8_LAS unsigned char* lds, const Gemm g, const Sched& S, const Epi& E) {
;     ...
;         const char* nA = has_next ? (const char*)g.A + (size_t)nxt.pm * tstep : cA; const char* nB = has_next ? (const char*)g.Bt + (size_t)nxt.pn * tstep : cB;
;         for (int t = 0; t < nt; t += 2) {
;             const bool last = (t == nt - 2);
;             const char* a1 = cA + (size_t)(t + 1) * kstep;
;             const char* a2 = last ? nA : cA + (size_t)(t + 2) * kstep; const char* b2 = last ? nB : cB + (size_t)(t + 2) * kstep;
;     ...
;             PG8_LDB(B0, 0, 0); PG8_LDB(B1, 0, 1); PG8_SCHED; PG8_LDA(At, 0, 0); PG8_STAGE(PG8_SA(1, 1), a1 + hstep, voffA);
;             PG8_WAIT_V(8); PG8_WAIT_L(0); PG8_BAR; PG8_MMA(0, 0, At, B0); PG8_MMA(0, 1, At, B1); PG8_BAR; PG8_SCHED;
;             PG8_LDA(At, 0, 1); PG8_STAGE(PG8_SB(0, 0), b2, voffB); PG8_STAGE(PG8_SB(0, 1), b2 + hstep, voffB); PG8_STAGE(PG8_SA(0, 0), a2, voffA);
;             PG8_WAIT_V(8); PG8_WAIT_L(0); PG8_BAR; PG8_MMA(1, 0, At, B0); PG8_MMA(1, 1, At, B1); PG8_BAR; PG8_SCHED;
.LBB0_747:
	ds_read_b128 v[128:131], v191
	ds_read_b128 v[132:135], v191 offset:1024
	ds_read_b128 v[136:139], v191 offset:2048
	ds_read_b128 v[140:143], v191 offset:3072
	ds_read_b128 v[144:147], v192
	ds_read_b128 v[148:151], v192 offset:1024
	ds_read_b128 v[152:155], v192 offset:2048
	ds_read_b128 v[156:159], v192 offset:3072
	s_add_u32 s48, s44, 0xfff80080
	s_addc_u32 s49, s45, -1
	s_cmp_eq_u32 s90, 28
	s_cselect_b32 s51, s37, s49
	s_cselect_b32 s50, s86, s48
	s_cselect_b32 s49, s35, s89
	s_cselect_b32 s48, s87, s88
	s_add_i32 m0, s43, 0xc000
	ds_read_b128 v[176:179], v193
	ds_read_b128 v[180:183], v193 offset:1024
	ds_read_b128 v[184:187], v193 offset:2048
	ds_read_b128 v[194:197], v193 offset:3072
	ds_read_b128 v[198:201], v193 offset:4096
	ds_read_b128 v[208:211], v193 offset:5120
	ds_read_b128 v[212:215], v193 offset:6144
	ds_read_b128 v[216:219], v193 offset:7168
	global_load_lds_dwordx4 v170, s[44:45]
	s_add_i32 m0, s43, 0xe000
	s_nop 0
	global_load_lds_dwordx4 v168, s[44:45]
	s_waitcnt vmcnt(8)
	s_waitcnt lgkmcnt(0)
	s_barrier
	v_mfma_f32_16x16x32_f16 v[120:123], v[136:139], v[176:179], v[120:123]
	v_mfma_f32_16x16x32_f16 v[124:127], v[128:131], v[176:179], v[124:127]
	v_mfma_f32_16x16x32_f16 v[104:107], v[136:139], v[184:187], v[104:107]
	v_mfma_f32_16x16x32_f16 v[112:115], v[128:131], v[184:187], v[112:115]
	v_mfma_f32_16x16x32_f16 v[88:91], v[136:139], v[198:201], v[88:91]
	v_mfma_f32_16x16x32_f16 v[96:99], v[128:131], v[198:201], v[96:99]
	v_mfma_f32_16x16x32_f16 v[72:75], v[136:139], v[212:215], v[72:75]
	v_mfma_f32_16x16x32_f16 v[80:83], v[128:131], v[212:215], v[80:83]
	v_mfma_f32_16x16x32_f16 v[120:123], v[140:143], v[180:183], v[120:123]
	v_mfma_f32_16x16x32_f16 v[124:127], v[132:135], v[180:183], v[124:127]
	v_mfma_f32_16x16x32_f16 v[104:107], v[140:143], v[194:197], v[104:107]
	v_mfma_f32_16x16x32_f16 v[112:115], v[132:135], v[194:197], v[112:115]
	v_mfma_f32_16x16x32_f16 v[88:91], v[140:143], v[208:211], v[88:91]
	v_mfma_f32_16x16x32_f16 v[96:99], v[132:135], v[208:211], v[96:99]
	v_mfma_f32_16x16x32_f16 v[72:75], v[140:143], v[216:219], v[72:75]
	v_mfma_f32_16x16x32_f16 v[80:83], v[132:135], v[216:219], v[80:83]
	v_mfma_f32_16x16x32_f16 v[108:111], v[152:155], v[176:179], v[108:111]
	v_mfma_f32_16x16x32_f16 v[116:119], v[144:147], v[176:179], v[116:119]
	v_mfma_f32_16x16x32_f16 v[92:95], v[152:155], v[184:187], v[92:95]
	v_mfma_f32_16x16x32_f16 v[100:103], v[144:147], v[184:187], v[100:103]
	v_mfma_f32_16x16x32_f16 v[76:79], v[152:155], v[198:201], v[76:79]
	v_mfma_f32_16x16x32_f16 v[84:87], v[144:147], v[198:201], v[84:87]
	v_mfma_f32_16x16x32_f16 v[64:67], v[152:155], v[212:215], v[64:67]
	v_mfma_f32_16x16x32_f16 v[68:71], v[144:147], v[212:215], v[68:71]
	v_mfma_f32_16x16x32_f16 v[108:111], v[156:159], v[180:183], v[108:111]
	v_mfma_f32_16x16x32_f16 v[116:119], v[148:151], v[180:183], v[116:119]
	v_mfma_f32_16x16x32_f16 v[92:95], v[156:159], v[194:197], v[92:95]
	v_mfma_f32_16x16x32_f16 v[100:103], v[148:151], v[194:197], v[100:103]
	v_mfma_f32_16x16x32_f16 v[76:79], v[156:159], v[208:211], v[76:79]
	v_mfma_f32_16x16x32_f16 v[84:87], v[148:151], v[208:211], v[84:87]
	v_mfma_f32_16x16x32_f16 v[64:67], v[156:159], v[216:219], v[64:67]
	v_mfma_f32_16x16x32_f16 v[68:71], v[148:151], v[216:219], v[68:71]
	s_barrier
	s_add_i32 s91, s68, s61
	s_add_u32 s98, s48, s18
	s_addc_u32 s99, s49, s19
	s_mov_b32 m0, s91
	ds_read_b128 v[176:179], v193 offset:16384
	ds_read_b128 v[180:183], v193 offset:17408
	ds_read_b128 v[184:187], v193 offset:18432
	ds_read_b128 v[194:197], v193 offset:19456
	ds_read_b128 v[198:201], v193 offset:20480
	ds_read_b128 v[208:211], v193 offset:21504
	ds_read_b128 v[212:215], v193 offset:22528
	ds_read_b128 v[216:219], v193 offset:23552
	global_load_lds_dwordx4 v162, s[48:49]
	s_add_i32 m0, s91, 0x2000
	s_add_u32 s92, s48, 0x80000
	s_addc_u32 s93, s49, 0
	s_add_i32 s91, s69, s61
	global_load_lds_dwordx4 v166, s[48:49]
	s_mov_b32 m0, s91
	s_nop 0
	global_load_lds_dwordx4 v162, s[92:93]
	s_add_i32 m0, s91, 0x2000
	s_nop 0
	global_load_lds_dwordx4 v166, s[92:93]
	s_mov_b32 m0, s43
	s_add_u32 s100, s50, s18
	s_addc_u32 s101, s51, s19
	global_load_lds_dwordx4 v160, s[50:51]
	s_mov_b32 m0, s62
	s_nop 0
	global_load_lds_dwordx4 v164, s[50:51]
	s_waitcnt vmcnt(8)
	s_waitcnt lgkmcnt(0)
	s_barrier
	v_mfma_f32_16x16x32_f16 v[56:59], v[136:139], v[176:179], v[56:59]
	v_mfma_f32_16x16x32_f16 v[60:63], v[128:131], v[176:179], v[60:63]
	v_mfma_f32_16x16x32_f16 v[44:47], v[136:139], v[184:187], v[44:47]
	v_mfma_f32_16x16x32_f16 v[52:55], v[128:131], v[184:187], v[52:55]
	v_mfma_f32_16x16x32_f16 v[28:31], v[136:139], v[198:201], v[28:31]
	v_mfma_f32_16x16x32_f16 v[36:39], v[128:131], v[198:201], v[36:39]
	v_mfma_f32_16x16x32_f16 v[12:15], v[136:139], v[212:215], v[12:15]
	v_mfma_f32_16x16x32_f16 v[20:23], v[128:131], v[212:215], v[20:23]
	v_mfma_f32_16x16x32_f16 v[56:59], v[140:143], v[180:183], v[56:59]
	v_mfma_f32_16x16x32_f16 v[60:63], v[132:135], v[180:183], v[60:63]
	v_mfma_f32_16x16x32_f16 v[44:47], v[140:143], v[194:197], v[44:47]
	v_mfma_f32_16x16x32_f16 v[52:55], v[132:135], v[194:197], v[52:55]
	v_mfma_f32_16x16x32_f16 v[28:31], v[140:143], v[208:211], v[28:31]
	v_mfma_f32_16x16x32_f16 v[36:39], v[132:135], v[208:211], v[36:39]
	v_mfma_f32_16x16x32_f16 v[12:15], v[140:143], v[216:219], v[12:15]
	v_mfma_f32_16x16x32_f16 v[20:23], v[132:135], v[216:219], v[20:23]
	v_mfma_f32_16x16x32_f16 v[40:43], v[152:155], v[176:179], v[40:43]
	v_mfma_f32_16x16x32_f16 v[48:51], v[144:147], v[176:179], v[48:51]
	v_mfma_f32_16x16x32_f16 v[24:27], v[152:155], v[184:187], v[24:27]
	v_mfma_f32_16x16x32_f16 v[32:35], v[144:147], v[184:187], v[32:35]
	v_mfma_f32_16x16x32_f16 v[8:11], v[152:155], v[198:201], v[8:11]
	v_mfma_f32_16x16x32_f16 v[16:19], v[144:147], v[198:201], v[16:19]
	v_mfma_f32_16x16x32_f16 v[0:3], v[152:155], v[212:215], v[0:3]
	v_mfma_f32_16x16x32_f16 v[4:7], v[144:147], v[212:215], v[4:7]
	v_mfma_f32_16x16x32_f16 v[40:43], v[156:159], v[180:183], v[40:43]
	v_mfma_f32_16x16x32_f16 v[48:51], v[148:151], v[180:183], v[48:51]
	v_mfma_f32_16x16x32_f16 v[24:27], v[156:159], v[194:197], v[24:27]
	v_mfma_f32_16x16x32_f16 v[32:35], v[148:151], v[194:197], v[32:35]
	v_mfma_f32_16x16x32_f16 v[8:11], v[156:159], v[208:211], v[8:11]
	v_mfma_f32_16x16x32_f16 v[16:19], v[148:151], v[208:211], v[16:19]
	v_mfma_f32_16x16x32_f16 v[0:3], v[156:159], v[216:219], v[0:3]
	v_mfma_f32_16x16x32_f16 v[4:7], v[148:151], v[216:219], v[4:7]
	s_barrier
; #define PG8_STAGE(bufoff, gbase, voff) do { _Pragma("unroll") for (int _i = 0; _i < 2; ++_i) \
;         __builtin_amdgcn_global_load_lds((const unsigned*)((const char*)(gbase) + (voff)[_i]), (PG8_LAS unsigned*)(lds + (bufoff) + ldsw + _i * 8192), 16, 0, 0); } while (0)
; #define PG8_LDA(dst, b, h) do { _Pragma("unroll") for (int m = 0; m < 4; ++m) _Pragma("unroll") for (int k = 0; k < 2; ++k) dst[m][k] = *(const PG8_LAS bf16x8*)(lds + PG8_SA(b, h) + aoff + m * 2048 + k * 1024); } while (0)
; #define PG8_LDB(dst, b, h) do { _Pragma("unroll") for (int n = 0; n < 2; ++n) _Pragma("unroll") for (int k = 0; k < 2; ++k) dst[n][k] = *(const PG8_LAS bf16x8*)(lds + PG8_SB(b, h) + boff + n * 2048 + k * 1024); } while (0)
; #define PG8_MMA(ai, bj, At, Bt) do { __builtin_amdgcn_s_setprio(1); _Pragma("unroll") for (int m = 0; m < 4; ++m) _Pragma("unroll") for (int n = 0; n < 2; ++n) _Pragma("unroll") for (int k = 0; k < 2; ++k) \
;         acc[ai][bj][m][n] = __builtin_amdgcn_mfma_f32_16x16x32_f16(Bt[n][k], At[m][k], acc[ai][bj][m][n], 0, 0, 0); __builtin_amdgcn_s_setprio(0); } while (0)
; #define PG8_WAIT_V(n) asm volatile("s_waitcnt vmcnt(" #n ")" ::: "memory")
; #define PG8_WAIT_L(n) asm volatile("s_waitcnt lgkmcnt(" #n ")" ::: "memory")
; #define PG8_BAR __builtin_amdgcn_s_barrier()
; #define PG8_SCHED __builtin_amdgcn_sched_barrier(0)
; template <class Epi, class Sched, bool ALIGN_EPI = false, bool SP2 = false>
; __device__ __forceinline__ void gemm_phase(PG8_LAS unsigned char* lds, const Gemm g, const Sched& S, const Epi& E) {
;     ...
;         for (int t = 0; t < nt; t += 2) {
;     ...
;             PG8_LDB(B0, 1, 0); PG8_LDB(B1, 1, 1); PG8_SCHED; PG8_LDA(At, 1, 0); PG8_STAGE(PG8_SA(0, 1), a2 + hstep, voffA);
;             PG8_WAIT_V(8); PG8_WAIT_L(0); PG8_BAR; PG8_MMA(0, 0, At, B0); PG8_MMA(0, 1, At, B1); PG8_BAR; PG8_SCHED;
;             PG8_LDA(At, 1, 1); PG8_STAGE(PG8_SB(1, 0), b3, voffB); PG8_STAGE(PG8_SB(1, 1), b3 + hstep, voffB); PG8_STAGE(PG8_SA(1, 0), a3, voffA);
;             PG8_WAIT_V(8); PG8_WAIT_L(0); PG8_BAR; PG8_MMA(1, 0, At, B0); PG8_MMA(1, 1, At, B1); PG8_BAR; PG8_SCHED;
	s_add_i32 s91, 0, 0x18000
	s_add_i32 s92, 0, 0x1c000
	v_add_u32_e32 v140, s91, v189
	v_add_u32_e32 v156, s92, v189
	ds_read_b128 v[128:131], v140
	ds_read_b128 v[132:135], v140 offset:1024
	ds_read_b128 v[136:139], v140 offset:2048
	ds_read_b128 v[140:143], v140 offset:3072
	ds_read_b128 v[144:147], v156
	ds_read_b128 v[148:151], v156 offset:1024
	ds_read_b128 v[152:155], v156 offset:2048
	ds_read_b128 v[156:159], v156 offset:3072
	s_add_u32 s50, s50, 0x80000
	s_addc_u32 s51, s51, 0
	s_mov_b32 m0, s63
	ds_read_b128 v[176:179], v193 offset:32768
	ds_read_b128 v[180:183], v193 offset:33792
	ds_read_b128 v[184:187], v193 offset:34816
	ds_read_b128 v[194:197], v193 offset:35840
	ds_read_b128 v[198:201], v193 offset:36864
	ds_read_b128 v[208:211], v193 offset:37888
	ds_read_b128 v[212:215], v193 offset:38912
	ds_read_b128 v[216:219], v193 offset:39936
	global_load_lds_dwordx4 v160, s[50:51]
	s_mov_b32 m0, s64
	s_nop 0
	global_load_lds_dwordx4 v164, s[50:51]
	s_waitcnt vmcnt(8)
	s_waitcnt lgkmcnt(0)
	s_barrier
	v_mfma_f32_16x16x32_f16 v[120:123], v[136:139], v[176:179], v[120:123]
	v_mfma_f32_16x16x32_f16 v[124:127], v[128:131], v[176:179], v[124:127]
	v_mfma_f32_16x16x32_f16 v[104:107], v[136:139], v[184:187], v[104:107]
	v_mfma_f32_16x16x32_f16 v[112:115], v[128:131], v[184:187], v[112:115]
	v_mfma_f32_16x16x32_f16 v[88:91], v[136:139], v[198:201], v[88:91]
	v_mfma_f32_16x16x32_f16 v[96:99], v[128:131], v[198:201], v[96:99]
	v_mfma_f32_16x16x32_f16 v[72:75], v[136:139], v[212:215], v[72:75]
	v_mfma_f32_16x16x32_f16 v[80:83], v[128:131], v[212:215], v[80:83]
	v_mfma_f32_16x16x32_f16 v[120:123], v[140:143], v[180:183], v[120:123]
	v_mfma_f32_16x16x32_f16 v[124:127], v[132:135], v[180:183], v[124:127]
	v_mfma_f32_16x16x32_f16 v[104:107], v[140:143], v[194:197], v[104:107]
	v_mfma_f32_16x16x32_f16 v[112:115], v[132:135], v[194:197], v[112:115]
	v_mfma_f32_16x16x32_f16 v[88:91], v[140:143], v[208:211], v[88:91]
	v_mfma_f32_16x16x32_f16 v[96:99], v[132:135], v[208:211], v[96:99]
	v_mfma_f32_16x16x32_f16 v[72:75], v[140:143], v[216:219], v[72:75]
	v_mfma_f32_16x16x32_f16 v[80:83], v[132:135], v[216:219], v[80:83]
	v_mfma_f32_16x16x32_f16 v[108:111], v[152:155], v[176:179], v[108:111]
	v_mfma_f32_16x16x32_f16 v[116:119], v[144:147], v[176:179], v[116:119]
	v_mfma_f32_16x16x32_f16 v[92:95], v[152:155], v[184:187], v[92:95]
	v_mfma_f32_16x16x32_f16 v[100:103], v[144:147], v[184:187], v[100:103]
	v_mfma_f32_16x16x32_f16 v[76:79], v[152:155], v[198:201], v[76:79]
	v_mfma_f32_16x16x32_f16 v[84:87], v[144:147], v[198:201], v[84:87]
	v_mfma_f32_16x16x32_f16 v[64:67], v[152:155], v[212:215], v[64:67]
	v_mfma_f32_16x16x32_f16 v[68:71], v[144:147], v[212:215], v[68:71]
	v_mfma_f32_16x16x32_f16 v[108:111], v[156:159], v[180:183], v[108:111]
	v_mfma_f32_16x16x32_f16 v[116:119], v[148:151], v[180:183], v[116:119]
	v_mfma_f32_16x16x32_f16 v[92:95], v[156:159], v[194:197], v[92:95]
	v_mfma_f32_16x16x32_f16 v[100:103], v[148:151], v[194:197], v[100:103]
	v_mfma_f32_16x16x32_f16 v[76:79], v[156:159], v[208:211], v[76:79]
	v_mfma_f32_16x16x32_f16 v[84:87], v[148:151], v[208:211], v[84:87]
	v_mfma_f32_16x16x32_f16 v[64:67], v[156:159], v[216:219], v[64:67]
	v_mfma_f32_16x16x32_f16 v[68:71], v[148:151], v[216:219], v[68:71]
	s_barrier
	s_add_i32 s50, s91, s61
	s_mov_b32 m0, s50
	ds_read_b128 v[176:179], v193 offset:49152
	ds_read_b128 v[180:183], v193 offset:50176
	ds_read_b128 v[184:187], v193 offset:51200
	ds_read_b128 v[194:197], v193 offset:52224
	ds_read_b128 v[198:201], v193 offset:53248
	ds_read_b128 v[208:211], v193 offset:54272
	ds_read_b128 v[212:215], v193 offset:55296
	ds_read_b128 v[216:219], v193 offset:56320
	global_load_lds_dwordx4 v162, s[98:99]
	s_add_i32 m0, s50, 0x2000
	s_add_u32 s48, s48, 0x80080
	s_addc_u32 s49, s49, 0
	s_add_i32 s50, s92, s61
	global_load_lds_dwordx4 v166, s[98:99]
	s_mov_b32 m0, s50
	s_nop 0
	global_load_lds_dwordx4 v162, s[48:49]
	s_add_i32 m0, s50, 0x2000
	s_nop 0
	global_load_lds_dwordx4 v166, s[48:49]
	s_mov_b32 m0, s66
	s_nop 0
	global_load_lds_dwordx4 v160, s[100:101]
	s_mov_b32 m0, s67
	s_nop 0
	global_load_lds_dwordx4 v164, s[100:101]
	s_waitcnt vmcnt(8)
	s_waitcnt lgkmcnt(0)
	s_barrier
	v_mfma_f32_16x16x32_f16 v[56:59], v[136:139], v[176:179], v[56:59]
	v_mfma_f32_16x16x32_f16 v[60:63], v[128:131], v[176:179], v[60:63]
	v_mfma_f32_16x16x32_f16 v[44:47], v[136:139], v[184:187], v[44:47]
	v_mfma_f32_16x16x32_f16 v[52:55], v[128:131], v[184:187], v[52:55]
	v_mfma_f32_16x16x32_f16 v[28:31], v[136:139], v[198:201], v[28:31]
	v_mfma_f32_16x16x32_f16 v[36:39], v[128:131], v[198:201], v[36:39]
	v_mfma_f32_16x16x32_f16 v[12:15], v[136:139], v[212:215], v[12:15]
	v_mfma_f32_16x16x32_f16 v[20:23], v[128:131], v[212:215], v[20:23]
	v_mfma_f32_16x16x32_f16 v[56:59], v[140:143], v[180:183], v[56:59]
	v_mfma_f32_16x16x32_f16 v[60:63], v[132:135], v[180:183], v[60:63]
	v_mfma_f32_16x16x32_f16 v[44:47], v[140:143], v[194:197], v[44:47]
	v_mfma_f32_16x16x32_f16 v[52:55], v[132:135], v[194:197], v[52:55]
	v_mfma_f32_16x16x32_f16 v[28:31], v[140:143], v[208:211], v[28:31]
	v_mfma_f32_16x16x32_f16 v[36:39], v[132:135], v[208:211], v[36:39]
	v_mfma_f32_16x16x32_f16 v[12:15], v[140:143], v[216:219], v[12:15]
	v_mfma_f32_16x16x32_f16 v[20:23], v[132:135], v[216:219], v[20:23]
	v_mfma_f32_16x16x32_f16 v[40:43], v[152:155], v[176:179], v[40:43]
	v_mfma_f32_16x16x32_f16 v[48:51], v[144:147], v[176:179], v[48:51]
	v_mfma_f32_16x16x32_f16 v[24:27], v[152:155], v[184:187], v[24:27]
	v_mfma_f32_16x16x32_f16 v[32:35], v[144:147], v[184:187], v[32:35]
	v_mfma_f32_16x16x32_f16 v[8:11], v[152:155], v[198:201], v[8:11]
	v_mfma_f32_16x16x32_f16 v[16:19], v[144:147], v[198:201], v[16:19]
	v_mfma_f32_16x16x32_f16 v[0:3], v[152:155], v[212:215], v[0:3]
	v_mfma_f32_16x16x32_f16 v[4:7], v[144:147], v[212:215], v[4:7]
	v_mfma_f32_16x16x32_f16 v[40:43], v[156:159], v[180:183], v[40:43]
	v_mfma_f32_16x16x32_f16 v[48:51], v[148:151], v[180:183], v[48:51]
	v_mfma_f32_16x16x32_f16 v[24:27], v[156:159], v[194:197], v[24:27]
	v_mfma_f32_16x16x32_f16 v[32:35], v[148:151], v[194:197], v[32:35]
	v_mfma_f32_16x16x32_f16 v[8:11], v[156:159], v[208:211], v[8:11]
	v_mfma_f32_16x16x32_f16 v[16:19], v[148:151], v[208:211], v[16:19]
	v_mfma_f32_16x16x32_f16 v[0:3], v[156:159], v[216:219], v[0:3]
	v_mfma_f32_16x16x32_f16 v[4:7], v[148:151], v[216:219], v[4:7]
	s_barrier
	s_add_i32 s90, s90, 2
	s_add_u32 s88, s88, 0x100
	s_addc_u32 s89, s89, 0
	s_add_u32 s44, s44, 0x100
	s_addc_u32 s45, s45, 0
	s_cmp_gt_u32 s90, 29
	s_cbranch_scc0 .LBB0_747
	s_and_b64 vcc, exec, s[20:21]
	s_cbranch_vccz .LBB0_750
	s_barrier

; #define PG8_STAGE(bufoff, gbase, voff) do { _Pragma("unroll") for (int _i = 0; _i < 2; ++_i) \
;         __builtin_amdgcn_global_load_lds((const unsigned*)((const char*)(gbase) + (voff)[_i]), (PG8_LAS unsigned*)(lds + (bufoff) + ldsw + _i * 8192), 16, 0, 0); } while (0)
; #define PG8_LDA(dst, b, h) do { _Pragma("unroll") for (int m = 0; m < 4; ++m) _Pragma("unroll") for (int k = 0; k < 2; ++k) dst[m][k] = *(const PG8_LAS bf16x8*)(lds + PG8_SA(b, h) + aoff + m * 2048 + k * 1024); } while (0)
; #define PG8_LDB(dst, b, h) do { _Pragma("unroll") for (int n = 0; n < 2; ++n) _Pragma("unroll") for (int k = 0; k < 2; ++k) dst[n][k] = *(const PG8_LAS bf16x8*)(lds + PG8_SB(b, h) + boff + n * 2048 + k * 1024); } while (0)
; #define PG8_MMA(ai, bj, At, Bt) do { __builtin_amdgcn_s_setprio(1); _Pragma("unroll") for (int m = 0; m < 4; ++m) _Pragma("unroll") for (int n = 0; n < 2; ++n) _Pragma("unroll") for (int k = 0; k < 2; ++k) \
;         acc[ai][bj][m][n] = __builtin_amdgcn_mfma_f32_16x16x32_f16(Bt[n][k], At[m][k], acc[ai][bj][m][n], 0, 0, 0); __builtin_amdgcn_s_setprio(0); } while (0)
; #define PG8_WAIT_V(n) asm volatile("s_waitcnt vmcnt(" #n ")" ::: "memory")
; #define PG8_BAR __builtin_amdgcn_s_barrier()
; template <class Epi, class Sched, bool ALIGN_EPI = false, bool SP2 = false>
; __device__ __forceinline__ void gemm_phase(PG8_LAS unsigned char* lds, const Gemm g, const Sched& S, const Epi& E) {
;     ...
;         const char* nA = has_next ? (const char*)g.A + (size_t)nxt.pm * tstep : cA; const char* nB = has_next ? (const char*)g.Bt + (size_t)nxt.pn * tstep : cB;
;         for (int t = 0; t < nt; t += 2) {
;             const bool last = (t == nt - 2);
;             const char* a1 = cA + (size_t)(t + 1) * kstep;
;             const char* a2 = last ? nA : cA + (size_t)(t + 2) * kstep; const char* b2 = last ? nB : cB + (size_t)(t + 2) * kstep;
;     ...
;             PG8_LDB(B0, 0, 0); PG8_LDB(B1, 0, 1); PG8_SCHED; PG8_LDA(At, 0, 0); PG8_STAGE(PG8_SA(1, 1), a1 + hstep, voffA);
;             PG8_WAIT_V(8); PG8_WAIT_L(0); PG8_BAR; PG8_MMA(0, 0, At, B0); PG8_MMA(0, 1, At, B1); PG8_BAR; PG8_SCHED;
;             PG8_LDA(At, 0, 1); PG8_STAGE(PG8_SB(0, 0), b2, voffB); PG8_STAGE(PG8_SB(0, 1), b2 + hstep, voffB); PG8_STAGE(PG8_SA(0, 0), a2, voffA);
;             PG8_WAIT_V(8); PG8_WAIT_L(0); PG8_BAR; PG8_MMA(1, 0, At, B0); PG8_MMA(1, 1, At, B1); PG8_BAR; PG8_SCHED;
.LBB0_872:
	ds_read_b128 v[128:131], v187
	ds_read_b128 v[132:135], v187 offset:1024
	ds_read_b128 v[136:139], v187 offset:2048
	ds_read_b128 v[140:143], v187 offset:3072
	ds_read_b128 v[144:147], v188
	ds_read_b128 v[148:151], v188 offset:1024
	ds_read_b128 v[152:155], v188 offset:2048
	ds_read_b128 v[156:159], v188 offset:3072
	s_add_u32 s28, s26, 0xfffe0080
	s_addc_u32 s29, s27, -1
	s_cmp_eq_u32 s65, 4
	s_cselect_b32 s31, s21, s29
	s_cselect_b32 s30, s61, s28
	s_cselect_b32 s29, s19, s64
	s_cselect_b32 s28, s62, s63
	s_add_i32 m0, s39, 0xc000
	ds_read_b128 v[160:163], v189
	ds_read_b128 v[164:167], v189 offset:1024
	ds_read_b128 v[192:195], v189 offset:2048
	ds_read_b128 v[196:199], v189 offset:3072
	ds_read_b128 v[200:203], v189 offset:4096
	ds_read_b128 v[208:211], v189 offset:5120
	ds_read_b128 v[212:215], v189 offset:6144
	ds_read_b128 v[216:219], v189 offset:7168
	global_load_lds_dwordx4 v178, s[26:27]
	s_add_i32 m0, s39, 0xe000
	s_nop 0
	global_load_lds_dwordx4 v176, s[26:27]
	s_waitcnt vmcnt(8)
	s_waitcnt lgkmcnt(0)
	s_barrier
	v_mfma_f32_16x16x32_f16 v[120:123], v[136:139], v[160:163], v[120:123]
	v_mfma_f32_16x16x32_f16 v[124:127], v[128:131], v[160:163], v[124:127]
	v_mfma_f32_16x16x32_f16 v[104:107], v[136:139], v[192:195], v[104:107]
	v_mfma_f32_16x16x32_f16 v[108:111], v[128:131], v[192:195], v[108:111]
	v_mfma_f32_16x16x32_f16 v[88:91], v[136:139], v[200:203], v[88:91]
	v_mfma_f32_16x16x32_f16 v[92:95], v[128:131], v[200:203], v[92:95]
	v_mfma_f32_16x16x32_f16 v[72:75], v[136:139], v[212:215], v[72:75]
	v_mfma_f32_16x16x32_f16 v[76:79], v[128:131], v[212:215], v[76:79]
	v_mfma_f32_16x16x32_f16 v[120:123], v[140:143], v[164:167], v[120:123]
	v_mfma_f32_16x16x32_f16 v[124:127], v[132:135], v[164:167], v[124:127]
	v_mfma_f32_16x16x32_f16 v[104:107], v[140:143], v[196:199], v[104:107]
	v_mfma_f32_16x16x32_f16 v[108:111], v[132:135], v[196:199], v[108:111]
	v_mfma_f32_16x16x32_f16 v[88:91], v[140:143], v[208:211], v[88:91]
	v_mfma_f32_16x16x32_f16 v[92:95], v[132:135], v[208:211], v[92:95]
	v_mfma_f32_16x16x32_f16 v[72:75], v[140:143], v[216:219], v[72:75]
	v_mfma_f32_16x16x32_f16 v[76:79], v[132:135], v[216:219], v[76:79]
	v_mfma_f32_16x16x32_f16 v[112:115], v[152:155], v[160:163], v[112:115]
	v_mfma_f32_16x16x32_f16 v[116:119], v[144:147], v[160:163], v[116:119]
	v_mfma_f32_16x16x32_f16 v[96:99], v[152:155], v[192:195], v[96:99]
	v_mfma_f32_16x16x32_f16 v[100:103], v[144:147], v[192:195], v[100:103]
	v_mfma_f32_16x16x32_f16 v[80:83], v[152:155], v[200:203], v[80:83]
	v_mfma_f32_16x16x32_f16 v[84:87], v[144:147], v[200:203], v[84:87]
	v_mfma_f32_16x16x32_f16 v[64:67], v[152:155], v[212:215], v[64:67]
	v_mfma_f32_16x16x32_f16 v[68:71], v[144:147], v[212:215], v[68:71]
	v_mfma_f32_16x16x32_f16 v[112:115], v[156:159], v[164:167], v[112:115]
	v_mfma_f32_16x16x32_f16 v[116:119], v[148:151], v[164:167], v[116:119]
	v_mfma_f32_16x16x32_f16 v[96:99], v[156:159], v[196:199], v[96:99]
	v_mfma_f32_16x16x32_f16 v[100:103], v[148:151], v[196:199], v[100:103]
	v_mfma_f32_16x16x32_f16 v[80:83], v[156:159], v[208:211], v[80:83]
	v_mfma_f32_16x16x32_f16 v[84:87], v[148:151], v[208:211], v[84:87]
	v_mfma_f32_16x16x32_f16 v[64:67], v[156:159], v[216:219], v[64:67]
	v_mfma_f32_16x16x32_f16 v[68:71], v[148:151], v[216:219], v[68:71]
	s_barrier
	s_add_i32 s66, s49, s37
	s_add_u32 s98, s28, s14
	s_addc_u32 s99, s29, s15
	s_mov_b32 m0, s66
	ds_read_b128 v[160:163], v189 offset:16384
	ds_read_b128 v[164:167], v189 offset:17408
	ds_read_b128 v[192:195], v189 offset:18432
	ds_read_b128 v[196:199], v189 offset:19456
	ds_read_b128 v[200:203], v189 offset:20480
	ds_read_b128 v[208:211], v189 offset:21504
	ds_read_b128 v[212:215], v189 offset:22528
	ds_read_b128 v[216:219], v189 offset:23552
	global_load_lds_dwordx4 v170, s[28:29]
	s_add_i32 m0, s66, 0x2000
	s_add_u32 s66, s28, 0x20000
	s_addc_u32 s67, s29, 0
	s_add_i32 s68, s50, s37
	global_load_lds_dwordx4 v168, s[28:29]
	s_mov_b32 m0, s68
	s_nop 0
	global_load_lds_dwordx4 v170, s[66:67]
	s_add_i32 m0, s68, 0x2000
	s_nop 0
	global_load_lds_dwordx4 v168, s[66:67]
	s_mov_b32 m0, s39
	s_add_u32 s100, s30, s14
	s_addc_u32 s101, s31, s15
	global_load_lds_dwordx4 v170, s[30:31]
	s_mov_b32 m0, s40
	s_nop 0
	global_load_lds_dwordx4 v168, s[30:31]
	s_waitcnt vmcnt(8)
	s_waitcnt lgkmcnt(0)
	s_barrier
	v_mfma_f32_16x16x32_f16 v[56:59], v[136:139], v[160:163], v[56:59]
	v_mfma_f32_16x16x32_f16 v[60:63], v[128:131], v[160:163], v[60:63]
	v_mfma_f32_16x16x32_f16 v[40:43], v[136:139], v[192:195], v[40:43]
	v_mfma_f32_16x16x32_f16 v[44:47], v[128:131], v[192:195], v[44:47]
	v_mfma_f32_16x16x32_f16 v[24:27], v[136:139], v[200:203], v[24:27]
	v_mfma_f32_16x16x32_f16 v[28:31], v[128:131], v[200:203], v[28:31]
	v_mfma_f32_16x16x32_f16 v[8:11], v[136:139], v[212:215], v[8:11]
	v_mfma_f32_16x16x32_f16 v[12:15], v[128:131], v[212:215], v[12:15]
	v_mfma_f32_16x16x32_f16 v[56:59], v[140:143], v[164:167], v[56:59]
	v_mfma_f32_16x16x32_f16 v[60:63], v[132:135], v[164:167], v[60:63]
	v_mfma_f32_16x16x32_f16 v[40:43], v[140:143], v[196:199], v[40:43]
	v_mfma_f32_16x16x32_f16 v[44:47], v[132:135], v[196:199], v[44:47]
	v_mfma_f32_16x16x32_f16 v[24:27], v[140:143], v[208:211], v[24:27]
	v_mfma_f32_16x16x32_f16 v[28:31], v[132:135], v[208:211], v[28:31]
	v_mfma_f32_16x16x32_f16 v[8:11], v[140:143], v[216:219], v[8:11]
	v_mfma_f32_16x16x32_f16 v[12:15], v[132:135], v[216:219], v[12:15]
	v_mfma_f32_16x16x32_f16 v[48:51], v[152:155], v[160:163], v[48:51]
	v_mfma_f32_16x16x32_f16 v[52:55], v[144:147], v[160:163], v[52:55]
	v_mfma_f32_16x16x32_f16 v[32:35], v[152:155], v[192:195], v[32:35]
	v_mfma_f32_16x16x32_f16 v[36:39], v[144:147], v[192:195], v[36:39]
	v_mfma_f32_16x16x32_f16 v[16:19], v[152:155], v[200:203], v[16:19]
	v_mfma_f32_16x16x32_f16 v[20:23], v[144:147], v[200:203], v[20:23]
	v_mfma_f32_16x16x32_f16 v[0:3], v[152:155], v[212:215], v[0:3]
	v_mfma_f32_16x16x32_f16 v[4:7], v[144:147], v[212:215], v[4:7]
	v_mfma_f32_16x16x32_f16 v[48:51], v[156:159], v[164:167], v[48:51]
	v_mfma_f32_16x16x32_f16 v[52:55], v[148:151], v[164:167], v[52:55]
	v_mfma_f32_16x16x32_f16 v[32:35], v[156:159], v[196:199], v[32:35]
	v_mfma_f32_16x16x32_f16 v[36:39], v[148:151], v[196:199], v[36:39]
	v_mfma_f32_16x16x32_f16 v[16:19], v[156:159], v[208:211], v[16:19]
	v_mfma_f32_16x16x32_f16 v[20:23], v[148:151], v[208:211], v[20:23]
	v_mfma_f32_16x16x32_f16 v[0:3], v[156:159], v[216:219], v[0:3]
	v_mfma_f32_16x16x32_f16 v[4:7], v[148:151], v[216:219], v[4:7]
	s_barrier
; #define PG8_STAGE(bufoff, gbase, voff) do { _Pragma("unroll") for (int _i = 0; _i < 2; ++_i) \
;         __builtin_amdgcn_global_load_lds((const unsigned*)((const char*)(gbase) + (voff)[_i]), (PG8_LAS unsigned*)(lds + (bufoff) + ldsw + _i * 8192), 16, 0, 0); } while (0)
; #define PG8_LDA(dst, b, h) do { _Pragma("unroll") for (int m = 0; m < 4; ++m) _Pragma("unroll") for (int k = 0; k < 2; ++k) dst[m][k] = *(const PG8_LAS bf16x8*)(lds + PG8_SA(b, h) + aoff + m * 2048 + k * 1024); } while (0)
; #define PG8_LDB(dst, b, h) do { _Pragma("unroll") for (int n = 0; n < 2; ++n) _Pragma("unroll") for (int k = 0; k < 2; ++k) dst[n][k] = *(const PG8_LAS bf16x8*)(lds + PG8_SB(b, h) + boff + n * 2048 + k * 1024); } while (0)
; #define PG8_MMA(ai, bj, At, Bt) do { __builtin_amdgcn_s_setprio(1); _Pragma("unroll") for (int m = 0; m < 4; ++m) _Pragma("unroll") for (int n = 0; n < 2; ++n) _Pragma("unroll") for (int k = 0; k < 2; ++k) \
;         acc[ai][bj][m][n] = __builtin_amdgcn_mfma_f32_16x16x32_f16(Bt[n][k], At[m][k], acc[ai][bj][m][n], 0, 0, 0); __builtin_amdgcn_s_setprio(0); } while (0)
; #define PG8_WAIT_V(n) asm volatile("s_waitcnt vmcnt(" #n ")" ::: "memory")
; #define PG8_WAIT_L(n) asm volatile("s_waitcnt lgkmcnt(" #n ")" ::: "memory")
; #define PG8_BAR __builtin_amdgcn_s_barrier()
; #define PG8_SCHED __builtin_amdgcn_sched_barrier(0)
; template <class Epi, class Sched, bool ALIGN_EPI = false, bool SP2 = false>
; __device__ __forceinline__ void gemm_phase(PG8_LAS unsigned char* lds, const Gemm g, const Sched& S, const Epi& E) {
;     ...
;         for (int t = 0; t < nt; t += 2) {
;     ...
;             PG8_LDB(B0, 1, 0); PG8_LDB(B1, 1, 1); PG8_SCHED; PG8_LDA(At, 1, 0); PG8_STAGE(PG8_SA(0, 1), a2 + hstep, voffA);
;             PG8_WAIT_V(8); PG8_WAIT_L(0); PG8_BAR; PG8_MMA(0, 0, At, B0); PG8_MMA(0, 1, At, B1); PG8_BAR; PG8_SCHED;
;             PG8_LDA(At, 1, 1); PG8_STAGE(PG8_SB(1, 0), b3, voffB); PG8_STAGE(PG8_SB(1, 1), b3 + hstep, voffB); PG8_STAGE(PG8_SA(1, 0), a3, voffA);
;             PG8_WAIT_V(8); PG8_WAIT_L(0); PG8_BAR; PG8_MMA(1, 0, At, B0); PG8_MMA(1, 1, At, B1); PG8_BAR; PG8_SCHED;
	s_add_i32 s66, 0, 0x18000
	s_add_i32 s67, 0, 0x1c000
	v_add_u32_e32 v140, s66, v186
	v_add_u32_e32 v156, s67, v186
	ds_read_b128 v[128:131], v140
	ds_read_b128 v[132:135], v140 offset:1024
	ds_read_b128 v[136:139], v140 offset:2048
	ds_read_b128 v[140:143], v140 offset:3072
	ds_read_b128 v[144:147], v156
	ds_read_b128 v[148:151], v156 offset:1024
	ds_read_b128 v[152:155], v156 offset:2048
	ds_read_b128 v[156:159], v156 offset:3072
	s_add_u32 s30, s30, 0x20000
	s_addc_u32 s31, s31, 0
	s_mov_b32 m0, s41
	ds_read_b128 v[160:163], v189 offset:32768
	ds_read_b128 v[164:167], v189 offset:33792
	ds_read_b128 v[192:195], v189 offset:34816
	ds_read_b128 v[196:199], v189 offset:35840
	ds_read_b128 v[200:203], v189 offset:36864
	ds_read_b128 v[208:211], v189 offset:37888
	ds_read_b128 v[212:215], v189 offset:38912
	ds_read_b128 v[216:219], v189 offset:39936
	global_load_lds_dwordx4 v170, s[30:31]
	s_mov_b32 m0, s42
	s_nop 0
	global_load_lds_dwordx4 v168, s[30:31]
	s_waitcnt vmcnt(8)
	s_waitcnt lgkmcnt(0)
	s_barrier
	v_mfma_f32_16x16x32_f16 v[120:123], v[136:139], v[160:163], v[120:123]
	v_mfma_f32_16x16x32_f16 v[124:127], v[128:131], v[160:163], v[124:127]
	v_mfma_f32_16x16x32_f16 v[104:107], v[136:139], v[192:195], v[104:107]
	v_mfma_f32_16x16x32_f16 v[108:111], v[128:131], v[192:195], v[108:111]
	v_mfma_f32_16x16x32_f16 v[88:91], v[136:139], v[200:203], v[88:91]
	v_mfma_f32_16x16x32_f16 v[92:95], v[128:131], v[200:203], v[92:95]
	v_mfma_f32_16x16x32_f16 v[72:75], v[136:139], v[212:215], v[72:75]
	v_mfma_f32_16x16x32_f16 v[76:79], v[128:131], v[212:215], v[76:79]
	v_mfma_f32_16x16x32_f16 v[120:123], v[140:143], v[164:167], v[120:123]
	v_mfma_f32_16x16x32_f16 v[124:127], v[132:135], v[164:167], v[124:127]
	v_mfma_f32_16x16x32_f16 v[104:107], v[140:143], v[196:199], v[104:107]
	v_mfma_f32_16x16x32_f16 v[108:111], v[132:135], v[196:199], v[108:111]
	v_mfma_f32_16x16x32_f16 v[88:91], v[140:143], v[208:211], v[88:91]
	v_mfma_f32_16x16x32_f16 v[92:95], v[132:135], v[208:211], v[92:95]
	v_mfma_f32_16x16x32_f16 v[72:75], v[140:143], v[216:219], v[72:75]
	v_mfma_f32_16x16x32_f16 v[76:79], v[132:135], v[216:219], v[76:79]
	v_mfma_f32_16x16x32_f16 v[112:115], v[152:155], v[160:163], v[112:115]
	v_mfma_f32_16x16x32_f16 v[116:119], v[144:147], v[160:163], v[116:119]
	v_mfma_f32_16x16x32_f16 v[96:99], v[152:155], v[192:195], v[96:99]
	v_mfma_f32_16x16x32_f16 v[100:103], v[144:147], v[192:195], v[100:103]
	v_mfma_f32_16x16x32_f16 v[80:83], v[152:155], v[200:203], v[80:83]
	v_mfma_f32_16x16x32_f16 v[84:87], v[144:147], v[200:203], v[84:87]
	v_mfma_f32_16x16x32_f16 v[64:67], v[152:155], v[212:215], v[64:67]
	v_mfma_f32_16x16x32_f16 v[68:71], v[144:147], v[212:215], v[68:71]
	v_mfma_f32_16x16x32_f16 v[112:115], v[156:159], v[164:167], v[112:115]
	v_mfma_f32_16x16x32_f16 v[116:119], v[148:151], v[164:167], v[116:119]
	v_mfma_f32_16x16x32_f16 v[96:99], v[156:159], v[196:199], v[96:99]
	v_mfma_f32_16x16x32_f16 v[100:103], v[148:151], v[196:199], v[100:103]
	v_mfma_f32_16x16x32_f16 v[80:83], v[156:159], v[208:211], v[80:83]
	v_mfma_f32_16x16x32_f16 v[84:87], v[148:151], v[208:211], v[84:87]
	v_mfma_f32_16x16x32_f16 v[64:67], v[156:159], v[216:219], v[64:67]
	v_mfma_f32_16x16x32_f16 v[68:71], v[148:151], v[216:219], v[68:71]
	s_barrier
	s_add_i32 s30, s66, s37
	s_mov_b32 m0, s30
	ds_read_b128 v[160:163], v189 offset:49152
	ds_read_b128 v[164:167], v189 offset:50176
	ds_read_b128 v[192:195], v189 offset:51200
	ds_read_b128 v[196:199], v189 offset:52224
	ds_read_b128 v[200:203], v189 offset:53248
	ds_read_b128 v[208:211], v189 offset:54272
	ds_read_b128 v[212:215], v189 offset:55296
	ds_read_b128 v[216:219], v189 offset:56320
	global_load_lds_dwordx4 v170, s[98:99]
	s_add_i32 m0, s30, 0x2000
	s_add_u32 s28, s28, 0x20080
	s_addc_u32 s29, s29, 0
	s_add_i32 s30, s67, s37
	global_load_lds_dwordx4 v168, s[98:99]
	s_mov_b32 m0, s30
	s_nop 0
	global_load_lds_dwordx4 v170, s[28:29]
	s_add_i32 m0, s30, 0x2000
	s_nop 0
	global_load_lds_dwordx4 v168, s[28:29]
	s_mov_b32 m0, s45
	s_nop 0
	global_load_lds_dwordx4 v170, s[100:101]
	s_mov_b32 m0, s48
	s_nop 0
	global_load_lds_dwordx4 v168, s[100:101]
	s_waitcnt vmcnt(8)
	s_waitcnt lgkmcnt(0)
	s_barrier
	v_mfma_f32_16x16x32_f16 v[56:59], v[136:139], v[160:163], v[56:59]
	v_mfma_f32_16x16x32_f16 v[60:63], v[128:131], v[160:163], v[60:63]
	v_mfma_f32_16x16x32_f16 v[40:43], v[136:139], v[192:195], v[40:43]
	v_mfma_f32_16x16x32_f16 v[44:47], v[128:131], v[192:195], v[44:47]
	v_mfma_f32_16x16x32_f16 v[24:27], v[136:139], v[200:203], v[24:27]
	v_mfma_f32_16x16x32_f16 v[28:31], v[128:131], v[200:203], v[28:31]
	v_mfma_f32_16x16x32_f16 v[8:11], v[136:139], v[212:215], v[8:11]
	v_mfma_f32_16x16x32_f16 v[12:15], v[128:131], v[212:215], v[12:15]
	v_mfma_f32_16x16x32_f16 v[56:59], v[140:143], v[164:167], v[56:59]
	v_mfma_f32_16x16x32_f16 v[60:63], v[132:135], v[164:167], v[60:63]
	v_mfma_f32_16x16x32_f16 v[40:43], v[140:143], v[196:199], v[40:43]
	v_mfma_f32_16x16x32_f16 v[44:47], v[132:135], v[196:199], v[44:47]
	v_mfma_f32_16x16x32_f16 v[24:27], v[140:143], v[208:211], v[24:27]
	v_mfma_f32_16x16x32_f16 v[28:31], v[132:135], v[208:211], v[28:31]
	v_mfma_f32_16x16x32_f16 v[8:11], v[140:143], v[216:219], v[8:11]
	v_mfma_f32_16x16x32_f16 v[12:15], v[132:135], v[216:219], v[12:15]
	v_mfma_f32_16x16x32_f16 v[48:51], v[152:155], v[160:163], v[48:51]
	v_mfma_f32_16x16x32_f16 v[52:55], v[144:147], v[160:163], v[52:55]
	v_mfma_f32_16x16x32_f16 v[32:35], v[152:155], v[192:195], v[32:35]
	v_mfma_f32_16x16x32_f16 v[36:39], v[144:147], v[192:195], v[36:39]
	v_mfma_f32_16x16x32_f16 v[16:19], v[152:155], v[200:203], v[16:19]
	v_mfma_f32_16x16x32_f16 v[20:23], v[144:147], v[200:203], v[20:23]
	v_mfma_f32_16x16x32_f16 v[0:3], v[152:155], v[212:215], v[0:3]
	v_mfma_f32_16x16x32_f16 v[4:7], v[144:147], v[212:215], v[4:7]
	v_mfma_f32_16x16x32_f16 v[48:51], v[156:159], v[164:167], v[48:51]
	v_mfma_f32_16x16x32_f16 v[52:55], v[148:151], v[164:167], v[52:55]
	v_mfma_f32_16x16x32_f16 v[32:35], v[156:159], v[196:199], v[32:35]
	v_mfma_f32_16x16x32_f16 v[36:39], v[148:151], v[196:199], v[36:39]
	v_mfma_f32_16x16x32_f16 v[16:19], v[156:159], v[208:211], v[16:19]
	v_mfma_f32_16x16x32_f16 v[20:23], v[148:151], v[208:211], v[20:23]
	v_mfma_f32_16x16x32_f16 v[0:3], v[156:159], v[216:219], v[0:3]
	v_mfma_f32_16x16x32_f16 v[4:7], v[148:151], v[216:219], v[4:7]
	s_barrier
	s_add_i32 s65, s65, 2
	s_add_u32 s63, s63, 0x100
	s_addc_u32 s64, s64, 0
	s_add_u32 s26, s26, 0x100
	s_addc_u32 s27, s27, 0
	s_cmp_gt_u32 s65, 5
	s_cbranch_scc0 .LBB0_872
	s_and_b64 vcc, exec, s[16:17]
	s_cbranch_vccz .LBB0_875
	s_barrier

; #define PG8_STAGE(bufoff, gbase, voff) do { _Pragma("unroll") for (int _i = 0; _i < 2; ++_i) \
;         __builtin_amdgcn_global_load_lds((const unsigned*)((const char*)(gbase) + (voff)[_i]), (PG8_LAS unsigned*)(lds + (bufoff) + ldsw + _i * 8192), 16, 0, 0); } while (0)
; #define PG8_LDA(dst, b, h) do { _Pragma("unroll") for (int m = 0; m < 4; ++m) _Pragma("unroll") for (int k = 0; k < 2; ++k) dst[m][k] = *(const PG8_LAS bf16x8*)(lds + PG8_SA(b, h) + aoff + m * 2048 + k * 1024); } while (0)
; #define PG8_LDB(dst, b, h) do { _Pragma("unroll") for (int n = 0; n < 2; ++n) _Pragma("unroll") for (int k = 0; k < 2; ++k) dst[n][k] = *(const PG8_LAS bf16x8*)(lds + PG8_SB(b, h) + boff + n * 2048 + k * 1024); } while (0)
; #define PG8_MMA(ai, bj, At, Bt) do { __builtin_amdgcn_s_setprio(1); _Pragma("unroll") for (int m = 0; m < 4; ++m) _Pragma("unroll") for (int n = 0; n < 2; ++n) _Pragma("unroll") for (int k = 0; k < 2; ++k) \
;         acc[ai][bj][m][n] = __builtin_amdgcn_mfma_f32_16x16x32_f16(Bt[n][k], At[m][k], acc[ai][bj][m][n], 0, 0, 0); __builtin_amdgcn_s_setprio(0); } while (0)
; #define PG8_WAIT_V(n) asm volatile("s_waitcnt vmcnt(" #n ")" ::: "memory")
; #define PG8_BAR __builtin_amdgcn_s_barrier()
; template <class Epi, class Sched, bool ALIGN_EPI = false, bool SP2 = false>
; __device__ __forceinline__ void gemm_phase(PG8_LAS unsigned char* lds, const Gemm g, const Sched& S, const Epi& E) {
;     ...
;         const char* nA = has_next ? (const char*)g.A + (size_t)nxt.pm * tstep : cA; const char* nB = has_next ? (const char*)g.Bt + (size_t)nxt.pn * tstep : cB;
;         for (int t = 0; t < nt; t += 2) {
;             const bool last = (t == nt - 2);
;             const char* a1 = cA + (size_t)(t + 1) * kstep;
;             const char* a2 = last ? nA : cA + (size_t)(t + 2) * kstep; const char* b2 = last ? nB : cB + (size_t)(t + 2) * kstep;
;     ...
;             PG8_LDB(B0, 0, 0); PG8_LDB(B1, 0, 1); PG8_SCHED; PG8_LDA(At, 0, 0); PG8_STAGE(PG8_SA(1, 1), a1 + hstep, voffA);
;             PG8_WAIT_V(8); PG8_WAIT_L(0); PG8_BAR; PG8_MMA(0, 0, At, B0); PG8_MMA(0, 1, At, B1); PG8_BAR; PG8_SCHED;
;             PG8_LDA(At, 0, 1); PG8_STAGE(PG8_SB(0, 0), b2, voffB); PG8_STAGE(PG8_SB(0, 1), b2 + hstep, voffB); PG8_STAGE(PG8_SA(0, 0), a2, voffA);
;             PG8_WAIT_V(8); PG8_WAIT_L(0); PG8_BAR; PG8_MMA(1, 0, At, B0); PG8_MMA(1, 1, At, B1); PG8_BAR; PG8_SCHED;
.LBB0_1075:
	ds_read_b128 v[128:131], v211
	ds_read_b128 v[132:135], v211 offset:1024
	ds_read_b128 v[136:139], v211 offset:2048
	ds_read_b128 v[140:143], v211 offset:3072
	ds_read_b128 v[144:147], v212
	ds_read_b128 v[148:151], v212 offset:1024
	ds_read_b128 v[152:155], v212 offset:2048
	ds_read_b128 v[156:159], v212 offset:3072
	s_add_u32 s42, s40, 0xfff80080
	s_addc_u32 s43, s41, -1
	s_cmp_eq_u32 s70, 28
	s_cselect_b32 s45, s29, s43
	s_cselect_b32 s44, s37, s42
	s_cselect_b32 s43, s27, s69
	s_cselect_b32 s42, s67, s68
	s_add_i32 m0, s39, 0xc000
	ds_read_b128 v[160:163], v213
	ds_read_b128 v[164:167], v213 offset:1024
	ds_read_b128 v[184:187], v213 offset:2048
	ds_read_b128 v[188:191], v213 offset:3072
	ds_read_b128 v[192:195], v213 offset:4096
	ds_read_b128 v[196:199], v213 offset:5120
	ds_read_b128 v[200:203], v213 offset:6144
	ds_read_b128 v[214:217], v213 offset:7168
	global_load_lds_dwordx4 v178, s[40:41]
	s_add_i32 m0, s39, 0xe000
	s_nop 0
	global_load_lds_dwordx4 v176, s[40:41]
	s_waitcnt vmcnt(8)
	s_waitcnt lgkmcnt(0)
	s_barrier
	v_mfma_f32_16x16x32_f16 v[120:123], v[136:139], v[160:163], v[120:123]
	v_mfma_f32_16x16x32_f16 v[124:127], v[128:131], v[160:163], v[124:127]
	v_mfma_f32_16x16x32_f16 v[104:107], v[136:139], v[184:187], v[104:107]
	v_mfma_f32_16x16x32_f16 v[108:111], v[128:131], v[184:187], v[108:111]
	v_mfma_f32_16x16x32_f16 v[88:91], v[136:139], v[192:195], v[88:91]
	v_mfma_f32_16x16x32_f16 v[92:95], v[128:131], v[192:195], v[92:95]
	v_mfma_f32_16x16x32_f16 v[72:75], v[136:139], v[200:203], v[72:75]
	v_mfma_f32_16x16x32_f16 v[76:79], v[128:131], v[200:203], v[76:79]
	v_mfma_f32_16x16x32_f16 v[120:123], v[140:143], v[164:167], v[120:123]
	v_mfma_f32_16x16x32_f16 v[124:127], v[132:135], v[164:167], v[124:127]
	v_mfma_f32_16x16x32_f16 v[104:107], v[140:143], v[188:191], v[104:107]
	v_mfma_f32_16x16x32_f16 v[108:111], v[132:135], v[188:191], v[108:111]
	v_mfma_f32_16x16x32_f16 v[88:91], v[140:143], v[196:199], v[88:91]
	v_mfma_f32_16x16x32_f16 v[92:95], v[132:135], v[196:199], v[92:95]
	v_mfma_f32_16x16x32_f16 v[72:75], v[140:143], v[214:217], v[72:75]
	v_mfma_f32_16x16x32_f16 v[76:79], v[132:135], v[214:217], v[76:79]
	v_mfma_f32_16x16x32_f16 v[112:115], v[152:155], v[160:163], v[112:115]
	v_mfma_f32_16x16x32_f16 v[116:119], v[144:147], v[160:163], v[116:119]
	v_mfma_f32_16x16x32_f16 v[96:99], v[152:155], v[184:187], v[96:99]
	v_mfma_f32_16x16x32_f16 v[100:103], v[144:147], v[184:187], v[100:103]
	v_mfma_f32_16x16x32_f16 v[80:83], v[152:155], v[192:195], v[80:83]
	v_mfma_f32_16x16x32_f16 v[84:87], v[144:147], v[192:195], v[84:87]
	v_mfma_f32_16x16x32_f16 v[64:67], v[152:155], v[200:203], v[64:67]
	v_mfma_f32_16x16x32_f16 v[68:71], v[144:147], v[200:203], v[68:71]
	v_mfma_f32_16x16x32_f16 v[112:115], v[156:159], v[164:167], v[112:115]
	v_mfma_f32_16x16x32_f16 v[116:119], v[148:151], v[164:167], v[116:119]
	v_mfma_f32_16x16x32_f16 v[96:99], v[156:159], v[188:191], v[96:99]
	v_mfma_f32_16x16x32_f16 v[100:103], v[148:151], v[188:191], v[100:103]
	v_mfma_f32_16x16x32_f16 v[80:83], v[156:159], v[196:199], v[80:83]
	v_mfma_f32_16x16x32_f16 v[84:87], v[148:151], v[196:199], v[84:87]
	v_mfma_f32_16x16x32_f16 v[64:67], v[156:159], v[214:217], v[64:67]
	v_mfma_f32_16x16x32_f16 v[68:71], v[148:151], v[214:217], v[68:71]
	s_barrier
	s_add_i32 s71, s64, s48
	s_add_u32 s98, s42, s18
	s_addc_u32 s99, s43, s19
	s_mov_b32 m0, s71
	ds_read_b128 v[160:163], v213 offset:16384
	ds_read_b128 v[164:167], v213 offset:17408
	ds_read_b128 v[184:187], v213 offset:18432
	ds_read_b128 v[188:191], v213 offset:19456
	ds_read_b128 v[192:195], v213 offset:20480
	ds_read_b128 v[196:199], v213 offset:21504
	ds_read_b128 v[200:203], v213 offset:22528
	ds_read_b128 v[214:217], v213 offset:23552
	global_load_lds_dwordx4 v170, s[42:43]
	s_add_i32 m0, s71, 0x2000
	s_add_u32 s72, s42, 0x80000
	s_addc_u32 s73, s43, 0
	s_add_i32 s71, s65, s48
	global_load_lds_dwordx4 v174, s[42:43]
	s_mov_b32 m0, s71
	s_nop 0
	global_load_lds_dwordx4 v170, s[72:73]
	s_add_i32 m0, s71, 0x2000
	s_nop 0
	global_load_lds_dwordx4 v174, s[72:73]
	s_mov_b32 m0, s39
	s_add_u32 s100, s44, s18
	s_addc_u32 s101, s45, s19
	global_load_lds_dwordx4 v168, s[44:45]
	s_mov_b32 m0, s49
	s_nop 0
	global_load_lds_dwordx4 v172, s[44:45]
	s_waitcnt vmcnt(8)
	s_waitcnt lgkmcnt(0)
	s_barrier
	v_mfma_f32_16x16x32_f16 v[56:59], v[136:139], v[160:163], v[56:59]
	v_mfma_f32_16x16x32_f16 v[60:63], v[128:131], v[160:163], v[60:63]
	v_mfma_f32_16x16x32_f16 v[40:43], v[136:139], v[184:187], v[40:43]
	v_mfma_f32_16x16x32_f16 v[44:47], v[128:131], v[184:187], v[44:47]
	v_mfma_f32_16x16x32_f16 v[24:27], v[136:139], v[192:195], v[24:27]
	v_mfma_f32_16x16x32_f16 v[28:31], v[128:131], v[192:195], v[28:31]
	v_mfma_f32_16x16x32_f16 v[8:11], v[136:139], v[200:203], v[8:11]
	v_mfma_f32_16x16x32_f16 v[12:15], v[128:131], v[200:203], v[12:15]
	v_mfma_f32_16x16x32_f16 v[56:59], v[140:143], v[164:167], v[56:59]
	v_mfma_f32_16x16x32_f16 v[60:63], v[132:135], v[164:167], v[60:63]
	v_mfma_f32_16x16x32_f16 v[40:43], v[140:143], v[188:191], v[40:43]
	v_mfma_f32_16x16x32_f16 v[44:47], v[132:135], v[188:191], v[44:47]
	v_mfma_f32_16x16x32_f16 v[24:27], v[140:143], v[196:199], v[24:27]
	v_mfma_f32_16x16x32_f16 v[28:31], v[132:135], v[196:199], v[28:31]
	v_mfma_f32_16x16x32_f16 v[8:11], v[140:143], v[214:217], v[8:11]
	v_mfma_f32_16x16x32_f16 v[12:15], v[132:135], v[214:217], v[12:15]
	v_mfma_f32_16x16x32_f16 v[48:51], v[152:155], v[160:163], v[48:51]
	v_mfma_f32_16x16x32_f16 v[52:55], v[144:147], v[160:163], v[52:55]
	v_mfma_f32_16x16x32_f16 v[32:35], v[152:155], v[184:187], v[32:35]
	v_mfma_f32_16x16x32_f16 v[36:39], v[144:147], v[184:187], v[36:39]
	v_mfma_f32_16x16x32_f16 v[16:19], v[152:155], v[192:195], v[16:19]
	v_mfma_f32_16x16x32_f16 v[20:23], v[144:147], v[192:195], v[20:23]
	v_mfma_f32_16x16x32_f16 v[0:3], v[152:155], v[200:203], v[0:3]
	v_mfma_f32_16x16x32_f16 v[4:7], v[144:147], v[200:203], v[4:7]
	v_mfma_f32_16x16x32_f16 v[48:51], v[156:159], v[164:167], v[48:51]
	v_mfma_f32_16x16x32_f16 v[52:55], v[148:151], v[164:167], v[52:55]
	v_mfma_f32_16x16x32_f16 v[32:35], v[156:159], v[188:191], v[32:35]
	v_mfma_f32_16x16x32_f16 v[36:39], v[148:151], v[188:191], v[36:39]
	v_mfma_f32_16x16x32_f16 v[16:19], v[156:159], v[196:199], v[16:19]
	v_mfma_f32_16x16x32_f16 v[20:23], v[148:151], v[196:199], v[20:23]
	v_mfma_f32_16x16x32_f16 v[0:3], v[156:159], v[214:217], v[0:3]
	v_mfma_f32_16x16x32_f16 v[4:7], v[148:151], v[214:217], v[4:7]
	s_barrier
; #define PG8_STAGE(bufoff, gbase, voff) do { _Pragma("unroll") for (int _i = 0; _i < 2; ++_i) \
;         __builtin_amdgcn_global_load_lds((const unsigned*)((const char*)(gbase) + (voff)[_i]), (PG8_LAS unsigned*)(lds + (bufoff) + ldsw + _i * 8192), 16, 0, 0); } while (0)
; #define PG8_LDA(dst, b, h) do { _Pragma("unroll") for (int m = 0; m < 4; ++m) _Pragma("unroll") for (int k = 0; k < 2; ++k) dst[m][k] = *(const PG8_LAS bf16x8*)(lds + PG8_SA(b, h) + aoff + m * 2048 + k * 1024); } while (0)
; #define PG8_LDB(dst, b, h) do { _Pragma("unroll") for (int n = 0; n < 2; ++n) _Pragma("unroll") for (int k = 0; k < 2; ++k) dst[n][k] = *(const PG8_LAS bf16x8*)(lds + PG8_SB(b, h) + boff + n * 2048 + k * 1024); } while (0)
; #define PG8_MMA(ai, bj, At, Bt) do { __builtin_amdgcn_s_setprio(1); _Pragma("unroll") for (int m = 0; m < 4; ++m) _Pragma("unroll") for (int n = 0; n < 2; ++n) _Pragma("unroll") for (int k = 0; k < 2; ++k) \
;         acc[ai][bj][m][n] = __builtin_amdgcn_mfma_f32_16x16x32_f16(Bt[n][k], At[m][k], acc[ai][bj][m][n], 0, 0, 0); __builtin_amdgcn_s_setprio(0); } while (0)
; #define PG8_WAIT_V(n) asm volatile("s_waitcnt vmcnt(" #n ")" ::: "memory")
; #define PG8_WAIT_L(n) asm volatile("s_waitcnt lgkmcnt(" #n ")" ::: "memory")
; #define PG8_BAR __builtin_amdgcn_s_barrier()
; #define PG8_SCHED __builtin_amdgcn_sched_barrier(0)
; template <class Epi, class Sched, bool ALIGN_EPI = false, bool SP2 = false>
; __device__ __forceinline__ void gemm_phase(PG8_LAS unsigned char* lds, const Gemm g, const Sched& S, const Epi& E) {
;     ...
;         for (int t = 0; t < nt; t += 2) {
;     ...
;             PG8_LDB(B0, 1, 0); PG8_LDB(B1, 1, 1); PG8_SCHED; PG8_LDA(At, 1, 0); PG8_STAGE(PG8_SA(0, 1), a2 + hstep, voffA);
;             PG8_WAIT_V(8); PG8_WAIT_L(0); PG8_BAR; PG8_MMA(0, 0, At, B0); PG8_MMA(0, 1, At, B1); PG8_BAR; PG8_SCHED;
;             PG8_LDA(At, 1, 1); PG8_STAGE(PG8_SB(1, 0), b3, voffB); PG8_STAGE(PG8_SB(1, 1), b3 + hstep, voffB); PG8_STAGE(PG8_SA(1, 0), a3, voffA);
;             PG8_WAIT_V(8); PG8_WAIT_L(0); PG8_BAR; PG8_MMA(1, 0, At, B0); PG8_MMA(1, 1, At, B1); PG8_BAR; PG8_SCHED;
	s_add_i32 s71, 0, 0x18000
	s_add_i32 s72, 0, 0x1c000
	v_add_u32_e32 v140, s71, v209
	v_add_u32_e32 v156, s72, v209
	ds_read_b128 v[128:131], v140
	ds_read_b128 v[132:135], v140 offset:1024
	ds_read_b128 v[136:139], v140 offset:2048
	ds_read_b128 v[140:143], v140 offset:3072
	ds_read_b128 v[144:147], v156
	ds_read_b128 v[148:151], v156 offset:1024
	ds_read_b128 v[152:155], v156 offset:2048
	ds_read_b128 v[156:159], v156 offset:3072
	s_add_u32 s44, s44, 0x80000
	s_addc_u32 s45, s45, 0
	s_mov_b32 m0, s50
	ds_read_b128 v[160:163], v213 offset:32768
	ds_read_b128 v[164:167], v213 offset:33792
	ds_read_b128 v[184:187], v213 offset:34816
	ds_read_b128 v[188:191], v213 offset:35840
	ds_read_b128 v[192:195], v213 offset:36864
	ds_read_b128 v[196:199], v213 offset:37888
	ds_read_b128 v[200:203], v213 offset:38912
	ds_read_b128 v[214:217], v213 offset:39936
	global_load_lds_dwordx4 v168, s[44:45]
	s_mov_b32 m0, s51
	s_nop 0
	global_load_lds_dwordx4 v172, s[44:45]
	s_waitcnt vmcnt(8)
	s_waitcnt lgkmcnt(0)
	s_barrier
	v_mfma_f32_16x16x32_f16 v[120:123], v[136:139], v[160:163], v[120:123]
	v_mfma_f32_16x16x32_f16 v[124:127], v[128:131], v[160:163], v[124:127]
	v_mfma_f32_16x16x32_f16 v[104:107], v[136:139], v[184:187], v[104:107]
	v_mfma_f32_16x16x32_f16 v[108:111], v[128:131], v[184:187], v[108:111]
	v_mfma_f32_16x16x32_f16 v[88:91], v[136:139], v[192:195], v[88:91]
	v_mfma_f32_16x16x32_f16 v[92:95], v[128:131], v[192:195], v[92:95]
	v_mfma_f32_16x16x32_f16 v[72:75], v[136:139], v[200:203], v[72:75]
	v_mfma_f32_16x16x32_f16 v[76:79], v[128:131], v[200:203], v[76:79]
	v_mfma_f32_16x16x32_f16 v[120:123], v[140:143], v[164:167], v[120:123]
	v_mfma_f32_16x16x32_f16 v[124:127], v[132:135], v[164:167], v[124:127]
	v_mfma_f32_16x16x32_f16 v[104:107], v[140:143], v[188:191], v[104:107]
	v_mfma_f32_16x16x32_f16 v[108:111], v[132:135], v[188:191], v[108:111]
	v_mfma_f32_16x16x32_f16 v[88:91], v[140:143], v[196:199], v[88:91]
	v_mfma_f32_16x16x32_f16 v[92:95], v[132:135], v[196:199], v[92:95]
	v_mfma_f32_16x16x32_f16 v[72:75], v[140:143], v[214:217], v[72:75]
	v_mfma_f32_16x16x32_f16 v[76:79], v[132:135], v[214:217], v[76:79]
	v_mfma_f32_16x16x32_f16 v[112:115], v[152:155], v[160:163], v[112:115]
	v_mfma_f32_16x16x32_f16 v[116:119], v[144:147], v[160:163], v[116:119]
	v_mfma_f32_16x16x32_f16 v[96:99], v[152:155], v[184:187], v[96:99]
	v_mfma_f32_16x16x32_f16 v[100:103], v[144:147], v[184:187], v[100:103]
	v_mfma_f32_16x16x32_f16 v[80:83], v[152:155], v[192:195], v[80:83]
	v_mfma_f32_16x16x32_f16 v[84:87], v[144:147], v[192:195], v[84:87]
	v_mfma_f32_16x16x32_f16 v[64:67], v[152:155], v[200:203], v[64:67]
	v_mfma_f32_16x16x32_f16 v[68:71], v[144:147], v[200:203], v[68:71]
	v_mfma_f32_16x16x32_f16 v[112:115], v[156:159], v[164:167], v[112:115]
	v_mfma_f32_16x16x32_f16 v[116:119], v[148:151], v[164:167], v[116:119]
	v_mfma_f32_16x16x32_f16 v[96:99], v[156:159], v[188:191], v[96:99]
	v_mfma_f32_16x16x32_f16 v[100:103], v[148:151], v[188:191], v[100:103]
	v_mfma_f32_16x16x32_f16 v[80:83], v[156:159], v[196:199], v[80:83]
	v_mfma_f32_16x16x32_f16 v[84:87], v[148:151], v[196:199], v[84:87]
	v_mfma_f32_16x16x32_f16 v[64:67], v[156:159], v[214:217], v[64:67]
	v_mfma_f32_16x16x32_f16 v[68:71], v[148:151], v[214:217], v[68:71]
	s_barrier
	s_add_i32 s44, s71, s48
	s_mov_b32 m0, s44
	ds_read_b128 v[160:163], v213 offset:49152
	ds_read_b128 v[164:167], v213 offset:50176
	ds_read_b128 v[184:187], v213 offset:51200
	ds_read_b128 v[188:191], v213 offset:52224
	ds_read_b128 v[192:195], v213 offset:53248
	ds_read_b128 v[196:199], v213 offset:54272
	ds_read_b128 v[200:203], v213 offset:55296
	ds_read_b128 v[214:217], v213 offset:56320
	global_load_lds_dwordx4 v170, s[98:99]
	s_add_i32 m0, s44, 0x2000
	s_add_u32 s42, s42, 0x80080
	s_addc_u32 s43, s43, 0
	s_add_i32 s44, s72, s48
	global_load_lds_dwordx4 v174, s[98:99]
	s_mov_b32 m0, s44
	s_nop 0
	global_load_lds_dwordx4 v170, s[42:43]
	s_add_i32 m0, s44, 0x2000
	s_nop 0
	global_load_lds_dwordx4 v174, s[42:43]
	s_mov_b32 m0, s61
	s_nop 0
	global_load_lds_dwordx4 v168, s[100:101]
	s_mov_b32 m0, s62
	s_nop 0
	global_load_lds_dwordx4 v172, s[100:101]
	s_waitcnt vmcnt(8)
	s_waitcnt lgkmcnt(0)
	s_barrier
	v_mfma_f32_16x16x32_f16 v[56:59], v[136:139], v[160:163], v[56:59]
	v_mfma_f32_16x16x32_f16 v[60:63], v[128:131], v[160:163], v[60:63]
	v_mfma_f32_16x16x32_f16 v[40:43], v[136:139], v[184:187], v[40:43]
	v_mfma_f32_16x16x32_f16 v[44:47], v[128:131], v[184:187], v[44:47]
	v_mfma_f32_16x16x32_f16 v[24:27], v[136:139], v[192:195], v[24:27]
	v_mfma_f32_16x16x32_f16 v[28:31], v[128:131], v[192:195], v[28:31]
	v_mfma_f32_16x16x32_f16 v[8:11], v[136:139], v[200:203], v[8:11]
	v_mfma_f32_16x16x32_f16 v[12:15], v[128:131], v[200:203], v[12:15]
	v_mfma_f32_16x16x32_f16 v[56:59], v[140:143], v[164:167], v[56:59]
	v_mfma_f32_16x16x32_f16 v[60:63], v[132:135], v[164:167], v[60:63]
	v_mfma_f32_16x16x32_f16 v[40:43], v[140:143], v[188:191], v[40:43]
	v_mfma_f32_16x16x32_f16 v[44:47], v[132:135], v[188:191], v[44:47]
	v_mfma_f32_16x16x32_f16 v[24:27], v[140:143], v[196:199], v[24:27]
	v_mfma_f32_16x16x32_f16 v[28:31], v[132:135], v[196:199], v[28:31]
	v_mfma_f32_16x16x32_f16 v[8:11], v[140:143], v[214:217], v[8:11]
	v_mfma_f32_16x16x32_f16 v[12:15], v[132:135], v[214:217], v[12:15]
	v_mfma_f32_16x16x32_f16 v[48:51], v[152:155], v[160:163], v[48:51]
	v_mfma_f32_16x16x32_f16 v[52:55], v[144:147], v[160:163], v[52:55]
	v_mfma_f32_16x16x32_f16 v[32:35], v[152:155], v[184:187], v[32:35]
	v_mfma_f32_16x16x32_f16 v[36:39], v[144:147], v[184:187], v[36:39]
	v_mfma_f32_16x16x32_f16 v[16:19], v[152:155], v[192:195], v[16:19]
	v_mfma_f32_16x16x32_f16 v[20:23], v[144:147], v[192:195], v[20:23]
	v_mfma_f32_16x16x32_f16 v[0:3], v[152:155], v[200:203], v[0:3]
	v_mfma_f32_16x16x32_f16 v[4:7], v[144:147], v[200:203], v[4:7]
	v_mfma_f32_16x16x32_f16 v[48:51], v[156:159], v[164:167], v[48:51]
	v_mfma_f32_16x16x32_f16 v[52:55], v[148:151], v[164:167], v[52:55]
	v_mfma_f32_16x16x32_f16 v[32:35], v[156:159], v[188:191], v[32:35]
	v_mfma_f32_16x16x32_f16 v[36:39], v[148:151], v[188:191], v[36:39]
	v_mfma_f32_16x16x32_f16 v[16:19], v[156:159], v[196:199], v[16:19]
	v_mfma_f32_16x16x32_f16 v[20:23], v[148:151], v[196:199], v[20:23]
	v_mfma_f32_16x16x32_f16 v[0:3], v[156:159], v[214:217], v[0:3]
	v_mfma_f32_16x16x32_f16 v[4:7], v[148:151], v[214:217], v[4:7]
	s_barrier
	s_add_i32 s70, s70, 2
	s_add_u32 s68, s68, 0x100
	s_addc_u32 s69, s69, 0
	s_add_u32 s40, s40, 0x100
	s_addc_u32 s41, s41, 0
	s_cmp_gt_u32 s70, 29
	s_cbranch_scc0 .LBB0_1075
	s_and_b64 vcc, exec, s[20:21]
	s_cbranch_vccz .LBB0_1078
	s_barrier

; #define PG8_STAGE(bufoff, gbase, voff) do { _Pragma("unroll") for (int _i = 0; _i < 2; ++_i) \
;         __builtin_amdgcn_global_load_lds((const unsigned*)((const char*)(gbase) + (voff)[_i]), (PG8_LAS unsigned*)(lds + (bufoff) + ldsw + _i * 8192), 16, 0, 0); } while (0)
; #define PG8_LDA(dst, b, h) do { _Pragma("unroll") for (int m = 0; m < 4; ++m) _Pragma("unroll") for (int k = 0; k < 2; ++k) dst[m][k] = *(const PG8_LAS bf16x8*)(lds + PG8_SA(b, h) + aoff + m * 2048 + k * 1024); } while (0)
; #define PG8_LDB(dst, b, h) do { _Pragma("unroll") for (int n = 0; n < 2; ++n) _Pragma("unroll") for (int k = 0; k < 2; ++k) dst[n][k] = *(const PG8_LAS bf16x8*)(lds + PG8_SB(b, h) + boff + n * 2048 + k * 1024); } while (0)
; #define PG8_MMA(ai, bj, At, Bt) do { __builtin_amdgcn_s_setprio(1); _Pragma("unroll") for (int m = 0; m < 4; ++m) _Pragma("unroll") for (int n = 0; n < 2; ++n) _Pragma("unroll") for (int k = 0; k < 2; ++k) \
;         acc[ai][bj][m][n] = __builtin_amdgcn_mfma_f32_16x16x32_f16(Bt[n][k], At[m][k], acc[ai][bj][m][n], 0, 0, 0); __builtin_amdgcn_s_setprio(0); } while (0)
; #define PG8_WAIT_V(n) asm volatile("s_waitcnt vmcnt(" #n ")" ::: "memory")
; #define PG8_BAR __builtin_amdgcn_s_barrier()
; template <class Epi, class Sched, bool ALIGN_EPI = false, bool SP2 = false>
; __device__ __forceinline__ void gemm_phase(PG8_LAS unsigned char* lds, const Gemm g, const Sched& S, const Epi& E) {
;     ...
;         const char* nA = has_next ? (const char*)g.A + (size_t)nxt.pm * tstep : cA; const char* nB = has_next ? (const char*)g.Bt + (size_t)nxt.pn * tstep : cB;
;         for (int t = 0; t < nt; t += 2) {
;             const bool last = (t == nt - 2);
;             const char* a1 = cA + (size_t)(t + 1) * kstep;
;             const char* a2 = last ? nA : cA + (size_t)(t + 2) * kstep; const char* b2 = last ? nB : cB + (size_t)(t + 2) * kstep;
;     ...
;             PG8_LDB(B0, 0, 0); PG8_LDB(B1, 0, 1); PG8_SCHED; PG8_LDA(At, 0, 0); PG8_STAGE(PG8_SA(1, 1), a1 + hstep, voffA);
;             PG8_WAIT_V(8); PG8_WAIT_L(0); PG8_BAR; PG8_MMA(0, 0, At, B0); PG8_MMA(0, 1, At, B1); PG8_BAR; PG8_SCHED;
;             PG8_LDA(At, 0, 1); PG8_STAGE(PG8_SB(0, 0), b2, voffB); PG8_STAGE(PG8_SB(0, 1), b2 + hstep, voffB); PG8_STAGE(PG8_SA(0, 0), a2, voffA);
;             PG8_WAIT_V(8); PG8_WAIT_L(0); PG8_BAR; PG8_MMA(1, 0, At, B0); PG8_MMA(1, 1, At, B1); PG8_BAR; PG8_SCHED;
.LBB0_1167:
	ds_read_b128 v[128:131], v198
	ds_read_b128 v[132:135], v198 offset:1024
	ds_read_b128 v[136:139], v198 offset:2048
	ds_read_b128 v[140:143], v198 offset:3072
	ds_read_b128 v[144:147], v199
	ds_read_b128 v[148:151], v199 offset:1024
	ds_read_b128 v[152:155], v199 offset:2048
	ds_read_b128 v[156:159], v199 offset:3072
	s_add_u32 s44, s42, 0xfff80080
	s_addc_u32 s45, s43, -1
	s_cmp_eq_u32 s81, 28
	s_cselect_b32 s49, s35, s45
	s_cselect_b32 s48, s72, s44
	s_cselect_b32 s45, s31, s75
	s_cselect_b32 s44, s73, s74
	s_add_i32 m0, s41, 0xc000
	ds_read_b128 v[176:179], v200
	ds_read_b128 v[180:183], v200 offset:1024
	ds_read_b128 v[184:187], v200 offset:2048
	ds_read_b128 v[188:191], v200 offset:3072
	ds_read_b128 v[208:211], v200 offset:4096
	ds_read_b128 v[212:215], v200 offset:5120
	ds_read_b128 v[216:219], v200 offset:6144
	ds_read_b128 v[220:223], v200 offset:7168
	global_load_lds_dwordx4 v170, s[42:43]
	s_add_i32 m0, s41, 0xe000
	s_nop 0
	global_load_lds_dwordx4 v168, s[42:43]
	s_waitcnt vmcnt(8)
	s_waitcnt lgkmcnt(0)
	s_barrier
	v_mfma_f32_16x16x32_f16 v[120:123], v[136:139], v[176:179], v[120:123]
	v_mfma_f32_16x16x32_f16 v[124:127], v[128:131], v[176:179], v[124:127]
	v_mfma_f32_16x16x32_f16 v[104:107], v[136:139], v[184:187], v[104:107]
	v_mfma_f32_16x16x32_f16 v[108:111], v[128:131], v[184:187], v[108:111]
	v_mfma_f32_16x16x32_f16 v[88:91], v[136:139], v[208:211], v[88:91]
	v_mfma_f32_16x16x32_f16 v[92:95], v[128:131], v[208:211], v[92:95]
	v_mfma_f32_16x16x32_f16 v[72:75], v[136:139], v[216:219], v[72:75]
	v_mfma_f32_16x16x32_f16 v[76:79], v[128:131], v[216:219], v[76:79]
	v_mfma_f32_16x16x32_f16 v[120:123], v[140:143], v[180:183], v[120:123]
	v_mfma_f32_16x16x32_f16 v[124:127], v[132:135], v[180:183], v[124:127]
	v_mfma_f32_16x16x32_f16 v[104:107], v[140:143], v[188:191], v[104:107]
	v_mfma_f32_16x16x32_f16 v[108:111], v[132:135], v[188:191], v[108:111]
	v_mfma_f32_16x16x32_f16 v[88:91], v[140:143], v[212:215], v[88:91]
	v_mfma_f32_16x16x32_f16 v[92:95], v[132:135], v[212:215], v[92:95]
	v_mfma_f32_16x16x32_f16 v[72:75], v[140:143], v[220:223], v[72:75]
	v_mfma_f32_16x16x32_f16 v[76:79], v[132:135], v[220:223], v[76:79]
	v_mfma_f32_16x16x32_f16 v[112:115], v[152:155], v[176:179], v[112:115]
	v_mfma_f32_16x16x32_f16 v[116:119], v[144:147], v[176:179], v[116:119]
	v_mfma_f32_16x16x32_f16 v[96:99], v[152:155], v[184:187], v[96:99]
	v_mfma_f32_16x16x32_f16 v[100:103], v[144:147], v[184:187], v[100:103]
	v_mfma_f32_16x16x32_f16 v[80:83], v[152:155], v[208:211], v[80:83]
	v_mfma_f32_16x16x32_f16 v[84:87], v[144:147], v[208:211], v[84:87]
	v_mfma_f32_16x16x32_f16 v[64:67], v[152:155], v[216:219], v[64:67]
	v_mfma_f32_16x16x32_f16 v[68:71], v[144:147], v[216:219], v[68:71]
	v_mfma_f32_16x16x32_f16 v[112:115], v[156:159], v[180:183], v[112:115]
	v_mfma_f32_16x16x32_f16 v[116:119], v[148:151], v[180:183], v[116:119]
	v_mfma_f32_16x16x32_f16 v[96:99], v[156:159], v[188:191], v[96:99]
	v_mfma_f32_16x16x32_f16 v[100:103], v[148:151], v[188:191], v[100:103]
	v_mfma_f32_16x16x32_f16 v[80:83], v[156:159], v[212:215], v[80:83]
	v_mfma_f32_16x16x32_f16 v[84:87], v[148:151], v[212:215], v[84:87]
	v_mfma_f32_16x16x32_f16 v[64:67], v[156:159], v[220:223], v[64:67]
	v_mfma_f32_16x16x32_f16 v[68:71], v[148:151], v[220:223], v[68:71]
	s_barrier
	s_add_i32 s82, s65, s52
	s_add_u32 s98, s44, s16
	s_addc_u32 s99, s45, s17
	s_mov_b32 m0, s82
	ds_read_b128 v[176:179], v200 offset:16384
	ds_read_b128 v[180:183], v200 offset:17408
	ds_read_b128 v[184:187], v200 offset:18432
	ds_read_b128 v[188:191], v200 offset:19456
	ds_read_b128 v[208:211], v200 offset:20480
	ds_read_b128 v[212:215], v200 offset:21504
	ds_read_b128 v[216:219], v200 offset:22528
	ds_read_b128 v[220:223], v200 offset:23552
	global_load_lds_dwordx4 v162, s[44:45]
	s_add_i32 m0, s82, 0x2000
	s_add_u32 s82, s44, 0x80000
	s_addc_u32 s83, s45, 0
	s_add_i32 s86, s66, s52
	global_load_lds_dwordx4 v166, s[44:45]
	s_mov_b32 m0, s86
	s_nop 0
	global_load_lds_dwordx4 v162, s[82:83]
	s_add_i32 m0, s86, 0x2000
	s_nop 0
	global_load_lds_dwordx4 v166, s[82:83]
	s_mov_b32 m0, s41
	s_add_u32 s100, s48, s16
	s_addc_u32 s101, s49, s17
	global_load_lds_dwordx4 v160, s[48:49]
	s_mov_b32 m0, s53
	s_nop 0
	global_load_lds_dwordx4 v164, s[48:49]
	s_waitcnt vmcnt(8)
	s_waitcnt lgkmcnt(0)
	s_barrier
	v_mfma_f32_16x16x32_f16 v[56:59], v[136:139], v[176:179], v[56:59]
	v_mfma_f32_16x16x32_f16 v[60:63], v[128:131], v[176:179], v[60:63]
	v_mfma_f32_16x16x32_f16 v[40:43], v[136:139], v[184:187], v[40:43]
	v_mfma_f32_16x16x32_f16 v[44:47], v[128:131], v[184:187], v[44:47]
	v_mfma_f32_16x16x32_f16 v[24:27], v[136:139], v[208:211], v[24:27]
	v_mfma_f32_16x16x32_f16 v[28:31], v[128:131], v[208:211], v[28:31]
	v_mfma_f32_16x16x32_f16 v[8:11], v[136:139], v[216:219], v[8:11]
	v_mfma_f32_16x16x32_f16 v[12:15], v[128:131], v[216:219], v[12:15]
	v_mfma_f32_16x16x32_f16 v[56:59], v[140:143], v[180:183], v[56:59]
	v_mfma_f32_16x16x32_f16 v[60:63], v[132:135], v[180:183], v[60:63]
	v_mfma_f32_16x16x32_f16 v[40:43], v[140:143], v[188:191], v[40:43]
	v_mfma_f32_16x16x32_f16 v[44:47], v[132:135], v[188:191], v[44:47]
	v_mfma_f32_16x16x32_f16 v[24:27], v[140:143], v[212:215], v[24:27]
	v_mfma_f32_16x16x32_f16 v[28:31], v[132:135], v[212:215], v[28:31]
	v_mfma_f32_16x16x32_f16 v[8:11], v[140:143], v[220:223], v[8:11]
	v_mfma_f32_16x16x32_f16 v[12:15], v[132:135], v[220:223], v[12:15]
	v_mfma_f32_16x16x32_f16 v[48:51], v[152:155], v[176:179], v[48:51]
	v_mfma_f32_16x16x32_f16 v[52:55], v[144:147], v[176:179], v[52:55]
	v_mfma_f32_16x16x32_f16 v[32:35], v[152:155], v[184:187], v[32:35]
	v_mfma_f32_16x16x32_f16 v[36:39], v[144:147], v[184:187], v[36:39]
	v_mfma_f32_16x16x32_f16 v[16:19], v[152:155], v[208:211], v[16:19]
	v_mfma_f32_16x16x32_f16 v[20:23], v[144:147], v[208:211], v[20:23]
	v_mfma_f32_16x16x32_f16 v[0:3], v[152:155], v[216:219], v[0:3]
	v_mfma_f32_16x16x32_f16 v[4:7], v[144:147], v[216:219], v[4:7]
	v_mfma_f32_16x16x32_f16 v[48:51], v[156:159], v[180:183], v[48:51]
	v_mfma_f32_16x16x32_f16 v[52:55], v[148:151], v[180:183], v[52:55]
	v_mfma_f32_16x16x32_f16 v[32:35], v[156:159], v[188:191], v[32:35]
	v_mfma_f32_16x16x32_f16 v[36:39], v[148:151], v[188:191], v[36:39]
	v_mfma_f32_16x16x32_f16 v[16:19], v[156:159], v[212:215], v[16:19]
	v_mfma_f32_16x16x32_f16 v[20:23], v[148:151], v[212:215], v[20:23]
	v_mfma_f32_16x16x32_f16 v[0:3], v[156:159], v[220:223], v[0:3]
	v_mfma_f32_16x16x32_f16 v[4:7], v[148:151], v[220:223], v[4:7]
	s_barrier
; #define PG8_STAGE(bufoff, gbase, voff) do { _Pragma("unroll") for (int _i = 0; _i < 2; ++_i) \
;         __builtin_amdgcn_global_load_lds((const unsigned*)((const char*)(gbase) + (voff)[_i]), (PG8_LAS unsigned*)(lds + (bufoff) + ldsw + _i * 8192), 16, 0, 0); } while (0)
; #define PG8_LDA(dst, b, h) do { _Pragma("unroll") for (int m = 0; m < 4; ++m) _Pragma("unroll") for (int k = 0; k < 2; ++k) dst[m][k] = *(const PG8_LAS bf16x8*)(lds + PG8_SA(b, h) + aoff + m * 2048 + k * 1024); } while (0)
; #define PG8_LDB(dst, b, h) do { _Pragma("unroll") for (int n = 0; n < 2; ++n) _Pragma("unroll") for (int k = 0; k < 2; ++k) dst[n][k] = *(const PG8_LAS bf16x8*)(lds + PG8_SB(b, h) + boff + n * 2048 + k * 1024); } while (0)
; #define PG8_MMA(ai, bj, At, Bt) do { __builtin_amdgcn_s_setprio(1); _Pragma("unroll") for (int m = 0; m < 4; ++m) _Pragma("unroll") for (int n = 0; n < 2; ++n) _Pragma("unroll") for (int k = 0; k < 2; ++k) \
;         acc[ai][bj][m][n] = __builtin_amdgcn_mfma_f32_16x16x32_f16(Bt[n][k], At[m][k], acc[ai][bj][m][n], 0, 0, 0); __builtin_amdgcn_s_setprio(0); } while (0)
; #define PG8_WAIT_V(n) asm volatile("s_waitcnt vmcnt(" #n ")" ::: "memory")
; #define PG8_WAIT_L(n) asm volatile("s_waitcnt lgkmcnt(" #n ")" ::: "memory")
; #define PG8_BAR __builtin_amdgcn_s_barrier()
; #define PG8_SCHED __builtin_amdgcn_sched_barrier(0)
; template <class Epi, class Sched, bool ALIGN_EPI = false, bool SP2 = false>
; __device__ __forceinline__ void gemm_phase(PG8_LAS unsigned char* lds, const Gemm g, const Sched& S, const Epi& E) {
;     ...
;         for (int t = 0; t < nt; t += 2) {
;     ...
;             PG8_LDB(B0, 1, 0); PG8_LDB(B1, 1, 1); PG8_SCHED; PG8_LDA(At, 1, 0); PG8_STAGE(PG8_SA(0, 1), a2 + hstep, voffA);
;             PG8_WAIT_V(8); PG8_WAIT_L(0); PG8_BAR; PG8_MMA(0, 0, At, B0); PG8_MMA(0, 1, At, B1); PG8_BAR; PG8_SCHED;
;             PG8_LDA(At, 1, 1); PG8_STAGE(PG8_SB(1, 0), b3, voffB); PG8_STAGE(PG8_SB(1, 1), b3 + hstep, voffB); PG8_STAGE(PG8_SA(1, 0), a3, voffA);
;             PG8_WAIT_V(8); PG8_WAIT_L(0); PG8_BAR; PG8_MMA(1, 0, At, B0); PG8_MMA(1, 1, At, B1); PG8_BAR; PG8_SCHED;
	s_add_i32 s82, 0, 0x18000
	s_add_i32 s83, 0, 0x1c000
	v_add_u32_e32 v140, s82, v196
	v_add_u32_e32 v156, s83, v196
	ds_read_b128 v[128:131], v140
	ds_read_b128 v[132:135], v140 offset:1024
	ds_read_b128 v[136:139], v140 offset:2048
	ds_read_b128 v[140:143], v140 offset:3072
	ds_read_b128 v[144:147], v156
	ds_read_b128 v[148:151], v156 offset:1024
	ds_read_b128 v[152:155], v156 offset:2048
	ds_read_b128 v[156:159], v156 offset:3072
	s_add_u32 s48, s48, 0x80000
	s_addc_u32 s49, s49, 0
	s_mov_b32 m0, s60
	ds_read_b128 v[176:179], v200 offset:32768
	ds_read_b128 v[180:183], v200 offset:33792
	ds_read_b128 v[184:187], v200 offset:34816
	ds_read_b128 v[188:191], v200 offset:35840
	ds_read_b128 v[208:211], v200 offset:36864
	ds_read_b128 v[212:215], v200 offset:37888
	ds_read_b128 v[216:219], v200 offset:38912
	ds_read_b128 v[220:223], v200 offset:39936
	global_load_lds_dwordx4 v160, s[48:49]
	s_mov_b32 m0, s61
	s_nop 0
	global_load_lds_dwordx4 v164, s[48:49]
	s_waitcnt vmcnt(8)
	s_waitcnt lgkmcnt(0)
	s_barrier
	v_mfma_f32_16x16x32_f16 v[120:123], v[136:139], v[176:179], v[120:123]
	v_mfma_f32_16x16x32_f16 v[124:127], v[128:131], v[176:179], v[124:127]
	v_mfma_f32_16x16x32_f16 v[104:107], v[136:139], v[184:187], v[104:107]
	v_mfma_f32_16x16x32_f16 v[108:111], v[128:131], v[184:187], v[108:111]
	v_mfma_f32_16x16x32_f16 v[88:91], v[136:139], v[208:211], v[88:91]
	v_mfma_f32_16x16x32_f16 v[92:95], v[128:131], v[208:211], v[92:95]
	v_mfma_f32_16x16x32_f16 v[72:75], v[136:139], v[216:219], v[72:75]
	v_mfma_f32_16x16x32_f16 v[76:79], v[128:131], v[216:219], v[76:79]
	v_mfma_f32_16x16x32_f16 v[120:123], v[140:143], v[180:183], v[120:123]
	v_mfma_f32_16x16x32_f16 v[124:127], v[132:135], v[180:183], v[124:127]
	v_mfma_f32_16x16x32_f16 v[104:107], v[140:143], v[188:191], v[104:107]
	v_mfma_f32_16x16x32_f16 v[108:111], v[132:135], v[188:191], v[108:111]
	v_mfma_f32_16x16x32_f16 v[88:91], v[140:143], v[212:215], v[88:91]
	v_mfma_f32_16x16x32_f16 v[92:95], v[132:135], v[212:215], v[92:95]
	v_mfma_f32_16x16x32_f16 v[72:75], v[140:143], v[220:223], v[72:75]
	v_mfma_f32_16x16x32_f16 v[76:79], v[132:135], v[220:223], v[76:79]
	v_mfma_f32_16x16x32_f16 v[112:115], v[152:155], v[176:179], v[112:115]
	v_mfma_f32_16x16x32_f16 v[116:119], v[144:147], v[176:179], v[116:119]
	v_mfma_f32_16x16x32_f16 v[96:99], v[152:155], v[184:187], v[96:99]
	v_mfma_f32_16x16x32_f16 v[100:103], v[144:147], v[184:187], v[100:103]
	v_mfma_f32_16x16x32_f16 v[80:83], v[152:155], v[208:211], v[80:83]
	v_mfma_f32_16x16x32_f16 v[84:87], v[144:147], v[208:211], v[84:87]
	v_mfma_f32_16x16x32_f16 v[64:67], v[152:155], v[216:219], v[64:67]
	v_mfma_f32_16x16x32_f16 v[68:71], v[144:147], v[216:219], v[68:71]
	v_mfma_f32_16x16x32_f16 v[112:115], v[156:159], v[180:183], v[112:115]
	v_mfma_f32_16x16x32_f16 v[116:119], v[148:151], v[180:183], v[116:119]
	v_mfma_f32_16x16x32_f16 v[96:99], v[156:159], v[188:191], v[96:99]
	v_mfma_f32_16x16x32_f16 v[100:103], v[148:151], v[188:191], v[100:103]
	v_mfma_f32_16x16x32_f16 v[80:83], v[156:159], v[212:215], v[80:83]
	v_mfma_f32_16x16x32_f16 v[84:87], v[148:151], v[212:215], v[84:87]
	v_mfma_f32_16x16x32_f16 v[64:67], v[156:159], v[220:223], v[64:67]
	v_mfma_f32_16x16x32_f16 v[68:71], v[148:151], v[220:223], v[68:71]
	s_barrier
	s_add_i32 s48, s82, s52
	s_mov_b32 m0, s48
	ds_read_b128 v[176:179], v200 offset:49152
	ds_read_b128 v[180:183], v200 offset:50176
	ds_read_b128 v[184:187], v200 offset:51200
	ds_read_b128 v[188:191], v200 offset:52224
	ds_read_b128 v[208:211], v200 offset:53248
	ds_read_b128 v[212:215], v200 offset:54272
	ds_read_b128 v[216:219], v200 offset:55296
	ds_read_b128 v[220:223], v200 offset:56320
	global_load_lds_dwordx4 v162, s[98:99]
	s_add_i32 m0, s48, 0x2000
	s_add_u32 s44, s44, 0x80080
	s_addc_u32 s45, s45, 0
	s_add_i32 s48, s83, s52
	global_load_lds_dwordx4 v166, s[98:99]
	s_mov_b32 m0, s48
	s_nop 0
	global_load_lds_dwordx4 v162, s[44:45]
	s_add_i32 m0, s48, 0x2000
	s_nop 0
	global_load_lds_dwordx4 v166, s[44:45]
	s_mov_b32 m0, s63
	s_nop 0
	global_load_lds_dwordx4 v160, s[100:101]
	s_mov_b32 m0, s64
	s_nop 0
	global_load_lds_dwordx4 v164, s[100:101]
	s_waitcnt vmcnt(8)
	s_waitcnt lgkmcnt(0)
	s_barrier
	v_mfma_f32_16x16x32_f16 v[56:59], v[136:139], v[176:179], v[56:59]
	v_mfma_f32_16x16x32_f16 v[60:63], v[128:131], v[176:179], v[60:63]
	v_mfma_f32_16x16x32_f16 v[40:43], v[136:139], v[184:187], v[40:43]
	v_mfma_f32_16x16x32_f16 v[44:47], v[128:131], v[184:187], v[44:47]
	v_mfma_f32_16x16x32_f16 v[24:27], v[136:139], v[208:211], v[24:27]
	v_mfma_f32_16x16x32_f16 v[28:31], v[128:131], v[208:211], v[28:31]
	v_mfma_f32_16x16x32_f16 v[8:11], v[136:139], v[216:219], v[8:11]
	v_mfma_f32_16x16x32_f16 v[12:15], v[128:131], v[216:219], v[12:15]
	v_mfma_f32_16x16x32_f16 v[56:59], v[140:143], v[180:183], v[56:59]
	v_mfma_f32_16x16x32_f16 v[60:63], v[132:135], v[180:183], v[60:63]
	v_mfma_f32_16x16x32_f16 v[40:43], v[140:143], v[188:191], v[40:43]
	v_mfma_f32_16x16x32_f16 v[44:47], v[132:135], v[188:191], v[44:47]
	v_mfma_f32_16x16x32_f16 v[24:27], v[140:143], v[212:215], v[24:27]
	v_mfma_f32_16x16x32_f16 v[28:31], v[132:135], v[212:215], v[28:31]
	v_mfma_f32_16x16x32_f16 v[8:11], v[140:143], v[220:223], v[8:11]
	v_mfma_f32_16x16x32_f16 v[12:15], v[132:135], v[220:223], v[12:15]
	v_mfma_f32_16x16x32_f16 v[48:51], v[152:155], v[176:179], v[48:51]
	v_mfma_f32_16x16x32_f16 v[52:55], v[144:147], v[176:179], v[52:55]
	v_mfma_f32_16x16x32_f16 v[32:35], v[152:155], v[184:187], v[32:35]
	v_mfma_f32_16x16x32_f16 v[36:39], v[144:147], v[184:187], v[36:39]
	v_mfma_f32_16x16x32_f16 v[16:19], v[152:155], v[208:211], v[16:19]
	v_mfma_f32_16x16x32_f16 v[20:23], v[144:147], v[208:211], v[20:23]
	v_mfma_f32_16x16x32_f16 v[0:3], v[152:155], v[216:219], v[0:3]
	v_mfma_f32_16x16x32_f16 v[4:7], v[144:147], v[216:219], v[4:7]
	v_mfma_f32_16x16x32_f16 v[48:51], v[156:159], v[180:183], v[48:51]
	v_mfma_f32_16x16x32_f16 v[52:55], v[148:151], v[180:183], v[52:55]
	v_mfma_f32_16x16x32_f16 v[32:35], v[156:159], v[188:191], v[32:35]
	v_mfma_f32_16x16x32_f16 v[36:39], v[148:151], v[188:191], v[36:39]
	v_mfma_f32_16x16x32_f16 v[16:19], v[156:159], v[212:215], v[16:19]
	v_mfma_f32_16x16x32_f16 v[20:23], v[148:151], v[212:215], v[20:23]
	v_mfma_f32_16x16x32_f16 v[0:3], v[156:159], v[220:223], v[0:3]
	v_mfma_f32_16x16x32_f16 v[4:7], v[148:151], v[220:223], v[4:7]
	s_barrier
	s_add_i32 s81, s81, 2
	s_add_u32 s74, s74, 0x100
	s_addc_u32 s75, s75, 0
	s_add_u32 s42, s42, 0x100
	s_addc_u32 s43, s43, 0
	s_cmp_gt_u32 s81, 29
	s_cbranch_scc0 .LBB0_1167
	s_and_b64 vcc, exec, s[18:19]
	s_cbranch_vccz .LBB0_1170
	s_barrier

; #define PG8_STAGE(bufoff, gbase, voff) do { _Pragma("unroll") for (int _i = 0; _i < 2; ++_i) \
;         __builtin_amdgcn_global_load_lds((const unsigned*)((const char*)(gbase) + (voff)[_i]), (PG8_LAS unsigned*)(lds + (bufoff) + ldsw + _i * 8192), 16, 0, 0); } while (0)
; #define PG8_LDA(dst, b, h) do { _Pragma("unroll") for (int m = 0; m < 4; ++m) _Pragma("unroll") for (int k = 0; k < 2; ++k) dst[m][k] = *(const PG8_LAS bf16x8*)(lds + PG8_SA(b, h) + aoff + m * 2048 + k * 1024); } while (0)
; #define PG8_LDB(dst, b, h) do { _Pragma("unroll") for (int n = 0; n < 2; ++n) _Pragma("unroll") for (int k = 0; k < 2; ++k) dst[n][k] = *(const PG8_LAS bf16x8*)(lds + PG8_SB(b, h) + boff + n * 2048 + k * 1024); } while (0)
; #define PG8_MMA(ai, bj, At, Bt) do { __builtin_amdgcn_s_setprio(1); _Pragma("unroll") for (int m = 0; m < 4; ++m) _Pragma("unroll") for (int n = 0; n < 2; ++n) _Pragma("unroll") for (int k = 0; k < 2; ++k) \
;         acc[ai][bj][m][n] = __builtin_amdgcn_mfma_f32_16x16x32_f16(Bt[n][k], At[m][k], acc[ai][bj][m][n], 0, 0, 0); __builtin_amdgcn_s_setprio(0); } while (0)
; #define PG8_WAIT_V(n) asm volatile("s_waitcnt vmcnt(" #n ")" ::: "memory")
; #define PG8_BAR __builtin_amdgcn_s_barrier()
; template <class Epi, class Sched, bool ALIGN_EPI = false, bool SP2 = false>
; __device__ __forceinline__ void gemm_phase(PG8_LAS unsigned char* lds, const Gemm g, const Sched& S, const Epi& E) {
;     ...
;         const char* nA = has_next ? (const char*)g.A + (size_t)nxt.pm * tstep : cA; const char* nB = has_next ? (const char*)g.Bt + (size_t)nxt.pn * tstep : cB;
;         for (int t = 0; t < nt; t += 2) {
;             const bool last = (t == nt - 2);
;             const char* a1 = cA + (size_t)(t + 1) * kstep;
;             const char* a2 = last ? nA : cA + (size_t)(t + 2) * kstep; const char* b2 = last ? nB : cB + (size_t)(t + 2) * kstep;
;     ...
;             PG8_LDB(B0, 0, 0); PG8_LDB(B1, 0, 1); PG8_SCHED; PG8_LDA(At, 0, 0); PG8_STAGE(PG8_SA(1, 1), a1 + hstep, voffA);
;             PG8_WAIT_V(8); PG8_WAIT_L(0); PG8_BAR; PG8_MMA(0, 0, At, B0); PG8_MMA(0, 1, At, B1); PG8_BAR; PG8_SCHED;
;             PG8_LDA(At, 0, 1); PG8_STAGE(PG8_SB(0, 0), b2, voffB); PG8_STAGE(PG8_SB(0, 1), b2 + hstep, voffB); PG8_STAGE(PG8_SA(0, 0), a2, voffA);
;             PG8_WAIT_V(8); PG8_WAIT_L(0); PG8_BAR; PG8_MMA(1, 0, At, B0); PG8_MMA(1, 1, At, B1); PG8_BAR; PG8_SCHED;
.LBB0_1243:
	ds_read_b128 v[128:131], v189
	ds_read_b128 v[132:135], v189 offset:1024
	ds_read_b128 v[136:139], v189 offset:2048
	ds_read_b128 v[140:143], v189 offset:3072
	ds_read_b128 v[144:147], v190
	ds_read_b128 v[148:151], v190 offset:1024
	ds_read_b128 v[152:155], v190 offset:2048
	ds_read_b128 v[156:159], v190 offset:3072
	s_add_u32 s34, s30, 0xffe00080
	s_addc_u32 s35, s31, -1
	s_cmpk_eq_i32 s61, 0x7c
	s_cselect_b32 s37, s23, s35
	s_cselect_b32 s36, s51, s34
	s_cselect_b32 s35, s21, s60
	s_cselect_b32 s34, s52, s53
	s_add_i32 m0, s29, 0xc000
	ds_read_b128 v[176:179], v191
	ds_read_b128 v[180:183], v191 offset:1024
	ds_read_b128 v[192:195], v191 offset:2048
	ds_read_b128 v[196:199], v191 offset:3072
	ds_read_b128 v[200:203], v191 offset:4096
	ds_read_b128 v[208:211], v191 offset:5120
	ds_read_b128 v[212:215], v191 offset:6144
	ds_read_b128 v[216:219], v191 offset:7168
	global_load_lds_dwordx4 v170, s[30:31]
	s_add_i32 m0, s29, 0xe000
	s_nop 0
	global_load_lds_dwordx4 v168, s[30:31]
	s_waitcnt vmcnt(8)
	s_waitcnt lgkmcnt(0)
	s_barrier
	v_mfma_f32_16x16x32_f16 v[120:123], v[136:139], v[176:179], v[120:123]
	v_mfma_f32_16x16x32_f16 v[124:127], v[128:131], v[176:179], v[124:127]
	v_mfma_f32_16x16x32_f16 v[104:107], v[136:139], v[192:195], v[104:107]
	v_mfma_f32_16x16x32_f16 v[108:111], v[128:131], v[192:195], v[108:111]
	v_mfma_f32_16x16x32_f16 v[88:91], v[136:139], v[200:203], v[88:91]
	v_mfma_f32_16x16x32_f16 v[92:95], v[128:131], v[200:203], v[92:95]
	v_mfma_f32_16x16x32_f16 v[72:75], v[136:139], v[212:215], v[72:75]
	v_mfma_f32_16x16x32_f16 v[76:79], v[128:131], v[212:215], v[76:79]
	v_mfma_f32_16x16x32_f16 v[120:123], v[140:143], v[180:183], v[120:123]
	v_mfma_f32_16x16x32_f16 v[124:127], v[132:135], v[180:183], v[124:127]
	v_mfma_f32_16x16x32_f16 v[104:107], v[140:143], v[196:199], v[104:107]
	v_mfma_f32_16x16x32_f16 v[108:111], v[132:135], v[196:199], v[108:111]
	v_mfma_f32_16x16x32_f16 v[88:91], v[140:143], v[208:211], v[88:91]
	v_mfma_f32_16x16x32_f16 v[92:95], v[132:135], v[208:211], v[92:95]
	v_mfma_f32_16x16x32_f16 v[72:75], v[140:143], v[216:219], v[72:75]
	v_mfma_f32_16x16x32_f16 v[76:79], v[132:135], v[216:219], v[76:79]
	v_mfma_f32_16x16x32_f16 v[112:115], v[152:155], v[176:179], v[112:115]
	v_mfma_f32_16x16x32_f16 v[116:119], v[144:147], v[176:179], v[116:119]
	v_mfma_f32_16x16x32_f16 v[96:99], v[152:155], v[192:195], v[96:99]
	v_mfma_f32_16x16x32_f16 v[100:103], v[144:147], v[192:195], v[100:103]
	v_mfma_f32_16x16x32_f16 v[80:83], v[152:155], v[200:203], v[80:83]
	v_mfma_f32_16x16x32_f16 v[84:87], v[144:147], v[200:203], v[84:87]
	v_mfma_f32_16x16x32_f16 v[64:67], v[152:155], v[212:215], v[64:67]
	v_mfma_f32_16x16x32_f16 v[68:71], v[144:147], v[212:215], v[68:71]
	v_mfma_f32_16x16x32_f16 v[112:115], v[156:159], v[180:183], v[112:115]
	v_mfma_f32_16x16x32_f16 v[116:119], v[148:151], v[180:183], v[116:119]
	v_mfma_f32_16x16x32_f16 v[96:99], v[156:159], v[196:199], v[96:99]
	v_mfma_f32_16x16x32_f16 v[100:103], v[148:151], v[196:199], v[100:103]
	v_mfma_f32_16x16x32_f16 v[80:83], v[156:159], v[208:211], v[80:83]
	v_mfma_f32_16x16x32_f16 v[84:87], v[148:151], v[208:211], v[84:87]
	v_mfma_f32_16x16x32_f16 v[64:67], v[156:159], v[216:219], v[64:67]
	v_mfma_f32_16x16x32_f16 v[68:71], v[148:151], v[216:219], v[68:71]
	s_barrier
	s_add_i32 s62, s48, s39
	s_add_u32 s98, s34, s12
	s_addc_u32 s99, s35, s13
	s_mov_b32 m0, s62
	ds_read_b128 v[176:179], v191 offset:16384
	ds_read_b128 v[180:183], v191 offset:17408
	ds_read_b128 v[192:195], v191 offset:18432
	ds_read_b128 v[196:199], v191 offset:19456
	ds_read_b128 v[200:203], v191 offset:20480
	ds_read_b128 v[208:211], v191 offset:21504
	ds_read_b128 v[212:215], v191 offset:22528
	ds_read_b128 v[216:219], v191 offset:23552
	global_load_lds_dwordx4 v162, s[34:35]
	s_add_i32 m0, s62, 0x2000
	s_add_u32 s62, s34, 0x200000
	s_addc_u32 s63, s35, 0
	s_add_i32 s64, s49, s39
	global_load_lds_dwordx4 v166, s[34:35]
	s_mov_b32 m0, s64
	s_nop 0
	global_load_lds_dwordx4 v162, s[62:63]
	s_add_i32 m0, s64, 0x2000
	s_nop 0
	global_load_lds_dwordx4 v166, s[62:63]
	s_mov_b32 m0, s29
	s_add_u32 s100, s36, s12
	s_addc_u32 s101, s37, s13
	global_load_lds_dwordx4 v160, s[36:37]
	s_mov_b32 m0, s40
	s_nop 0
	global_load_lds_dwordx4 v164, s[36:37]
	s_waitcnt vmcnt(8)
	s_waitcnt lgkmcnt(0)
	s_barrier
	v_mfma_f32_16x16x32_f16 v[56:59], v[136:139], v[176:179], v[56:59]
	v_mfma_f32_16x16x32_f16 v[60:63], v[128:131], v[176:179], v[60:63]
	v_mfma_f32_16x16x32_f16 v[40:43], v[136:139], v[192:195], v[40:43]
	v_mfma_f32_16x16x32_f16 v[44:47], v[128:131], v[192:195], v[44:47]
	v_mfma_f32_16x16x32_f16 v[24:27], v[136:139], v[200:203], v[24:27]
	v_mfma_f32_16x16x32_f16 v[28:31], v[128:131], v[200:203], v[28:31]
	v_mfma_f32_16x16x32_f16 v[8:11], v[136:139], v[212:215], v[8:11]
	v_mfma_f32_16x16x32_f16 v[12:15], v[128:131], v[212:215], v[12:15]
	v_mfma_f32_16x16x32_f16 v[56:59], v[140:143], v[180:183], v[56:59]
	v_mfma_f32_16x16x32_f16 v[60:63], v[132:135], v[180:183], v[60:63]
	v_mfma_f32_16x16x32_f16 v[40:43], v[140:143], v[196:199], v[40:43]
	v_mfma_f32_16x16x32_f16 v[44:47], v[132:135], v[196:199], v[44:47]
	v_mfma_f32_16x16x32_f16 v[24:27], v[140:143], v[208:211], v[24:27]
	v_mfma_f32_16x16x32_f16 v[28:31], v[132:135], v[208:211], v[28:31]
	v_mfma_f32_16x16x32_f16 v[8:11], v[140:143], v[216:219], v[8:11]
	v_mfma_f32_16x16x32_f16 v[12:15], v[132:135], v[216:219], v[12:15]
	v_mfma_f32_16x16x32_f16 v[48:51], v[152:155], v[176:179], v[48:51]
	v_mfma_f32_16x16x32_f16 v[52:55], v[144:147], v[176:179], v[52:55]
	v_mfma_f32_16x16x32_f16 v[32:35], v[152:155], v[192:195], v[32:35]
	v_mfma_f32_16x16x32_f16 v[36:39], v[144:147], v[192:195], v[36:39]
	v_mfma_f32_16x16x32_f16 v[16:19], v[152:155], v[200:203], v[16:19]
	v_mfma_f32_16x16x32_f16 v[20:23], v[144:147], v[200:203], v[20:23]
	v_mfma_f32_16x16x32_f16 v[0:3], v[152:155], v[212:215], v[0:3]
	v_mfma_f32_16x16x32_f16 v[4:7], v[144:147], v[212:215], v[4:7]
	v_mfma_f32_16x16x32_f16 v[48:51], v[156:159], v[180:183], v[48:51]
	v_mfma_f32_16x16x32_f16 v[52:55], v[148:151], v[180:183], v[52:55]
	v_mfma_f32_16x16x32_f16 v[32:35], v[156:159], v[196:199], v[32:35]
	v_mfma_f32_16x16x32_f16 v[36:39], v[148:151], v[196:199], v[36:39]
	v_mfma_f32_16x16x32_f16 v[16:19], v[156:159], v[208:211], v[16:19]
	v_mfma_f32_16x16x32_f16 v[20:23], v[148:151], v[208:211], v[20:23]
	v_mfma_f32_16x16x32_f16 v[0:3], v[156:159], v[216:219], v[0:3]
	v_mfma_f32_16x16x32_f16 v[4:7], v[148:151], v[216:219], v[4:7]
	s_barrier
; #define PG8_STAGE(bufoff, gbase, voff) do { _Pragma("unroll") for (int _i = 0; _i < 2; ++_i) \
;         __builtin_amdgcn_global_load_lds((const unsigned*)((const char*)(gbase) + (voff)[_i]), (PG8_LAS unsigned*)(lds + (bufoff) + ldsw + _i * 8192), 16, 0, 0); } while (0)
; #define PG8_LDA(dst, b, h) do { _Pragma("unroll") for (int m = 0; m < 4; ++m) _Pragma("unroll") for (int k = 0; k < 2; ++k) dst[m][k] = *(const PG8_LAS bf16x8*)(lds + PG8_SA(b, h) + aoff + m * 2048 + k * 1024); } while (0)
; #define PG8_LDB(dst, b, h) do { _Pragma("unroll") for (int n = 0; n < 2; ++n) _Pragma("unroll") for (int k = 0; k < 2; ++k) dst[n][k] = *(const PG8_LAS bf16x8*)(lds + PG8_SB(b, h) + boff + n * 2048 + k * 1024); } while (0)
; #define PG8_MMA(ai, bj, At, Bt) do { __builtin_amdgcn_s_setprio(1); _Pragma("unroll") for (int m = 0; m < 4; ++m) _Pragma("unroll") for (int n = 0; n < 2; ++n) _Pragma("unroll") for (int k = 0; k < 2; ++k) \
;         acc[ai][bj][m][n] = __builtin_amdgcn_mfma_f32_16x16x32_f16(Bt[n][k], At[m][k], acc[ai][bj][m][n], 0, 0, 0); __builtin_amdgcn_s_setprio(0); } while (0)
; #define PG8_WAIT_V(n) asm volatile("s_waitcnt vmcnt(" #n ")" ::: "memory")
; #define PG8_WAIT_L(n) asm volatile("s_waitcnt lgkmcnt(" #n ")" ::: "memory")
; #define PG8_BAR __builtin_amdgcn_s_barrier()
; #define PG8_SCHED __builtin_amdgcn_sched_barrier(0)
; template <class Epi, class Sched, bool ALIGN_EPI = false, bool SP2 = false>
; __device__ __forceinline__ void gemm_phase(PG8_LAS unsigned char* lds, const Gemm g, const Sched& S, const Epi& E) {
;     ...
;             PG8_LDB(B0, 1, 0); PG8_LDB(B1, 1, 1); PG8_SCHED; PG8_LDA(At, 1, 0); PG8_STAGE(PG8_SA(0, 1), a2 + hstep, voffA);
;             PG8_WAIT_V(8); PG8_WAIT_L(0); PG8_BAR; PG8_MMA(0, 0, At, B0); PG8_MMA(0, 1, At, B1); PG8_BAR; PG8_SCHED;
;             PG8_LDA(At, 1, 1); PG8_STAGE(PG8_SB(1, 0), b3, voffB); PG8_STAGE(PG8_SB(1, 1), b3 + hstep, voffB); PG8_STAGE(PG8_SA(1, 0), a3, voffA);
;             PG8_WAIT_V(8); PG8_WAIT_L(0); PG8_BAR; PG8_MMA(1, 0, At, B0); PG8_MMA(1, 1, At, B1); PG8_BAR; PG8_SCHED;
;     ...
;         if constexpr (ALIGN_EPI) { if (wr == 0) PG8_BAR; }
	s_add_i32 s62, 0, 0x18000
	s_add_i32 s63, 0, 0x1c000
	v_add_u32_e32 v140, s62, v187
	v_add_u32_e32 v156, s63, v187
	ds_read_b128 v[128:131], v140
	ds_read_b128 v[132:135], v140 offset:1024
	ds_read_b128 v[136:139], v140 offset:2048
	ds_read_b128 v[140:143], v140 offset:3072
	ds_read_b128 v[144:147], v156
	ds_read_b128 v[148:151], v156 offset:1024
	ds_read_b128 v[152:155], v156 offset:2048
	ds_read_b128 v[156:159], v156 offset:3072
	s_add_u32 s36, s36, 0x200000
	s_addc_u32 s37, s37, 0
	s_mov_b32 m0, s41
	ds_read_b128 v[176:179], v191 offset:32768
	ds_read_b128 v[180:183], v191 offset:33792
	ds_read_b128 v[192:195], v191 offset:34816
	ds_read_b128 v[196:199], v191 offset:35840
	ds_read_b128 v[200:203], v191 offset:36864
	ds_read_b128 v[208:211], v191 offset:37888
	ds_read_b128 v[212:215], v191 offset:38912
	ds_read_b128 v[216:219], v191 offset:39936
	global_load_lds_dwordx4 v160, s[36:37]
	s_mov_b32 m0, s42
	s_nop 0
	global_load_lds_dwordx4 v164, s[36:37]
	s_waitcnt vmcnt(8)
	s_waitcnt lgkmcnt(0)
	s_barrier
	v_mfma_f32_16x16x32_f16 v[120:123], v[136:139], v[176:179], v[120:123]
	v_mfma_f32_16x16x32_f16 v[124:127], v[128:131], v[176:179], v[124:127]
	v_mfma_f32_16x16x32_f16 v[104:107], v[136:139], v[192:195], v[104:107]
	v_mfma_f32_16x16x32_f16 v[108:111], v[128:131], v[192:195], v[108:111]
	v_mfma_f32_16x16x32_f16 v[88:91], v[136:139], v[200:203], v[88:91]
	v_mfma_f32_16x16x32_f16 v[92:95], v[128:131], v[200:203], v[92:95]
	v_mfma_f32_16x16x32_f16 v[72:75], v[136:139], v[212:215], v[72:75]
	v_mfma_f32_16x16x32_f16 v[76:79], v[128:131], v[212:215], v[76:79]
	v_mfma_f32_16x16x32_f16 v[120:123], v[140:143], v[180:183], v[120:123]
	v_mfma_f32_16x16x32_f16 v[124:127], v[132:135], v[180:183], v[124:127]
	v_mfma_f32_16x16x32_f16 v[104:107], v[140:143], v[196:199], v[104:107]
	v_mfma_f32_16x16x32_f16 v[108:111], v[132:135], v[196:199], v[108:111]
	v_mfma_f32_16x16x32_f16 v[88:91], v[140:143], v[208:211], v[88:91]
	v_mfma_f32_16x16x32_f16 v[92:95], v[132:135], v[208:211], v[92:95]
	v_mfma_f32_16x16x32_f16 v[72:75], v[140:143], v[216:219], v[72:75]
	v_mfma_f32_16x16x32_f16 v[76:79], v[132:135], v[216:219], v[76:79]
	v_mfma_f32_16x16x32_f16 v[112:115], v[152:155], v[176:179], v[112:115]
	v_mfma_f32_16x16x32_f16 v[116:119], v[144:147], v[176:179], v[116:119]
	v_mfma_f32_16x16x32_f16 v[96:99], v[152:155], v[192:195], v[96:99]
	v_mfma_f32_16x16x32_f16 v[100:103], v[144:147], v[192:195], v[100:103]
	v_mfma_f32_16x16x32_f16 v[80:83], v[152:155], v[200:203], v[80:83]
	v_mfma_f32_16x16x32_f16 v[84:87], v[144:147], v[200:203], v[84:87]
	v_mfma_f32_16x16x32_f16 v[64:67], v[152:155], v[212:215], v[64:67]
	v_mfma_f32_16x16x32_f16 v[68:71], v[144:147], v[212:215], v[68:71]
	v_mfma_f32_16x16x32_f16 v[112:115], v[156:159], v[180:183], v[112:115]
	v_mfma_f32_16x16x32_f16 v[116:119], v[148:151], v[180:183], v[116:119]
	v_mfma_f32_16x16x32_f16 v[96:99], v[156:159], v[196:199], v[96:99]
	v_mfma_f32_16x16x32_f16 v[100:103], v[148:151], v[196:199], v[100:103]
	v_mfma_f32_16x16x32_f16 v[80:83], v[156:159], v[208:211], v[80:83]
	v_mfma_f32_16x16x32_f16 v[84:87], v[148:151], v[208:211], v[84:87]
	v_mfma_f32_16x16x32_f16 v[64:67], v[156:159], v[216:219], v[64:67]
	v_mfma_f32_16x16x32_f16 v[68:71], v[148:151], v[216:219], v[68:71]
	s_barrier
	s_add_i32 s36, s62, s39
	s_mov_b32 m0, s36
	ds_read_b128 v[176:179], v191 offset:49152
	ds_read_b128 v[180:183], v191 offset:50176
	ds_read_b128 v[192:195], v191 offset:51200
	ds_read_b128 v[196:199], v191 offset:52224
	ds_read_b128 v[200:203], v191 offset:53248
	ds_read_b128 v[208:211], v191 offset:54272
	ds_read_b128 v[212:215], v191 offset:55296
	ds_read_b128 v[216:219], v191 offset:56320
	global_load_lds_dwordx4 v162, s[98:99]
	s_add_i32 m0, s36, 0x2000
	s_add_u32 s34, s34, 0x200080
	s_addc_u32 s35, s35, 0
	s_add_i32 s36, s63, s39
	global_load_lds_dwordx4 v166, s[98:99]
	s_mov_b32 m0, s36
	s_nop 0
	global_load_lds_dwordx4 v162, s[34:35]
	s_add_i32 m0, s36, 0x2000
	s_nop 0
	global_load_lds_dwordx4 v166, s[34:35]
	s_mov_b32 m0, s44
	s_nop 0
	global_load_lds_dwordx4 v160, s[100:101]
	s_mov_b32 m0, s45
	s_nop 0
	global_load_lds_dwordx4 v164, s[100:101]
	s_waitcnt vmcnt(8)
	s_waitcnt lgkmcnt(0)
	s_barrier
	v_mfma_f32_16x16x32_f16 v[56:59], v[136:139], v[176:179], v[56:59]
	v_mfma_f32_16x16x32_f16 v[60:63], v[128:131], v[176:179], v[60:63]
	v_mfma_f32_16x16x32_f16 v[40:43], v[136:139], v[192:195], v[40:43]
	v_mfma_f32_16x16x32_f16 v[44:47], v[128:131], v[192:195], v[44:47]
	v_mfma_f32_16x16x32_f16 v[24:27], v[136:139], v[200:203], v[24:27]
	v_mfma_f32_16x16x32_f16 v[28:31], v[128:131], v[200:203], v[28:31]
	v_mfma_f32_16x16x32_f16 v[8:11], v[136:139], v[212:215], v[8:11]
	v_mfma_f32_16x16x32_f16 v[12:15], v[128:131], v[212:215], v[12:15]
	v_mfma_f32_16x16x32_f16 v[56:59], v[140:143], v[180:183], v[56:59]
	v_mfma_f32_16x16x32_f16 v[60:63], v[132:135], v[180:183], v[60:63]
	v_mfma_f32_16x16x32_f16 v[40:43], v[140:143], v[196:199], v[40:43]
	v_mfma_f32_16x16x32_f16 v[44:47], v[132:135], v[196:199], v[44:47]
	v_mfma_f32_16x16x32_f16 v[24:27], v[140:143], v[208:211], v[24:27]
	v_mfma_f32_16x16x32_f16 v[28:31], v[132:135], v[208:211], v[28:31]
	v_mfma_f32_16x16x32_f16 v[8:11], v[140:143], v[216:219], v[8:11]
	v_mfma_f32_16x16x32_f16 v[12:15], v[132:135], v[216:219], v[12:15]
	v_mfma_f32_16x16x32_f16 v[48:51], v[152:155], v[176:179], v[48:51]
	v_mfma_f32_16x16x32_f16 v[52:55], v[144:147], v[176:179], v[52:55]
	v_mfma_f32_16x16x32_f16 v[32:35], v[152:155], v[192:195], v[32:35]
	v_mfma_f32_16x16x32_f16 v[36:39], v[144:147], v[192:195], v[36:39]
	v_mfma_f32_16x16x32_f16 v[16:19], v[152:155], v[200:203], v[16:19]
	v_mfma_f32_16x16x32_f16 v[20:23], v[144:147], v[200:203], v[20:23]
	v_mfma_f32_16x16x32_f16 v[0:3], v[152:155], v[212:215], v[0:3]
	v_mfma_f32_16x16x32_f16 v[4:7], v[144:147], v[212:215], v[4:7]
	v_mfma_f32_16x16x32_f16 v[48:51], v[156:159], v[180:183], v[48:51]
	v_mfma_f32_16x16x32_f16 v[52:55], v[148:151], v[180:183], v[52:55]
	v_mfma_f32_16x16x32_f16 v[32:35], v[156:159], v[196:199], v[32:35]
	v_mfma_f32_16x16x32_f16 v[36:39], v[148:151], v[196:199], v[36:39]
	v_mfma_f32_16x16x32_f16 v[16:19], v[156:159], v[208:211], v[16:19]
	v_mfma_f32_16x16x32_f16 v[20:23], v[148:151], v[208:211], v[20:23]
	v_mfma_f32_16x16x32_f16 v[0:3], v[156:159], v[216:219], v[0:3]
	v_mfma_f32_16x16x32_f16 v[4:7], v[148:151], v[216:219], v[4:7]
	s_barrier
	s_add_i32 s61, s61, 2
	s_add_u32 s53, s53, 0x100
	s_addc_u32 s60, s60, 0
	s_add_u32 s30, s30, 0x100
	s_addc_u32 s31, s31, 0
	s_cmpk_gt_u32 s61, 0x7d
	s_cbranch_scc0 .LBB0_1243
	s_and_b64 vcc, exec, s[14:15]
	s_cbranch_vccz .LBB0_1246
	s_barrier
